# v12 + MFMA pair order grouped by activation fragment (srcB held 8 MFMAs across both column blocks; register-rotation phases keep block order)
# speedup vs baseline: 1.0064x; 1.0064x over previous
; #define PG8_STAGE(bufoff, gbase, voff) do { _Pragma("unroll") for (int _i = 0; _i < 2; ++_i) \
;         __builtin_amdgcn_global_load_lds((const unsigned*)((const char*)(gbase) + (voff)[_i]), (PG8_LAS unsigned*)(lds + (bufoff) + ldsw + _i * 8192), 16, 0, 0); } while (0)
; #define PG8_LDA(dst, b, h) do { _Pragma("unroll") for (int m = 0; m < 4; ++m) _Pragma("unroll") for (int k = 0; k < 2; ++k) dst[m][k] = *(const PG8_LAS bf16x8*)(lds + PG8_SA(b, h) + aoff + m * 2048 + k * 1024); } while (0)
; #define PG8_WAIT_V(n) asm volatile("s_waitcnt vmcnt(" #n ")" ::: "memory")
; #define PG8_BAR __builtin_amdgcn_s_barrier()
; template <class Epi, class Sched, bool ALIGN_EPI = false, bool SP2 = false>
; __device__ __forceinline__ void gemm_phase(PG8_LAS unsigned char* lds, const Gemm g, const Sched& S, const Epi& E) {
;     ...
;         for (int t = 0; t < nt; t += 2) {
;             if constexpr (Epi::KHOOK) { if ((t & 7) == 0 && t != 0) E.khook(acc, t >> 3, wr, fr, lds); }
;             const bool last = (t == nt - 2);
;             const char* a1 = cA + (size_t)(t + 1) * kstep;
;             const char* a2 = last ? nA : cA + (size_t)(t + 2) * kstep; const char* b2 = last ? nB : cB + (size_t)(t + 2) * kstep;
;             const char* a3 = a2 + kstep; const char* b3 = b2 + kstep;
;             if (last && has_next) S.a_ready(nxt);
;             if constexpr (SP2) {
;             PG8_LDB(B0, 0, 0); PG8_LDB(B1, 0, 1); PG8_SCHED; PG8_LDA(At, 0, 0); PG8_STAGE(PG8_SA(1, 1), a1 + hstep, voffA);
;             PG8_WAIT_V(8); PG8_WAIT_L(0); PG8_BAR; PG8_MMA(0, 0, At, B0); PG8_MMA(0, 1, At, B1); PG8_BAR; PG8_SCHED;
;             PG8_LDA(At, 0, 1); PG8_STAGE(PG8_SB(0, 0), b2, voffB); PG8_STAGE(PG8_SB(0, 1), b2 + hstep, voffB); PG8_STAGE(PG8_SA(0, 0), a2, voffA);
;             PG8_WAIT_V(8); PG8_WAIT_L(0); PG8_BAR; PG8_MMA(1, 0, At, B0); PG8_MMA(1, 1, At, B1); PG8_BAR; PG8_SCHED;
;             PG8_LDB(B0, 1, 0); PG8_LDB(B1, 1, 1); PG8_SCHED; PG8_LDA(At, 1, 0); PG8_STAGE(PG8_SA(0, 1), a2 + hstep, voffA);
;             PG8_WAIT_V(8); PG8_WAIT_L(0); PG8_BAR; PG8_MMA(0, 0, At, B0); PG8_MMA(0, 1, At, B1); PG8_BAR; PG8_SCHED;
;             PG8_LDA(At, 1, 1); PG8_STAGE(PG8_SB(1, 0), b3, voffB); PG8_STAGE(PG8_SB(1, 1), b3 + hstep, voffB); PG8_STAGE(PG8_SA(1, 0), a3, voffA);
;             PG8_WAIT_V(8); PG8_WAIT_L(0); PG8_BAR; PG8_MMA(1, 0, At, B0); PG8_MMA(1, 1, At, B1); PG8_BAR; PG8_SCHED;
.LBB0_202:
	s_add_i32 s78, s38, 2
	s_add_u32 s79, s22, 0x80
	s_addc_u32 s39, s23, 0
	s_cmp_eq_u32 s33, s38
	s_cselect_b32 s39, s7, s39
	s_cselect_b32 s38, s6, s79
	v_add_u32_e32 v0, s19, v150
	s_cselect_b32 s81, s17, s77
	s_cselect_b32 s80, s16, s76
	s_add_i32 s79, 0, 0x14000
	ds_read_b128 v[152:155], v0
	ds_read_b128 v[156:159], v0 offset:1024
	ds_read_b128 v[160:163], v0 offset:2048
	ds_read_b128 v[164:167], v0 offset:3072
	v_add_u32_e32 v0, s79, v150
	ds_read_b128 v[168:171], v0
	ds_read_b128 v[172:175], v0 offset:1024
	ds_read_b128 v[176:179], v0 offset:2048
	ds_read_b128 v[184:187], v0 offset:3072
	v_lshl_add_u64 v[2:3], s[22:23], 0, v[144:145]
	s_add_i32 m0, s42, 0xc000
	ds_read_b128 v[188:191], v151
	ds_read_b128 v[192:195], v151 offset:1024
	ds_read_b128 v[196:199], v151 offset:2048
	ds_read_b128 v[200:203], v151 offset:3072
	ds_read_b128 v[204:207], v151 offset:4096
	ds_read_b128 v[230:233], v151 offset:5120
	ds_read_b128 v[234:237], v151 offset:6144
	ds_read_b128 v[238:241], v151 offset:7168
	global_load_lds_dwordx4 v[2:3], off
	v_lshl_add_u64 v[2:3], s[22:23], 0, v[146:147]
	s_add_i32 m0, s42, 0xe000
	s_nop 0
	global_load_lds_dwordx4 v[2:3], off
	s_waitcnt vmcnt(8)
	s_waitcnt lgkmcnt(0)
	s_barrier
	s_setprio 1
	s_waitcnt lgkmcnt(0)
	v_mfma_f32_16x16x32_bf16 v[132:135], v[152:155], v[188:191], v[132:135]
	v_mfma_f32_16x16x32_bf16 v[132:135], v[156:159], v[192:195], v[132:135]
	v_mfma_f32_16x16x32_bf16 v[128:131], v[160:163], v[188:191], v[128:131]
	v_mfma_f32_16x16x32_bf16 v[128:131], v[164:167], v[192:195], v[128:131]
	v_mfma_f32_16x16x32_bf16 v[120:123], v[176:179], v[188:191], v[120:123]
	v_mfma_f32_16x16x32_bf16 v[120:123], v[184:187], v[192:195], v[120:123]
	v_mfma_f32_16x16x32_bf16 v[124:127], v[168:171], v[188:191], v[124:127]
	v_mfma_f32_16x16x32_bf16 v[124:127], v[172:175], v[192:195], v[124:127]
	v_mfma_f32_16x16x32_bf16 v[108:111], v[168:171], v[196:199], v[108:111]
	v_mfma_f32_16x16x32_bf16 v[108:111], v[172:175], v[200:203], v[108:111]
	v_mfma_f32_16x16x32_bf16 v[104:107], v[176:179], v[196:199], v[104:107]
	v_mfma_f32_16x16x32_bf16 v[104:107], v[184:187], v[200:203], v[104:107]
	v_mfma_f32_16x16x32_bf16 v[112:115], v[160:163], v[196:199], v[112:115]
	v_mfma_f32_16x16x32_bf16 v[112:115], v[164:167], v[200:203], v[112:115]
	v_mfma_f32_16x16x32_bf16 v[116:119], v[152:155], v[196:199], v[116:119]
	v_mfma_f32_16x16x32_bf16 v[116:119], v[156:159], v[200:203], v[116:119]
	s_setprio 0
	s_setprio 1
	v_mfma_f32_16x16x32_bf16 v[100:103], v[152:155], v[204:207], v[100:103]
	v_mfma_f32_16x16x32_bf16 v[100:103], v[156:159], v[230:233], v[100:103]
	v_mfma_f32_16x16x32_bf16 v[96:99], v[160:163], v[204:207], v[96:99]
	v_mfma_f32_16x16x32_bf16 v[96:99], v[164:167], v[230:233], v[96:99]
	v_mfma_f32_16x16x32_bf16 v[88:91], v[176:179], v[204:207], v[88:91]
	v_mfma_f32_16x16x32_bf16 v[88:91], v[184:187], v[230:233], v[88:91]
	v_mfma_f32_16x16x32_bf16 v[92:95], v[168:171], v[204:207], v[92:95]
	v_mfma_f32_16x16x32_bf16 v[92:95], v[172:175], v[230:233], v[92:95]
	v_mfma_f32_16x16x32_bf16 v[76:79], v[168:171], v[234:237], v[76:79]
	v_mfma_f32_16x16x32_bf16 v[76:79], v[172:175], v[238:241], v[76:79]
	v_mfma_f32_16x16x32_bf16 v[72:75], v[176:179], v[234:237], v[72:75]
	v_mfma_f32_16x16x32_bf16 v[72:75], v[184:187], v[238:241], v[72:75]
	v_mfma_f32_16x16x32_bf16 v[80:83], v[160:163], v[234:237], v[80:83]
	v_mfma_f32_16x16x32_bf16 v[80:83], v[164:167], v[238:241], v[80:83]
	v_mfma_f32_16x16x32_bf16 v[84:87], v[152:155], v[234:237], v[84:87]
	v_mfma_f32_16x16x32_bf16 v[84:87], v[156:159], v[238:241], v[84:87]
	s_setprio 0
	s_barrier
	s_add_i32 s82, s19, s20
	v_lshl_add_u64 v[2:3], s[80:81], 0, v[140:141]
	s_mov_b32 m0, s82
	ds_read_b128 v[188:191], v151 offset:16384
	ds_read_b128 v[192:195], v151 offset:17408
	ds_read_b128 v[196:199], v151 offset:18432
	ds_read_b128 v[200:203], v151 offset:19456
	ds_read_b128 v[204:207], v151 offset:20480
	ds_read_b128 v[230:233], v151 offset:21504
	ds_read_b128 v[234:237], v151 offset:22528
	ds_read_b128 v[238:241], v151 offset:23552
	global_load_lds_dwordx4 v[2:3], off
	s_add_i32 m0, s82, 0x2000
	v_lshl_add_u64 v[180:181], s[80:81], 0, v[136:137]
	s_add_u32 s80, s80, s48
	s_addc_u32 s81, s81, s49
	s_add_i32 s79, s79, s20
	global_load_lds_dwordx4 v[180:181], off
	v_lshl_add_u64 v[208:209], s[80:81], 0, v[140:141]
	s_mov_b32 m0, s79
	v_lshl_add_u64 v[216:217], s[80:81], 0, v[136:137]
	global_load_lds_dwordx4 v[208:209], off
	s_add_i32 m0, s79, 0x2000
	v_lshl_add_u64 v[224:225], s[38:39], 0, v[142:143]
	global_load_lds_dwordx4 v[216:217], off
	s_mov_b32 m0, s42
	v_lshl_add_u64 v[226:227], s[38:39], 0, v[138:139]
	global_load_lds_dwordx4 v[224:225], off
	s_mov_b32 m0, s45
	s_nop 0
	global_load_lds_dwordx4 v[226:227], off
	s_waitcnt vmcnt(8)
	s_waitcnt lgkmcnt(0)
	s_barrier
; #define PG8_STAGE(bufoff, gbase, voff) do { _Pragma("unroll") for (int _i = 0; _i < 2; ++_i) \
;         __builtin_amdgcn_global_load_lds((const unsigned*)((const char*)(gbase) + (voff)[_i]), (PG8_LAS unsigned*)(lds + (bufoff) + ldsw + _i * 8192), 16, 0, 0); } while (0)
; #define PG8_LDA(dst, b, h) do { _Pragma("unroll") for (int m = 0; m < 4; ++m) _Pragma("unroll") for (int k = 0; k < 2; ++k) dst[m][k] = *(const PG8_LAS bf16x8*)(lds + PG8_SA(b, h) + aoff + m * 2048 + k * 1024); } while (0)
; #define PG8_LDB(dst, b, h) do { _Pragma("unroll") for (int n = 0; n < 2; ++n) _Pragma("unroll") for (int k = 0; k < 2; ++k) dst[n][k] = *(const PG8_LAS bf16x8*)(lds + PG8_SB(b, h) + boff + n * 2048 + k * 1024); } while (0)
; #define PG8_MMA(ai, bj, At, Bt) do { __builtin_amdgcn_s_setprio(1); _Pragma("unroll") for (int m = 0; m < 4; ++m) _Pragma("unroll") for (int n = 0; n < 2; ++n) _Pragma("unroll") for (int k = 0; k < 2; ++k) \
;         acc[ai][bj][m][n] = __builtin_amdgcn_mfma_f32_16x16x32_bf16(Bt[n][k], At[m][k], acc[ai][bj][m][n], 0, 0, 0); __builtin_amdgcn_s_setprio(0); } while (0)
; #define PG8_BAR __builtin_amdgcn_s_barrier()
; template <class Epi, class Sched, bool ALIGN_EPI = false, bool SP2 = false>
; __device__ __forceinline__ void gemm_phase(PG8_LAS unsigned char* lds, const Gemm g, const Sched& S, const Epi& E) {
;     ...
;             if constexpr (SP2) {
;             PG8_LDB(B0, 0, 0); PG8_LDB(B1, 0, 1); PG8_SCHED; PG8_LDA(At, 0, 0); PG8_STAGE(PG8_SA(1, 1), a1 + hstep, voffA);
;             PG8_WAIT_V(8); PG8_WAIT_L(0); PG8_BAR; PG8_MMA(0, 0, At, B0); PG8_MMA(0, 1, At, B1); PG8_BAR; PG8_SCHED;
;             PG8_LDA(At, 0, 1); PG8_STAGE(PG8_SB(0, 0), b2, voffB); PG8_STAGE(PG8_SB(0, 1), b2 + hstep, voffB); PG8_STAGE(PG8_SA(0, 0), a2, voffA);
;             PG8_WAIT_V(8); PG8_WAIT_L(0); PG8_BAR; PG8_MMA(1, 0, At, B0); PG8_MMA(1, 1, At, B1); PG8_BAR; PG8_SCHED;
;             PG8_LDB(B0, 1, 0); PG8_LDB(B1, 1, 1); PG8_SCHED; PG8_LDA(At, 1, 0); PG8_STAGE(PG8_SA(0, 1), a2 + hstep, voffA);
;             PG8_WAIT_V(8); PG8_WAIT_L(0); PG8_BAR; PG8_MMA(0, 0, At, B0); PG8_MMA(0, 1, At, B1); PG8_BAR; PG8_SCHED;
;             PG8_LDA(At, 1, 1); PG8_STAGE(PG8_SB(1, 0), b3, voffB); PG8_STAGE(PG8_SB(1, 1), b3 + hstep, voffB); PG8_STAGE(PG8_SA(1, 0), a3, voffA);
;             PG8_WAIT_V(8); PG8_WAIT_L(0); PG8_BAR; PG8_MMA(1, 0, At, B0); PG8_MMA(1, 1, At, B1); PG8_BAR; PG8_SCHED;
	s_setprio 1
	s_waitcnt lgkmcnt(0)
	v_mfma_f32_16x16x32_bf16 v[68:71], v[152:155], v[188:191], v[68:71]
	v_mfma_f32_16x16x32_bf16 v[68:71], v[156:159], v[192:195], v[68:71]
	v_mfma_f32_16x16x32_bf16 v[64:67], v[160:163], v[188:191], v[64:67]
	v_mfma_f32_16x16x32_bf16 v[64:67], v[164:167], v[192:195], v[64:67]
	v_mfma_f32_16x16x32_bf16 v[56:59], v[176:179], v[188:191], v[56:59]
	v_mfma_f32_16x16x32_bf16 v[56:59], v[184:187], v[192:195], v[56:59]
	v_mfma_f32_16x16x32_bf16 v[60:63], v[168:171], v[188:191], v[60:63]
	v_mfma_f32_16x16x32_bf16 v[60:63], v[172:175], v[192:195], v[60:63]
	v_mfma_f32_16x16x32_bf16 v[44:47], v[168:171], v[196:199], v[44:47]
	v_mfma_f32_16x16x32_bf16 v[44:47], v[172:175], v[200:203], v[44:47]
	v_mfma_f32_16x16x32_bf16 v[40:43], v[176:179], v[196:199], v[40:43]
	v_mfma_f32_16x16x32_bf16 v[40:43], v[184:187], v[200:203], v[40:43]
	v_mfma_f32_16x16x32_bf16 v[48:51], v[160:163], v[196:199], v[48:51]
	v_mfma_f32_16x16x32_bf16 v[48:51], v[164:167], v[200:203], v[48:51]
	v_mfma_f32_16x16x32_bf16 v[52:55], v[152:155], v[196:199], v[52:55]
	v_mfma_f32_16x16x32_bf16 v[52:55], v[156:159], v[200:203], v[52:55]
	s_setprio 0
	s_setprio 1
	v_mfma_f32_16x16x32_bf16 v[36:39], v[152:155], v[204:207], v[36:39]
	v_mfma_f32_16x16x32_bf16 v[36:39], v[156:159], v[230:233], v[36:39]
	v_mfma_f32_16x16x32_bf16 v[32:35], v[160:163], v[204:207], v[32:35]
	v_mfma_f32_16x16x32_bf16 v[32:35], v[164:167], v[230:233], v[32:35]
	v_mfma_f32_16x16x32_bf16 v[24:27], v[176:179], v[204:207], v[24:27]
	v_mfma_f32_16x16x32_bf16 v[24:27], v[184:187], v[230:233], v[24:27]
	v_mfma_f32_16x16x32_bf16 v[28:31], v[168:171], v[204:207], v[28:31]
	v_mfma_f32_16x16x32_bf16 v[28:31], v[172:175], v[230:233], v[28:31]
	v_mfma_f32_16x16x32_bf16 v[12:15], v[168:171], v[234:237], v[12:15]
	v_mfma_f32_16x16x32_bf16 v[12:15], v[172:175], v[238:241], v[12:15]
	v_mfma_f32_16x16x32_bf16 v[8:11], v[176:179], v[234:237], v[8:11]
	v_mfma_f32_16x16x32_bf16 v[8:11], v[184:187], v[238:241], v[8:11]
	v_mfma_f32_16x16x32_bf16 v[16:19], v[160:163], v[234:237], v[16:19]
	v_mfma_f32_16x16x32_bf16 v[16:19], v[164:167], v[238:241], v[16:19]
	v_mfma_f32_16x16x32_bf16 v[20:23], v[152:155], v[234:237], v[20:23]
	v_mfma_f32_16x16x32_bf16 v[20:23], v[156:159], v[238:241], v[20:23]
	s_setprio 0
	s_barrier
	v_add_u32_e32 v0, s91, v150
	s_add_i32 s79, 0, 0x1c000
	ds_read_b128 v[152:155], v0
	ds_read_b128 v[156:159], v0 offset:1024
	ds_read_b128 v[160:163], v0 offset:2048
	ds_read_b128 v[164:167], v0 offset:3072
	v_add_u32_e32 v0, s79, v150
	ds_read_b128 v[168:171], v0
	ds_read_b128 v[172:175], v0 offset:1024
	ds_read_b128 v[176:179], v0 offset:2048
	ds_read_b128 v[184:187], v0 offset:3072
	s_add_u32 s38, s38, s48
	s_addc_u32 s39, s39, s49
	s_mov_b32 m0, s46
	v_lshl_add_u64 v[228:229], s[38:39], 0, v[142:143]
	ds_read_b128 v[188:191], v151 offset:32768
	ds_read_b128 v[192:195], v151 offset:33792
	ds_read_b128 v[196:199], v151 offset:34816
	ds_read_b128 v[200:203], v151 offset:35840
	ds_read_b128 v[204:207], v151 offset:36864
	ds_read_b128 v[230:233], v151 offset:37888
	ds_read_b128 v[234:237], v151 offset:38912
	ds_read_b128 v[238:241], v151 offset:39936
	global_load_lds_dwordx4 v[228:229], off
	v_lshl_add_u64 v[228:229], s[38:39], 0, v[138:139]
	s_mov_b32 m0, s47
	s_nop 0
	global_load_lds_dwordx4 v[228:229], off
	s_waitcnt vmcnt(8)
	s_waitcnt lgkmcnt(0)
	s_barrier
	s_setprio 1
	s_waitcnt lgkmcnt(0)
	v_mfma_f32_16x16x32_bf16 v[132:135], v[152:155], v[188:191], v[132:135]
	v_mfma_f32_16x16x32_bf16 v[132:135], v[156:159], v[192:195], v[132:135]
	v_mfma_f32_16x16x32_bf16 v[128:131], v[160:163], v[188:191], v[128:131]
	v_mfma_f32_16x16x32_bf16 v[128:131], v[164:167], v[192:195], v[128:131]
	v_mfma_f32_16x16x32_bf16 v[120:123], v[176:179], v[188:191], v[120:123]
	v_mfma_f32_16x16x32_bf16 v[120:123], v[184:187], v[192:195], v[120:123]
	v_mfma_f32_16x16x32_bf16 v[124:127], v[168:171], v[188:191], v[124:127]
	v_mfma_f32_16x16x32_bf16 v[124:127], v[172:175], v[192:195], v[124:127]
	v_mfma_f32_16x16x32_bf16 v[108:111], v[168:171], v[196:199], v[108:111]
	v_mfma_f32_16x16x32_bf16 v[108:111], v[172:175], v[200:203], v[108:111]
	v_mfma_f32_16x16x32_bf16 v[104:107], v[176:179], v[196:199], v[104:107]
	v_mfma_f32_16x16x32_bf16 v[104:107], v[184:187], v[200:203], v[104:107]
	v_mfma_f32_16x16x32_bf16 v[112:115], v[160:163], v[196:199], v[112:115]
	v_mfma_f32_16x16x32_bf16 v[112:115], v[164:167], v[200:203], v[112:115]
	v_mfma_f32_16x16x32_bf16 v[116:119], v[152:155], v[196:199], v[116:119]
	v_mfma_f32_16x16x32_bf16 v[116:119], v[156:159], v[200:203], v[116:119]
	s_setprio 0
	s_setprio 1
	v_mfma_f32_16x16x32_bf16 v[100:103], v[152:155], v[204:207], v[100:103]
	v_mfma_f32_16x16x32_bf16 v[100:103], v[156:159], v[230:233], v[100:103]
	v_mfma_f32_16x16x32_bf16 v[96:99], v[160:163], v[204:207], v[96:99]
	v_mfma_f32_16x16x32_bf16 v[96:99], v[164:167], v[230:233], v[96:99]
	v_mfma_f32_16x16x32_bf16 v[88:91], v[176:179], v[204:207], v[88:91]
	v_mfma_f32_16x16x32_bf16 v[88:91], v[184:187], v[230:233], v[88:91]
	v_mfma_f32_16x16x32_bf16 v[92:95], v[168:171], v[204:207], v[92:95]
	v_mfma_f32_16x16x32_bf16 v[92:95], v[172:175], v[230:233], v[92:95]
	v_mfma_f32_16x16x32_bf16 v[76:79], v[168:171], v[234:237], v[76:79]
	v_mfma_f32_16x16x32_bf16 v[76:79], v[172:175], v[238:241], v[76:79]
	v_mfma_f32_16x16x32_bf16 v[72:75], v[176:179], v[234:237], v[72:75]
	v_mfma_f32_16x16x32_bf16 v[72:75], v[184:187], v[238:241], v[72:75]
	v_mfma_f32_16x16x32_bf16 v[80:83], v[160:163], v[234:237], v[80:83]
	v_mfma_f32_16x16x32_bf16 v[80:83], v[164:167], v[238:241], v[80:83]
	v_mfma_f32_16x16x32_bf16 v[84:87], v[152:155], v[234:237], v[84:87]
	v_mfma_f32_16x16x32_bf16 v[84:87], v[156:159], v[238:241], v[84:87]
	s_setprio 0
	s_barrier
; #define PG8_STAGE(bufoff, gbase, voff) do { _Pragma("unroll") for (int _i = 0; _i < 2; ++_i) \
;         __builtin_amdgcn_global_load_lds((const unsigned*)((const char*)(gbase) + (voff)[_i]), (PG8_LAS unsigned*)(lds + (bufoff) + ldsw + _i * 8192), 16, 0, 0); } while (0)
; #define PG8_LDA(dst, b, h) do { _Pragma("unroll") for (int m = 0; m < 4; ++m) _Pragma("unroll") for (int k = 0; k < 2; ++k) dst[m][k] = *(const PG8_LAS bf16x8*)(lds + PG8_SA(b, h) + aoff + m * 2048 + k * 1024); } while (0)
; #define PG8_WAIT_V(n) asm volatile("s_waitcnt vmcnt(" #n ")" ::: "memory")
; #define PG8_BAR __builtin_amdgcn_s_barrier()
; template <class Epi, class Sched, bool ALIGN_EPI = false, bool SP2 = false>
; __device__ __forceinline__ void gemm_phase(PG8_LAS unsigned char* lds, const Gemm g, const Sched& S, const Epi& E) {
;     ...
;         for (int t = 0; t < nt; t += 2) {
;             if constexpr (Epi::KHOOK) { if ((t & 7) == 0 && t != 0) E.khook(acc, t >> 3, wr, fr, lds); }
;             const bool last = (t == nt - 2);
;             const char* a1 = cA + (size_t)(t + 1) * kstep;
;             const char* a2 = last ? nA : cA + (size_t)(t + 2) * kstep; const char* b2 = last ? nB : cB + (size_t)(t + 2) * kstep;
;             const char* a3 = a2 + kstep; const char* b3 = b2 + kstep;
;             if (last && has_next) S.a_ready(nxt);
;             if constexpr (SP2) {
;             PG8_LDB(B0, 0, 0); PG8_LDB(B1, 0, 1); PG8_SCHED; PG8_LDA(At, 0, 0); PG8_STAGE(PG8_SA(1, 1), a1 + hstep, voffA);
;             PG8_WAIT_V(8); PG8_WAIT_L(0); PG8_BAR; PG8_MMA(0, 0, At, B0); PG8_MMA(0, 1, At, B1); PG8_BAR; PG8_SCHED;
;             PG8_LDA(At, 0, 1); PG8_STAGE(PG8_SB(0, 0), b2, voffB); PG8_STAGE(PG8_SB(0, 1), b2 + hstep, voffB); PG8_STAGE(PG8_SA(0, 0), a2, voffA);
;             PG8_WAIT_V(8); PG8_WAIT_L(0); PG8_BAR; PG8_MMA(1, 0, At, B0); PG8_MMA(1, 1, At, B1); PG8_BAR; PG8_SCHED;
;             PG8_LDB(B0, 1, 0); PG8_LDB(B1, 1, 1); PG8_SCHED; PG8_LDA(At, 1, 0); PG8_STAGE(PG8_SA(0, 1), a2 + hstep, voffA);
;             PG8_WAIT_V(8); PG8_WAIT_L(0); PG8_BAR; PG8_MMA(0, 0, At, B0); PG8_MMA(0, 1, At, B1); PG8_BAR; PG8_SCHED;
;             PG8_LDA(At, 1, 1); PG8_STAGE(PG8_SB(1, 0), b3, voffB); PG8_STAGE(PG8_SB(1, 1), b3 + hstep, voffB); PG8_STAGE(PG8_SA(1, 0), a3, voffA);
;             PG8_WAIT_V(8); PG8_WAIT_L(0); PG8_BAR; PG8_MMA(1, 0, At, B0); PG8_MMA(1, 1, At, B1); PG8_BAR; PG8_SCHED;
	s_add_i32 s38, s91, s20
	v_lshl_add_u64 v[2:3], v[2:3], 0, s[24:25]
	s_mov_b32 m0, s38
	ds_read_b128 v[188:191], v151 offset:49152
	ds_read_b128 v[192:195], v151 offset:50176
	ds_read_b128 v[196:199], v151 offset:51200
	ds_read_b128 v[200:203], v151 offset:52224
	ds_read_b128 v[204:207], v151 offset:53248
	ds_read_b128 v[230:233], v151 offset:54272
	ds_read_b128 v[234:237], v151 offset:55296
	ds_read_b128 v[238:241], v151 offset:56320
	global_load_lds_dwordx4 v[2:3], off
	v_lshl_add_u64 v[2:3], v[180:181], 0, s[24:25]
	s_add_i32 m0, s38, 0x2000
	s_add_i32 s38, s79, s20
	global_load_lds_dwordx4 v[2:3], off
	v_lshl_add_u64 v[2:3], v[208:209], 0, s[24:25]
	s_mov_b32 m0, s38
	s_nop 0
	global_load_lds_dwordx4 v[2:3], off
	v_lshl_add_u64 v[2:3], v[216:217], 0, s[24:25]
	s_add_i32 m0, s38, 0x2000
	s_nop 0
	global_load_lds_dwordx4 v[2:3], off
	v_lshl_add_u64 v[2:3], v[224:225], 0, s[24:25]
	s_mov_b32 m0, s52
	s_nop 0
	global_load_lds_dwordx4 v[2:3], off
	v_lshl_add_u64 v[2:3], v[226:227], 0, s[24:25]
	s_mov_b32 m0, s53
	s_nop 0
	global_load_lds_dwordx4 v[2:3], off
	s_waitcnt vmcnt(8)
	s_waitcnt lgkmcnt(0)
	s_barrier
	s_setprio 1
	s_waitcnt lgkmcnt(0)
	v_mfma_f32_16x16x32_bf16 v[68:71], v[152:155], v[188:191], v[68:71]
	v_mfma_f32_16x16x32_bf16 v[68:71], v[156:159], v[192:195], v[68:71]
	v_mfma_f32_16x16x32_bf16 v[64:67], v[160:163], v[188:191], v[64:67]
	v_mfma_f32_16x16x32_bf16 v[64:67], v[164:167], v[192:195], v[64:67]
	v_mfma_f32_16x16x32_bf16 v[56:59], v[176:179], v[188:191], v[56:59]
	v_mfma_f32_16x16x32_bf16 v[56:59], v[184:187], v[192:195], v[56:59]
	v_mfma_f32_16x16x32_bf16 v[60:63], v[168:171], v[188:191], v[60:63]
	v_mfma_f32_16x16x32_bf16 v[60:63], v[172:175], v[192:195], v[60:63]
	v_mfma_f32_16x16x32_bf16 v[44:47], v[168:171], v[196:199], v[44:47]
	v_mfma_f32_16x16x32_bf16 v[44:47], v[172:175], v[200:203], v[44:47]
	v_mfma_f32_16x16x32_bf16 v[40:43], v[176:179], v[196:199], v[40:43]
	v_mfma_f32_16x16x32_bf16 v[40:43], v[184:187], v[200:203], v[40:43]
	v_mfma_f32_16x16x32_bf16 v[48:51], v[160:163], v[196:199], v[48:51]
	v_mfma_f32_16x16x32_bf16 v[48:51], v[164:167], v[200:203], v[48:51]
	v_mfma_f32_16x16x32_bf16 v[52:55], v[152:155], v[196:199], v[52:55]
	v_mfma_f32_16x16x32_bf16 v[52:55], v[156:159], v[200:203], v[52:55]
	s_setprio 0
	s_setprio 1
	v_mfma_f32_16x16x32_bf16 v[36:39], v[152:155], v[204:207], v[36:39]
	v_mfma_f32_16x16x32_bf16 v[36:39], v[156:159], v[230:233], v[36:39]
	v_mfma_f32_16x16x32_bf16 v[32:35], v[160:163], v[204:207], v[32:35]
	v_mfma_f32_16x16x32_bf16 v[32:35], v[164:167], v[230:233], v[32:35]
	v_mfma_f32_16x16x32_bf16 v[24:27], v[176:179], v[204:207], v[24:27]
	v_mfma_f32_16x16x32_bf16 v[24:27], v[184:187], v[230:233], v[24:27]
	v_mfma_f32_16x16x32_bf16 v[28:31], v[168:171], v[204:207], v[28:31]
	v_mfma_f32_16x16x32_bf16 v[28:31], v[172:175], v[230:233], v[28:31]
	v_mfma_f32_16x16x32_bf16 v[12:15], v[168:171], v[234:237], v[12:15]
	v_mfma_f32_16x16x32_bf16 v[12:15], v[172:175], v[238:241], v[12:15]
	v_mfma_f32_16x16x32_bf16 v[8:11], v[176:179], v[234:237], v[8:11]
	v_mfma_f32_16x16x32_bf16 v[8:11], v[184:187], v[238:241], v[8:11]
	v_mfma_f32_16x16x32_bf16 v[16:19], v[160:163], v[234:237], v[16:19]
	v_mfma_f32_16x16x32_bf16 v[16:19], v[164:167], v[238:241], v[16:19]
	v_mfma_f32_16x16x32_bf16 v[20:23], v[152:155], v[234:237], v[20:23]
	v_mfma_f32_16x16x32_bf16 v[20:23], v[156:159], v[238:241], v[20:23]
	s_setprio 0
	s_barrier
	s_add_u32 s22, s22, 0x100
	s_addc_u32 s23, s23, 0
	s_add_u32 s76, s76, 0x100
	s_addc_u32 s77, s77, 0
	s_cmp_ge_u32 s78, s9
	s_mov_b32 s38, s78
	s_cbranch_scc0 .LBB0_202

; #define PG8_STAGE(bufoff, gbase, voff) do { _Pragma("unroll") for (int _i = 0; _i < 2; ++_i) \
;         __builtin_amdgcn_global_load_lds((const unsigned*)((const char*)(gbase) + (voff)[_i]), (PG8_LAS unsigned*)(lds + (bufoff) + ldsw + _i * 8192), 16, 0, 0); } while (0)
; #define PG8_WAIT_V(n) asm volatile("s_waitcnt vmcnt(" #n ")" ::: "memory")
; #define PG8_BAR __builtin_amdgcn_s_barrier()
; template <class Epi, class Sched, bool ALIGN_EPI = false, bool SP2 = false>
; __device__ __forceinline__ void gemm_phase(PG8_LAS unsigned char* lds, const Gemm g, const Sched& S, const Epi& E) {
;     ...
;         const bool has_next = S.next(ui + 1, nxt);
;         const char* nA = has_next ? (const char*)g.A + (size_t)nxt.pm * tstepA : cA; const char* nB = has_next ? (const char*)g.Bt + (size_t)nxt.pn * tstep : cB;
;         for (int t = 0; t < nt; t += 2) {
;             if constexpr (Epi::KHOOK) { if ((t & 7) == 0 && t != 0) E.khook(acc, t >> 3, wr, fr, lds); }
;             const bool last = (t == nt - 2);
;             const char* a1 = cA + (size_t)(t + 1) * kstep;
;             const char* a2 = last ? nA : cA + (size_t)(t + 2) * kstep; const char* b2 = last ? nB : cB + (size_t)(t + 2) * kstep;
;             const char* a3 = a2 + kstep; const char* b3 = b2 + kstep;
;             if (last && has_next) S.a_ready(nxt);
;             if constexpr (SP2) {
;             PG8_LDB(B0, 0, 0); PG8_LDB(B1, 0, 1); PG8_SCHED; PG8_LDA(At, 0, 0); PG8_STAGE(PG8_SA(1, 1), a1 + hstep, voffA);
;             PG8_WAIT_V(8); PG8_WAIT_L(0); PG8_BAR; PG8_MMA(0, 0, At, B0); PG8_MMA(0, 1, At, B1); PG8_BAR; PG8_SCHED;
;             PG8_LDA(At, 0, 1); PG8_STAGE(PG8_SB(0, 0), b2, voffB); PG8_STAGE(PG8_SB(0, 1), b2 + hstep, voffB); PG8_STAGE(PG8_SA(0, 0), a2, voffA);
;             PG8_WAIT_V(8); PG8_WAIT_L(0); PG8_BAR; PG8_MMA(1, 0, At, B0); PG8_MMA(1, 1, At, B1); PG8_BAR; PG8_SCHED;
;             PG8_LDB(B0, 1, 0); PG8_LDB(B1, 1, 1); PG8_SCHED; PG8_LDA(At, 1, 0); PG8_STAGE(PG8_SA(0, 1), a2 + hstep, voffA);
;             PG8_WAIT_V(8); PG8_WAIT_L(0); PG8_BAR; PG8_MMA(0, 0, At, B0); PG8_MMA(0, 1, At, B1); PG8_BAR; PG8_SCHED;
;             PG8_LDA(At, 1, 1); PG8_STAGE(PG8_SB(1, 0), b3, voffB); PG8_STAGE(PG8_SB(1, 1), b3 + hstep, voffB); PG8_STAGE(PG8_SA(1, 0), a3, voffA);
;             PG8_WAIT_V(8); PG8_WAIT_L(0); PG8_BAR; PG8_MMA(1, 0, At, B0); PG8_MMA(1, 1, At, B1); PG8_BAR; PG8_SCHED;
.LBB0_245:
	v_readlane_b32 s22, v252, 59
	v_readlane_b32 s23, v252, 60
	s_andn2_b64 vcc, exec, s[22:23]
	s_cbranch_vccnz .LBB0_252
	s_add_u32 s40, s6, s48
	s_addc_u32 s41, s7, s49
	s_add_u32 s37, s6, 0x100
	s_addc_u32 s80, s7, 0
	s_and_b64 s[22:23], s[12:13], exec
	s_cselect_b32 s23, s5, s80
	s_cselect_b32 s22, s4, s37
	s_add_u32 s37, s10, 0x100
	s_addc_u32 s82, s11, 0
	s_and_b64 s[80:81], s[12:13], exec
	s_cselect_b32 s85, s17, s82
	s_cselect_b32 s84, s16, s37
	s_add_i32 s83, 0, 0x14000
	v_add_u32_e32 v150, s19, v147
	v_add_u32_e32 v151, s83, v147
	ds_read_b128 v[152:155], v150
	ds_read_b128 v[156:159], v150 offset:1024
	ds_read_b128 v[160:163], v150 offset:2048
	ds_read_b128 v[164:167], v150 offset:3072
	ds_read_b128 v[168:171], v151
	ds_read_b128 v[172:175], v151 offset:1024
	ds_read_b128 v[176:179], v151 offset:2048
	ds_read_b128 v[184:187], v151 offset:3072
	v_lshl_add_u64 v[180:181], s[40:41], 0, v[2:3]
	s_add_i32 s37, s47, 0xc000
	v_lshl_add_u64 v[180:181], v[180:181], 0, s[24:25]
	s_mov_b32 m0, s37
	ds_read_b128 v[188:191], v149
	ds_read_b128 v[192:195], v149 offset:1024
	ds_read_b128 v[196:199], v149 offset:2048
	ds_read_b128 v[200:203], v149 offset:3072
	ds_read_b128 v[204:207], v149 offset:4096
	ds_read_b128 v[230:233], v149 offset:5120
	ds_read_b128 v[234:237], v149 offset:6144
	ds_read_b128 v[238:241], v149 offset:7168
	global_load_lds_dwordx4 v[180:181], off
	v_lshl_add_u64 v[180:181], s[40:41], 0, v[136:137]
	s_add_i32 s80, s47, 0xe000
	v_lshl_add_u64 v[180:181], v[180:181], 0, s[24:25]
	s_mov_b32 m0, s80
	s_nop 0
	global_load_lds_dwordx4 v[180:181], off
	s_waitcnt vmcnt(8)
	s_waitcnt lgkmcnt(0)
	s_barrier
	s_setprio 1
	s_waitcnt lgkmcnt(0)
	v_mfma_f32_16x16x32_bf16 v[132:135], v[152:155], v[188:191], v[132:135]
	v_mfma_f32_16x16x32_bf16 v[132:135], v[156:159], v[192:195], v[132:135]
	v_mfma_f32_16x16x32_bf16 v[128:131], v[160:163], v[188:191], v[128:131]
	v_mfma_f32_16x16x32_bf16 v[128:131], v[164:167], v[192:195], v[128:131]
	v_mfma_f32_16x16x32_bf16 v[120:123], v[176:179], v[188:191], v[120:123]
	v_mfma_f32_16x16x32_bf16 v[120:123], v[184:187], v[192:195], v[120:123]
	v_mfma_f32_16x16x32_bf16 v[124:127], v[168:171], v[188:191], v[124:127]
	v_mfma_f32_16x16x32_bf16 v[124:127], v[172:175], v[192:195], v[124:127]
	v_mfma_f32_16x16x32_bf16 v[108:111], v[168:171], v[196:199], v[108:111]
	v_mfma_f32_16x16x32_bf16 v[108:111], v[172:175], v[200:203], v[108:111]
	v_mfma_f32_16x16x32_bf16 v[104:107], v[176:179], v[196:199], v[104:107]
	v_mfma_f32_16x16x32_bf16 v[104:107], v[184:187], v[200:203], v[104:107]
	v_mfma_f32_16x16x32_bf16 v[112:115], v[160:163], v[196:199], v[112:115]
	v_mfma_f32_16x16x32_bf16 v[112:115], v[164:167], v[200:203], v[112:115]
	v_mfma_f32_16x16x32_bf16 v[116:119], v[152:155], v[196:199], v[116:119]
	v_mfma_f32_16x16x32_bf16 v[116:119], v[156:159], v[200:203], v[116:119]
	s_setprio 0
	s_setprio 1
	v_mfma_f32_16x16x32_bf16 v[100:103], v[152:155], v[204:207], v[100:103]
	v_mfma_f32_16x16x32_bf16 v[100:103], v[156:159], v[230:233], v[100:103]
	v_mfma_f32_16x16x32_bf16 v[96:99], v[160:163], v[204:207], v[96:99]
	v_mfma_f32_16x16x32_bf16 v[96:99], v[164:167], v[230:233], v[96:99]
	v_mfma_f32_16x16x32_bf16 v[88:91], v[176:179], v[204:207], v[88:91]
	v_mfma_f32_16x16x32_bf16 v[88:91], v[184:187], v[230:233], v[88:91]
	v_mfma_f32_16x16x32_bf16 v[92:95], v[168:171], v[204:207], v[92:95]
	v_mfma_f32_16x16x32_bf16 v[92:95], v[172:175], v[230:233], v[92:95]
	v_mfma_f32_16x16x32_bf16 v[76:79], v[168:171], v[234:237], v[76:79]
	v_mfma_f32_16x16x32_bf16 v[76:79], v[172:175], v[238:241], v[76:79]
	v_mfma_f32_16x16x32_bf16 v[72:75], v[176:179], v[234:237], v[72:75]
	v_mfma_f32_16x16x32_bf16 v[72:75], v[184:187], v[238:241], v[72:75]
	v_mfma_f32_16x16x32_bf16 v[80:83], v[160:163], v[234:237], v[80:83]
	v_mfma_f32_16x16x32_bf16 v[80:83], v[164:167], v[238:241], v[80:83]
	v_mfma_f32_16x16x32_bf16 v[84:87], v[152:155], v[234:237], v[84:87]
	v_mfma_f32_16x16x32_bf16 v[84:87], v[156:159], v[238:241], v[84:87]
	s_setprio 0
	s_barrier
	s_add_i32 s81, s19, s46
	s_add_i32 s82, s81, 0x2000
	v_lshl_add_u64 v[208:209], s[84:85], 0, v[0:1]
	s_mov_b32 m0, s81
	s_add_u32 s40, s84, s48
	ds_read_b128 v[188:191], v149 offset:16384
	ds_read_b128 v[192:195], v149 offset:17408
	ds_read_b128 v[196:199], v149 offset:18432
	ds_read_b128 v[200:203], v149 offset:19456
	ds_read_b128 v[204:207], v149 offset:20480
	ds_read_b128 v[230:233], v149 offset:21504
	ds_read_b128 v[234:237], v149 offset:22528
	ds_read_b128 v[238:241], v149 offset:23552
	global_load_lds_dwordx4 v[208:209], off
	v_lshl_add_u64 v[216:217], s[84:85], 0, v[138:139]
	s_mov_b32 m0, s82
	s_addc_u32 s41, s85, s49
	s_add_i32 s83, s83, s46
	global_load_lds_dwordx4 v[216:217], off
	v_lshl_add_u64 v[224:225], s[40:41], 0, v[0:1]
	s_mov_b32 m0, s83
	s_add_i32 s84, s83, 0x2000
	global_load_lds_dwordx4 v[224:225], off
	v_lshl_add_u64 v[226:227], s[40:41], 0, v[138:139]
	s_mov_b32 m0, s84
	v_lshl_add_u64 v[228:229], s[22:23], 0, v[2:3]
	global_load_lds_dwordx4 v[226:227], off
	s_mov_b32 m0, s47
	v_lshl_add_u64 v[242:243], s[22:23], 0, v[136:137]
	global_load_lds_dwordx4 v[228:229], off
	s_mov_b32 m0, s52
	s_nop 0
	global_load_lds_dwordx4 v[242:243], off
	s_waitcnt vmcnt(8)
	s_waitcnt lgkmcnt(0)
	s_barrier
; #define PG8_STAGE(bufoff, gbase, voff) do { _Pragma("unroll") for (int _i = 0; _i < 2; ++_i) \
;         __builtin_amdgcn_global_load_lds((const unsigned*)((const char*)(gbase) + (voff)[_i]), (PG8_LAS unsigned*)(lds + (bufoff) + ldsw + _i * 8192), 16, 0, 0); } while (0)
; #define PG8_LDA(dst, b, h) do { _Pragma("unroll") for (int m = 0; m < 4; ++m) _Pragma("unroll") for (int k = 0; k < 2; ++k) dst[m][k] = *(const PG8_LAS bf16x8*)(lds + PG8_SA(b, h) + aoff + m * 2048 + k * 1024); } while (0)
; #define PG8_LDB(dst, b, h) do { _Pragma("unroll") for (int n = 0; n < 2; ++n) _Pragma("unroll") for (int k = 0; k < 2; ++k) dst[n][k] = *(const PG8_LAS bf16x8*)(lds + PG8_SB(b, h) + boff + n * 2048 + k * 1024); } while (0)
; #define PG8_MMA(ai, bj, At, Bt) do { __builtin_amdgcn_s_setprio(1); _Pragma("unroll") for (int m = 0; m < 4; ++m) _Pragma("unroll") for (int n = 0; n < 2; ++n) _Pragma("unroll") for (int k = 0; k < 2; ++k) \
;         acc[ai][bj][m][n] = __builtin_amdgcn_mfma_f32_16x16x32_bf16(Bt[n][k], At[m][k], acc[ai][bj][m][n], 0, 0, 0); __builtin_amdgcn_s_setprio(0); } while (0)
; #define PG8_BAR __builtin_amdgcn_s_barrier()
; template <class Epi, class Sched, bool ALIGN_EPI = false, bool SP2 = false>
; __device__ __forceinline__ void gemm_phase(PG8_LAS unsigned char* lds, const Gemm g, const Sched& S, const Epi& E) {
;     ...
;             if constexpr (SP2) {
;             PG8_LDB(B0, 0, 0); PG8_LDB(B1, 0, 1); PG8_SCHED; PG8_LDA(At, 0, 0); PG8_STAGE(PG8_SA(1, 1), a1 + hstep, voffA);
;             PG8_WAIT_V(8); PG8_WAIT_L(0); PG8_BAR; PG8_MMA(0, 0, At, B0); PG8_MMA(0, 1, At, B1); PG8_BAR; PG8_SCHED;
;             PG8_LDA(At, 0, 1); PG8_STAGE(PG8_SB(0, 0), b2, voffB); PG8_STAGE(PG8_SB(0, 1), b2 + hstep, voffB); PG8_STAGE(PG8_SA(0, 0), a2, voffA);
;             PG8_WAIT_V(8); PG8_WAIT_L(0); PG8_BAR; PG8_MMA(1, 0, At, B0); PG8_MMA(1, 1, At, B1); PG8_BAR; PG8_SCHED;
;             PG8_LDB(B0, 1, 0); PG8_LDB(B1, 1, 1); PG8_SCHED; PG8_LDA(At, 1, 0); PG8_STAGE(PG8_SA(0, 1), a2 + hstep, voffA);
;             PG8_WAIT_V(8); PG8_WAIT_L(0); PG8_BAR; PG8_MMA(0, 0, At, B0); PG8_MMA(0, 1, At, B1); PG8_BAR; PG8_SCHED;
;             PG8_LDA(At, 1, 1); PG8_STAGE(PG8_SB(1, 0), b3, voffB); PG8_STAGE(PG8_SB(1, 1), b3 + hstep, voffB); PG8_STAGE(PG8_SA(1, 0), a3, voffA);
;             PG8_WAIT_V(8); PG8_WAIT_L(0); PG8_BAR; PG8_MMA(1, 0, At, B0); PG8_MMA(1, 1, At, B1); PG8_BAR; PG8_SCHED;
	s_setprio 1
	s_waitcnt lgkmcnt(0)
	v_mfma_f32_16x16x32_bf16 v[68:71], v[152:155], v[188:191], v[68:71]
	v_mfma_f32_16x16x32_bf16 v[68:71], v[156:159], v[192:195], v[68:71]
	v_mfma_f32_16x16x32_bf16 v[64:67], v[160:163], v[188:191], v[64:67]
	v_mfma_f32_16x16x32_bf16 v[64:67], v[164:167], v[192:195], v[64:67]
	v_mfma_f32_16x16x32_bf16 v[56:59], v[176:179], v[188:191], v[56:59]
	v_mfma_f32_16x16x32_bf16 v[56:59], v[184:187], v[192:195], v[56:59]
	v_mfma_f32_16x16x32_bf16 v[60:63], v[168:171], v[188:191], v[60:63]
	v_mfma_f32_16x16x32_bf16 v[60:63], v[172:175], v[192:195], v[60:63]
	v_mfma_f32_16x16x32_bf16 v[44:47], v[168:171], v[196:199], v[44:47]
	v_mfma_f32_16x16x32_bf16 v[44:47], v[172:175], v[200:203], v[44:47]
	v_mfma_f32_16x16x32_bf16 v[40:43], v[176:179], v[196:199], v[40:43]
	v_mfma_f32_16x16x32_bf16 v[40:43], v[184:187], v[200:203], v[40:43]
	v_mfma_f32_16x16x32_bf16 v[48:51], v[160:163], v[196:199], v[48:51]
	v_mfma_f32_16x16x32_bf16 v[48:51], v[164:167], v[200:203], v[48:51]
	v_mfma_f32_16x16x32_bf16 v[52:55], v[152:155], v[196:199], v[52:55]
	v_mfma_f32_16x16x32_bf16 v[52:55], v[156:159], v[200:203], v[52:55]
	s_setprio 0
	s_setprio 1
	v_mfma_f32_16x16x32_bf16 v[36:39], v[152:155], v[204:207], v[36:39]
	v_mfma_f32_16x16x32_bf16 v[36:39], v[156:159], v[230:233], v[36:39]
	v_mfma_f32_16x16x32_bf16 v[32:35], v[160:163], v[204:207], v[32:35]
	v_mfma_f32_16x16x32_bf16 v[32:35], v[164:167], v[230:233], v[32:35]
	v_mfma_f32_16x16x32_bf16 v[24:27], v[176:179], v[204:207], v[24:27]
	v_mfma_f32_16x16x32_bf16 v[24:27], v[184:187], v[230:233], v[24:27]
	v_mfma_f32_16x16x32_bf16 v[28:31], v[168:171], v[204:207], v[28:31]
	v_mfma_f32_16x16x32_bf16 v[28:31], v[172:175], v[230:233], v[28:31]
	v_mfma_f32_16x16x32_bf16 v[12:15], v[168:171], v[234:237], v[12:15]
	v_mfma_f32_16x16x32_bf16 v[12:15], v[172:175], v[238:241], v[12:15]
	v_mfma_f32_16x16x32_bf16 v[8:11], v[176:179], v[234:237], v[8:11]
	v_mfma_f32_16x16x32_bf16 v[8:11], v[184:187], v[238:241], v[8:11]
	v_mfma_f32_16x16x32_bf16 v[16:19], v[160:163], v[234:237], v[16:19]
	v_mfma_f32_16x16x32_bf16 v[16:19], v[164:167], v[238:241], v[16:19]
	v_mfma_f32_16x16x32_bf16 v[20:23], v[152:155], v[234:237], v[20:23]
	v_mfma_f32_16x16x32_bf16 v[20:23], v[156:159], v[238:241], v[20:23]
	s_setprio 0
	s_barrier
	s_add_i32 s87, 0, 0x1c000
	v_add_u32_e32 v152, s91, v147
	v_add_u32_e32 v153, s87, v147
	ds_read_b128 v[154:157], v152
	ds_read_b128 v[158:161], v152 offset:1024
	ds_read_b128 v[162:165], v152 offset:2048
	ds_read_b128 v[166:169], v152 offset:3072
	ds_read_b128 v[170:173], v153
	ds_read_b128 v[174:177], v153 offset:1024
	ds_read_b128 v[178:181], v153 offset:2048
	ds_read_b128 v[184:187], v153 offset:3072
	s_add_u32 s22, s22, s48
	s_addc_u32 s23, s23, s49
	s_mov_b32 m0, s53
	v_lshl_add_u64 v[244:245], s[22:23], 0, v[2:3]
	ds_read_b128 v[188:191], v149 offset:32768
	ds_read_b128 v[192:195], v149 offset:33792
	ds_read_b128 v[196:199], v149 offset:34816
	ds_read_b128 v[200:203], v149 offset:35840
	ds_read_b128 v[204:207], v149 offset:36864
	ds_read_b128 v[230:233], v149 offset:37888
	ds_read_b128 v[234:237], v149 offset:38912
	ds_read_b128 v[238:241], v149 offset:39936
	global_load_lds_dwordx4 v[244:245], off
	v_lshl_add_u64 v[244:245], s[22:23], 0, v[136:137]
	s_mov_b32 m0, s72
	s_nop 0
	global_load_lds_dwordx4 v[244:245], off
	s_waitcnt vmcnt(8)
	s_waitcnt lgkmcnt(0)
	s_barrier
	s_setprio 1
	s_waitcnt lgkmcnt(0)
	v_mfma_f32_16x16x32_bf16 v[132:135], v[154:157], v[188:191], v[132:135]
	v_mfma_f32_16x16x32_bf16 v[132:135], v[158:161], v[192:195], v[132:135]
	v_mfma_f32_16x16x32_bf16 v[128:131], v[162:165], v[188:191], v[128:131]
	v_mfma_f32_16x16x32_bf16 v[128:131], v[166:169], v[192:195], v[128:131]
	v_mfma_f32_16x16x32_bf16 v[120:123], v[178:181], v[188:191], v[120:123]
	v_mfma_f32_16x16x32_bf16 v[120:123], v[184:187], v[192:195], v[120:123]
	v_mfma_f32_16x16x32_bf16 v[124:127], v[170:173], v[188:191], v[124:127]
	v_mfma_f32_16x16x32_bf16 v[124:127], v[174:177], v[192:195], v[124:127]
	v_mfma_f32_16x16x32_bf16 v[108:111], v[170:173], v[196:199], v[108:111]
	v_mfma_f32_16x16x32_bf16 v[108:111], v[174:177], v[200:203], v[108:111]
	v_mfma_f32_16x16x32_bf16 v[104:107], v[178:181], v[196:199], v[104:107]
	v_mfma_f32_16x16x32_bf16 v[104:107], v[184:187], v[200:203], v[104:107]
	v_mfma_f32_16x16x32_bf16 v[112:115], v[162:165], v[196:199], v[112:115]
	v_mfma_f32_16x16x32_bf16 v[112:115], v[166:169], v[200:203], v[112:115]
	v_mfma_f32_16x16x32_bf16 v[116:119], v[154:157], v[196:199], v[116:119]
	v_mfma_f32_16x16x32_bf16 v[116:119], v[158:161], v[200:203], v[116:119]
	s_setprio 0
	s_setprio 1
	v_mfma_f32_16x16x32_bf16 v[100:103], v[154:157], v[204:207], v[100:103]
	v_mfma_f32_16x16x32_bf16 v[100:103], v[158:161], v[230:233], v[100:103]
	v_mfma_f32_16x16x32_bf16 v[96:99], v[162:165], v[204:207], v[96:99]
	v_mfma_f32_16x16x32_bf16 v[96:99], v[166:169], v[230:233], v[96:99]
	v_mfma_f32_16x16x32_bf16 v[88:91], v[178:181], v[204:207], v[88:91]
	v_mfma_f32_16x16x32_bf16 v[88:91], v[184:187], v[230:233], v[88:91]
	v_mfma_f32_16x16x32_bf16 v[92:95], v[170:173], v[204:207], v[92:95]
	v_mfma_f32_16x16x32_bf16 v[92:95], v[174:177], v[230:233], v[92:95]
	v_mfma_f32_16x16x32_bf16 v[76:79], v[170:173], v[234:237], v[76:79]
	v_mfma_f32_16x16x32_bf16 v[76:79], v[174:177], v[238:241], v[76:79]
	v_mfma_f32_16x16x32_bf16 v[72:75], v[178:181], v[234:237], v[72:75]
	v_mfma_f32_16x16x32_bf16 v[72:75], v[184:187], v[238:241], v[72:75]
	v_mfma_f32_16x16x32_bf16 v[80:83], v[162:165], v[234:237], v[80:83]
	v_mfma_f32_16x16x32_bf16 v[80:83], v[166:169], v[238:241], v[80:83]
	v_mfma_f32_16x16x32_bf16 v[84:87], v[154:157], v[234:237], v[84:87]
	v_mfma_f32_16x16x32_bf16 v[84:87], v[158:161], v[238:241], v[84:87]
	s_setprio 0
	s_barrier
; #define PG8_STAGE(bufoff, gbase, voff) do { _Pragma("unroll") for (int _i = 0; _i < 2; ++_i) \
;         __builtin_amdgcn_global_load_lds((const unsigned*)((const char*)(gbase) + (voff)[_i]), (PG8_LAS unsigned*)(lds + (bufoff) + ldsw + _i * 8192), 16, 0, 0); } while (0)
; #define PG8_LDA(dst, b, h) do { _Pragma("unroll") for (int m = 0; m < 4; ++m) _Pragma("unroll") for (int k = 0; k < 2; ++k) dst[m][k] = *(const PG8_LAS bf16x8*)(lds + PG8_SA(b, h) + aoff + m * 2048 + k * 1024); } while (0)
; #define PG8_WAIT_V(n) asm volatile("s_waitcnt vmcnt(" #n ")" ::: "memory")
; #define PG8_WAIT_L(n) asm volatile("s_waitcnt lgkmcnt(" #n ")" ::: "memory")
; template <class Epi, class Sched, bool ALIGN_EPI = false, bool SP2 = false>
; __device__ __forceinline__ void gemm_phase(PG8_LAS unsigned char* lds, const Gemm g, const Sched& S, const Epi& E) {
;     ...
;             if constexpr (Epi::KHOOK) { if ((t & 7) == 0 && t != 0) E.khook(acc, t >> 3, wr, fr, lds); }
;             const bool last = (t == nt - 2);
;             const char* a1 = cA + (size_t)(t + 1) * kstep;
;             const char* a2 = last ? nA : cA + (size_t)(t + 2) * kstep; const char* b2 = last ? nB : cB + (size_t)(t + 2) * kstep;
;             const char* a3 = a2 + kstep; const char* b3 = b2 + kstep;
;             if (last && has_next) S.a_ready(nxt);
;             if constexpr (SP2) {
;             PG8_LDB(B0, 0, 0); PG8_LDB(B1, 0, 1); PG8_SCHED; PG8_LDA(At, 0, 0); PG8_STAGE(PG8_SA(1, 1), a1 + hstep, voffA);
;             PG8_WAIT_V(8); PG8_WAIT_L(0); PG8_BAR; PG8_MMA(0, 0, At, B0); PG8_MMA(0, 1, At, B1); PG8_BAR; PG8_SCHED;
;             PG8_LDA(At, 0, 1); PG8_STAGE(PG8_SB(0, 0), b2, voffB); PG8_STAGE(PG8_SB(0, 1), b2 + hstep, voffB); PG8_STAGE(PG8_SA(0, 0), a2, voffA);
;             PG8_WAIT_V(8); PG8_WAIT_L(0); PG8_BAR; PG8_MMA(1, 0, At, B0); PG8_MMA(1, 1, At, B1); PG8_BAR; PG8_SCHED;
;             PG8_LDB(B0, 1, 0); PG8_LDB(B1, 1, 1); PG8_SCHED; PG8_LDA(At, 1, 0); PG8_STAGE(PG8_SA(0, 1), a2 + hstep, voffA);
;             PG8_WAIT_V(8); PG8_WAIT_L(0); PG8_BAR; PG8_MMA(0, 0, At, B0); PG8_MMA(0, 1, At, B1); PG8_BAR; PG8_SCHED;
;             PG8_LDA(At, 1, 1); PG8_STAGE(PG8_SB(1, 0), b3, voffB); PG8_STAGE(PG8_SB(1, 1), b3 + hstep, voffB); PG8_STAGE(PG8_SA(1, 0), a3, voffA);
;             PG8_WAIT_V(8); PG8_WAIT_L(0); PG8_BAR; PG8_MMA(1, 0, At, B0); PG8_MMA(1, 1, At, B1); PG8_BAR; PG8_SCHED;
	s_add_i32 s85, s91, s46
	v_lshl_add_u64 v[208:209], v[208:209], 0, s[24:25]
	s_mov_b32 m0, s85
	s_add_i32 s86, s85, 0x2000
	ds_read_b128 v[188:191], v149 offset:49152
	ds_read_b128 v[192:195], v149 offset:50176
	ds_read_b128 v[196:199], v149 offset:51200
	ds_read_b128 v[200:203], v149 offset:52224
	ds_read_b128 v[204:207], v149 offset:53248
	ds_read_b128 v[230:233], v149 offset:54272
	ds_read_b128 v[234:237], v149 offset:55296
	ds_read_b128 v[238:241], v149 offset:56320
	global_load_lds_dwordx4 v[208:209], off
	v_lshl_add_u64 v[208:209], v[216:217], 0, s[24:25]
	s_mov_b32 m0, s86
	s_add_i32 s87, s87, s46
	global_load_lds_dwordx4 v[208:209], off
	v_lshl_add_u64 v[208:209], v[224:225], 0, s[24:25]
	s_mov_b32 m0, s87
	s_add_i32 s88, s87, 0x2000
	global_load_lds_dwordx4 v[208:209], off
	v_lshl_add_u64 v[208:209], v[226:227], 0, s[24:25]
	s_mov_b32 m0, s88
	s_nop 0
	global_load_lds_dwordx4 v[208:209], off
	v_lshl_add_u64 v[208:209], v[228:229], 0, s[24:25]
	s_mov_b32 m0, s75
	s_nop 0
	global_load_lds_dwordx4 v[208:209], off
	v_lshl_add_u64 v[208:209], v[242:243], 0, s[24:25]
	s_mov_b32 m0, s76
	s_nop 0
	global_load_lds_dwordx4 v[208:209], off
	s_waitcnt vmcnt(8)
	s_waitcnt lgkmcnt(0)
	s_barrier
	s_setprio 1
	s_waitcnt lgkmcnt(0)
	v_mfma_f32_16x16x32_bf16 v[68:71], v[154:157], v[188:191], v[68:71]
	v_mfma_f32_16x16x32_bf16 v[68:71], v[158:161], v[192:195], v[68:71]
	v_mfma_f32_16x16x32_bf16 v[64:67], v[162:165], v[188:191], v[64:67]
	v_mfma_f32_16x16x32_bf16 v[64:67], v[166:169], v[192:195], v[64:67]
	v_mfma_f32_16x16x32_bf16 v[56:59], v[178:181], v[188:191], v[56:59]
	v_mfma_f32_16x16x32_bf16 v[56:59], v[184:187], v[192:195], v[56:59]
	v_mfma_f32_16x16x32_bf16 v[60:63], v[170:173], v[188:191], v[60:63]
	v_mfma_f32_16x16x32_bf16 v[60:63], v[174:177], v[192:195], v[60:63]
	v_mfma_f32_16x16x32_bf16 v[44:47], v[170:173], v[196:199], v[44:47]
	v_mfma_f32_16x16x32_bf16 v[44:47], v[174:177], v[200:203], v[44:47]
	v_mfma_f32_16x16x32_bf16 v[40:43], v[178:181], v[196:199], v[40:43]
	v_mfma_f32_16x16x32_bf16 v[40:43], v[184:187], v[200:203], v[40:43]
	v_mfma_f32_16x16x32_bf16 v[48:51], v[162:165], v[196:199], v[48:51]
	v_mfma_f32_16x16x32_bf16 v[48:51], v[166:169], v[200:203], v[48:51]
	v_mfma_f32_16x16x32_bf16 v[52:55], v[154:157], v[196:199], v[52:55]
	v_mfma_f32_16x16x32_bf16 v[52:55], v[158:161], v[200:203], v[52:55]
	s_setprio 0
	s_setprio 1
	v_mfma_f32_16x16x32_bf16 v[36:39], v[154:157], v[204:207], v[36:39]
	v_mfma_f32_16x16x32_bf16 v[36:39], v[158:161], v[230:233], v[36:39]
	v_mfma_f32_16x16x32_bf16 v[32:35], v[162:165], v[204:207], v[32:35]
	v_mfma_f32_16x16x32_bf16 v[32:35], v[166:169], v[230:233], v[32:35]
	v_mfma_f32_16x16x32_bf16 v[24:27], v[178:181], v[204:207], v[24:27]
	v_mfma_f32_16x16x32_bf16 v[24:27], v[184:187], v[230:233], v[24:27]
	v_mfma_f32_16x16x32_bf16 v[28:31], v[170:173], v[204:207], v[28:31]
	v_mfma_f32_16x16x32_bf16 v[28:31], v[174:177], v[230:233], v[28:31]
	v_mfma_f32_16x16x32_bf16 v[12:15], v[170:173], v[234:237], v[12:15]
	v_mfma_f32_16x16x32_bf16 v[12:15], v[174:177], v[238:241], v[12:15]
	v_mfma_f32_16x16x32_bf16 v[8:11], v[178:181], v[234:237], v[8:11]
	v_mfma_f32_16x16x32_bf16 v[8:11], v[184:187], v[238:241], v[8:11]
	v_mfma_f32_16x16x32_bf16 v[16:19], v[162:165], v[234:237], v[16:19]
	v_mfma_f32_16x16x32_bf16 v[16:19], v[166:169], v[238:241], v[16:19]
	v_mfma_f32_16x16x32_bf16 v[20:23], v[154:157], v[234:237], v[20:23]
	v_mfma_f32_16x16x32_bf16 v[20:23], v[158:161], v[238:241], v[20:23]
	s_setprio 0
	s_barrier
	v_readlane_b32 s22, v252, 42
	v_readlane_b32 s23, v252, 43
	s_andn2_b64 vcc, exec, s[22:23]
	s_cbranch_vccnz .LBB0_251
	s_add_u32 s22, s6, 0x180
	s_addc_u32 s23, s7, 0
	s_add_u32 s89, s10, 0x200
	s_addc_u32 s92, s11, 0
	s_mov_b32 s93, 4
	v_mov_b32_e32 v154, v148
	s_add_i32 s40, s93, -2
	s_and_b32 s40, s40, 6
	s_cmp_lg_u32 s40, 0
	s_cbranch_scc1 .LBB0_250
	s_branch .LBB0_249

; #define PG8_STAGE(bufoff, gbase, voff) do { _Pragma("unroll") for (int _i = 0; _i < 2; ++_i) \
;         __builtin_amdgcn_global_load_lds((const unsigned*)((const char*)(gbase) + (voff)[_i]), (PG8_LAS unsigned*)(lds + (bufoff) + ldsw + _i * 8192), 16, 0, 0); } while (0)
; #define PG8_LDA(dst, b, h) do { _Pragma("unroll") for (int m = 0; m < 4; ++m) _Pragma("unroll") for (int k = 0; k < 2; ++k) dst[m][k] = *(const PG8_LAS bf16x8*)(lds + PG8_SA(b, h) + aoff + m * 2048 + k * 1024); } while (0)
; #define PG8_WAIT_V(n) asm volatile("s_waitcnt vmcnt(" #n ")" ::: "memory")
; #define PG8_BAR __builtin_amdgcn_s_barrier()
; template <class Epi, class Sched, bool ALIGN_EPI = false, bool SP2 = false>
; __device__ __forceinline__ void gemm_phase(PG8_LAS unsigned char* lds, const Gemm g, const Sched& S, const Epi& E) {
;     ...
;         for (int t = 0; t < nt; t += 2) {
;             if constexpr (Epi::KHOOK) { if ((t & 7) == 0 && t != 0) E.khook(acc, t >> 3, wr, fr, lds); }
;             const bool last = (t == nt - 2);
;             const char* a1 = cA + (size_t)(t + 1) * kstep;
;             const char* a2 = last ? nA : cA + (size_t)(t + 2) * kstep; const char* b2 = last ? nB : cB + (size_t)(t + 2) * kstep;
;             const char* a3 = a2 + kstep; const char* b3 = b2 + kstep;
;             if (last && has_next) S.a_ready(nxt);
;             if constexpr (SP2) {
;             PG8_LDB(B0, 0, 0); PG8_LDB(B1, 0, 1); PG8_SCHED; PG8_LDA(At, 0, 0); PG8_STAGE(PG8_SA(1, 1), a1 + hstep, voffA);
;             PG8_WAIT_V(8); PG8_WAIT_L(0); PG8_BAR; PG8_MMA(0, 0, At, B0); PG8_MMA(0, 1, At, B1); PG8_BAR; PG8_SCHED;
;             PG8_LDA(At, 0, 1); PG8_STAGE(PG8_SB(0, 0), b2, voffB); PG8_STAGE(PG8_SB(0, 1), b2 + hstep, voffB); PG8_STAGE(PG8_SA(0, 0), a2, voffA);
;             PG8_WAIT_V(8); PG8_WAIT_L(0); PG8_BAR; PG8_MMA(1, 0, At, B0); PG8_MMA(1, 1, At, B1); PG8_BAR; PG8_SCHED;
;             PG8_LDB(B0, 1, 0); PG8_LDB(B1, 1, 1); PG8_SCHED; PG8_LDA(At, 1, 0); PG8_STAGE(PG8_SA(0, 1), a2 + hstep, voffA);
;             PG8_WAIT_V(8); PG8_WAIT_L(0); PG8_BAR; PG8_MMA(0, 0, At, B0); PG8_MMA(0, 1, At, B1); PG8_BAR; PG8_SCHED;
;             PG8_LDA(At, 1, 1); PG8_STAGE(PG8_SB(1, 0), b3, voffB); PG8_STAGE(PG8_SB(1, 1), b3 + hstep, voffB); PG8_STAGE(PG8_SA(1, 0), a3, voffA);
;             PG8_WAIT_V(8); PG8_WAIT_L(0); PG8_BAR; PG8_MMA(1, 0, At, B0); PG8_MMA(1, 1, At, B1); PG8_BAR; PG8_SCHED;
.LBB0_250:
	ds_read_b128 v[156:159], v150
	ds_read_b128 v[160:163], v150 offset:1024
	ds_read_b128 v[164:167], v150 offset:2048
	ds_read_b128 v[168:171], v150 offset:3072
	ds_read_b128 v[172:175], v151
	ds_read_b128 v[176:179], v151 offset:1024
	ds_read_b128 v[184:187], v151 offset:2048
	ds_read_b128 v[188:191], v151 offset:3072
	s_add_u32 s40, s22, 0x80
	s_addc_u32 s41, s23, 0
	s_cmp_eq_u32 s9, s93
	s_cselect_b32 s40, s4, s40
	s_cselect_b32 s41, s5, s41
	s_cselect_b32 s95, s17, s92
	s_cselect_b32 s94, s16, s89
	s_mov_b32 m0, s37
	v_lshl_add_u64 v[180:181], s[22:23], 0, v[140:141]
	ds_read_b128 v[192:195], v149
	ds_read_b128 v[196:199], v149 offset:1024
	ds_read_b128 v[200:203], v149 offset:2048
	ds_read_b128 v[204:207], v149 offset:3072
	ds_read_b128 v[230:233], v149 offset:4096
	ds_read_b128 v[234:237], v149 offset:5120
	ds_read_b128 v[238:241], v149 offset:6144
	ds_read_b128 v[242:245], v149 offset:7168
	global_load_lds_dwordx4 v[180:181], off
	v_lshl_add_u64 v[180:181], s[22:23], 0, v[142:143]
	s_mov_b32 m0, s80
	s_nop 0
	global_load_lds_dwordx4 v[180:181], off
	s_waitcnt vmcnt(8)
	s_waitcnt lgkmcnt(0)
	s_barrier
	s_setprio 1
	s_waitcnt lgkmcnt(0)
	v_mfma_f32_16x16x32_bf16 v[132:135], v[156:159], v[192:195], v[132:135]
	v_mfma_f32_16x16x32_bf16 v[132:135], v[160:163], v[196:199], v[132:135]
	v_mfma_f32_16x16x32_bf16 v[128:131], v[164:167], v[192:195], v[128:131]
	v_mfma_f32_16x16x32_bf16 v[128:131], v[168:171], v[196:199], v[128:131]
	v_mfma_f32_16x16x32_bf16 v[120:123], v[184:187], v[192:195], v[120:123]
	v_mfma_f32_16x16x32_bf16 v[120:123], v[188:191], v[196:199], v[120:123]
	v_mfma_f32_16x16x32_bf16 v[124:127], v[172:175], v[192:195], v[124:127]
	v_mfma_f32_16x16x32_bf16 v[124:127], v[176:179], v[196:199], v[124:127]
	v_mfma_f32_16x16x32_bf16 v[108:111], v[172:175], v[200:203], v[108:111]
	v_mfma_f32_16x16x32_bf16 v[108:111], v[176:179], v[204:207], v[108:111]
	v_mfma_f32_16x16x32_bf16 v[104:107], v[184:187], v[200:203], v[104:107]
	v_mfma_f32_16x16x32_bf16 v[104:107], v[188:191], v[204:207], v[104:107]
	v_mfma_f32_16x16x32_bf16 v[112:115], v[164:167], v[200:203], v[112:115]
	v_mfma_f32_16x16x32_bf16 v[112:115], v[168:171], v[204:207], v[112:115]
	v_mfma_f32_16x16x32_bf16 v[116:119], v[156:159], v[200:203], v[116:119]
	v_mfma_f32_16x16x32_bf16 v[116:119], v[160:163], v[204:207], v[116:119]
	s_setprio 0
	s_setprio 1
	v_mfma_f32_16x16x32_bf16 v[100:103], v[156:159], v[230:233], v[100:103]
	v_mfma_f32_16x16x32_bf16 v[100:103], v[160:163], v[234:237], v[100:103]
	v_mfma_f32_16x16x32_bf16 v[96:99], v[164:167], v[230:233], v[96:99]
	v_mfma_f32_16x16x32_bf16 v[96:99], v[168:171], v[234:237], v[96:99]
	v_mfma_f32_16x16x32_bf16 v[88:91], v[184:187], v[230:233], v[88:91]
	v_mfma_f32_16x16x32_bf16 v[88:91], v[188:191], v[234:237], v[88:91]
	v_mfma_f32_16x16x32_bf16 v[92:95], v[172:175], v[230:233], v[92:95]
	v_mfma_f32_16x16x32_bf16 v[92:95], v[176:179], v[234:237], v[92:95]
	v_mfma_f32_16x16x32_bf16 v[76:79], v[172:175], v[238:241], v[76:79]
	v_mfma_f32_16x16x32_bf16 v[76:79], v[176:179], v[242:245], v[76:79]
	v_mfma_f32_16x16x32_bf16 v[72:75], v[184:187], v[238:241], v[72:75]
	v_mfma_f32_16x16x32_bf16 v[72:75], v[188:191], v[242:245], v[72:75]
	v_mfma_f32_16x16x32_bf16 v[80:83], v[164:167], v[238:241], v[80:83]
	v_mfma_f32_16x16x32_bf16 v[80:83], v[168:171], v[242:245], v[80:83]
	v_mfma_f32_16x16x32_bf16 v[84:87], v[156:159], v[238:241], v[84:87]
	v_mfma_f32_16x16x32_bf16 v[84:87], v[160:163], v[242:245], v[84:87]
	s_setprio 0
	s_barrier
	s_mov_b32 m0, s81
	v_lshl_add_u64 v[180:181], s[94:95], 0, v[0:1]
	v_lshl_add_u64 v[208:209], s[94:95], 0, v[138:139]
	s_add_u32 s94, s94, s48
	ds_read_b128 v[192:195], v149 offset:16384
	ds_read_b128 v[196:199], v149 offset:17408
	ds_read_b128 v[200:203], v149 offset:18432
	ds_read_b128 v[204:207], v149 offset:19456
	ds_read_b128 v[230:233], v149 offset:20480
	ds_read_b128 v[234:237], v149 offset:21504
	ds_read_b128 v[238:241], v149 offset:22528
	ds_read_b128 v[242:245], v149 offset:23552
	global_load_lds_dwordx4 v[180:181], off
	s_mov_b32 m0, s82
	s_addc_u32 s95, s95, s49
	global_load_lds_dwordx4 v[208:209], off
	v_lshl_add_u64 v[216:217], s[94:95], 0, v[0:1]
	s_mov_b32 m0, s83
	v_lshl_add_u64 v[224:225], s[94:95], 0, v[138:139]
	global_load_lds_dwordx4 v[216:217], off
	s_mov_b32 m0, s84
	v_lshl_add_u64 v[226:227], s[40:41], 0, v[2:3]
	global_load_lds_dwordx4 v[224:225], off
	s_mov_b32 m0, s47
	v_lshl_add_u64 v[228:229], s[40:41], 0, v[136:137]
	global_load_lds_dwordx4 v[226:227], off
	s_mov_b32 m0, s52
	s_nop 0
	global_load_lds_dwordx4 v[228:229], off
	s_waitcnt vmcnt(8)
	s_waitcnt lgkmcnt(0)
	s_barrier
; #define PG8_STAGE(bufoff, gbase, voff) do { _Pragma("unroll") for (int _i = 0; _i < 2; ++_i) \
;         __builtin_amdgcn_global_load_lds((const unsigned*)((const char*)(gbase) + (voff)[_i]), (PG8_LAS unsigned*)(lds + (bufoff) + ldsw + _i * 8192), 16, 0, 0); } while (0)
; #define PG8_LDA(dst, b, h) do { _Pragma("unroll") for (int m = 0; m < 4; ++m) _Pragma("unroll") for (int k = 0; k < 2; ++k) dst[m][k] = *(const PG8_LAS bf16x8*)(lds + PG8_SA(b, h) + aoff + m * 2048 + k * 1024); } while (0)
; #define PG8_LDB(dst, b, h) do { _Pragma("unroll") for (int n = 0; n < 2; ++n) _Pragma("unroll") for (int k = 0; k < 2; ++k) dst[n][k] = *(const PG8_LAS bf16x8*)(lds + PG8_SB(b, h) + boff + n * 2048 + k * 1024); } while (0)
; #define PG8_MMA(ai, bj, At, Bt) do { __builtin_amdgcn_s_setprio(1); _Pragma("unroll") for (int m = 0; m < 4; ++m) _Pragma("unroll") for (int n = 0; n < 2; ++n) _Pragma("unroll") for (int k = 0; k < 2; ++k) \
;         acc[ai][bj][m][n] = __builtin_amdgcn_mfma_f32_16x16x32_bf16(Bt[n][k], At[m][k], acc[ai][bj][m][n], 0, 0, 0); __builtin_amdgcn_s_setprio(0); } while (0)
; #define PG8_BAR __builtin_amdgcn_s_barrier()
; template <class Epi, class Sched, bool ALIGN_EPI = false, bool SP2 = false>
; __device__ __forceinline__ void gemm_phase(PG8_LAS unsigned char* lds, const Gemm g, const Sched& S, const Epi& E) {
;     ...
;             if constexpr (SP2) {
;             PG8_LDB(B0, 0, 0); PG8_LDB(B1, 0, 1); PG8_SCHED; PG8_LDA(At, 0, 0); PG8_STAGE(PG8_SA(1, 1), a1 + hstep, voffA);
;             PG8_WAIT_V(8); PG8_WAIT_L(0); PG8_BAR; PG8_MMA(0, 0, At, B0); PG8_MMA(0, 1, At, B1); PG8_BAR; PG8_SCHED;
;             PG8_LDA(At, 0, 1); PG8_STAGE(PG8_SB(0, 0), b2, voffB); PG8_STAGE(PG8_SB(0, 1), b2 + hstep, voffB); PG8_STAGE(PG8_SA(0, 0), a2, voffA);
;             PG8_WAIT_V(8); PG8_WAIT_L(0); PG8_BAR; PG8_MMA(1, 0, At, B0); PG8_MMA(1, 1, At, B1); PG8_BAR; PG8_SCHED;
;             PG8_LDB(B0, 1, 0); PG8_LDB(B1, 1, 1); PG8_SCHED; PG8_LDA(At, 1, 0); PG8_STAGE(PG8_SA(0, 1), a2 + hstep, voffA);
;             PG8_WAIT_V(8); PG8_WAIT_L(0); PG8_BAR; PG8_MMA(0, 0, At, B0); PG8_MMA(0, 1, At, B1); PG8_BAR; PG8_SCHED;
;             PG8_LDA(At, 1, 1); PG8_STAGE(PG8_SB(1, 0), b3, voffB); PG8_STAGE(PG8_SB(1, 1), b3 + hstep, voffB); PG8_STAGE(PG8_SA(1, 0), a3, voffA);
;             PG8_WAIT_V(8); PG8_WAIT_L(0); PG8_BAR; PG8_MMA(1, 0, At, B0); PG8_MMA(1, 1, At, B1); PG8_BAR; PG8_SCHED;
	s_setprio 1
	s_waitcnt lgkmcnt(0)
	v_mfma_f32_16x16x32_bf16 v[68:71], v[156:159], v[192:195], v[68:71]
	v_mfma_f32_16x16x32_bf16 v[68:71], v[160:163], v[196:199], v[68:71]
	v_mfma_f32_16x16x32_bf16 v[64:67], v[164:167], v[192:195], v[64:67]
	v_mfma_f32_16x16x32_bf16 v[64:67], v[168:171], v[196:199], v[64:67]
	v_mfma_f32_16x16x32_bf16 v[56:59], v[184:187], v[192:195], v[56:59]
	v_mfma_f32_16x16x32_bf16 v[56:59], v[188:191], v[196:199], v[56:59]
	v_mfma_f32_16x16x32_bf16 v[60:63], v[172:175], v[192:195], v[60:63]
	v_mfma_f32_16x16x32_bf16 v[60:63], v[176:179], v[196:199], v[60:63]
	v_mfma_f32_16x16x32_bf16 v[44:47], v[172:175], v[200:203], v[44:47]
	v_mfma_f32_16x16x32_bf16 v[44:47], v[176:179], v[204:207], v[44:47]
	v_mfma_f32_16x16x32_bf16 v[40:43], v[184:187], v[200:203], v[40:43]
	v_mfma_f32_16x16x32_bf16 v[40:43], v[188:191], v[204:207], v[40:43]
	v_mfma_f32_16x16x32_bf16 v[48:51], v[164:167], v[200:203], v[48:51]
	v_mfma_f32_16x16x32_bf16 v[48:51], v[168:171], v[204:207], v[48:51]
	v_mfma_f32_16x16x32_bf16 v[52:55], v[156:159], v[200:203], v[52:55]
	v_mfma_f32_16x16x32_bf16 v[52:55], v[160:163], v[204:207], v[52:55]
	s_setprio 0
	s_setprio 1
	v_mfma_f32_16x16x32_bf16 v[36:39], v[156:159], v[230:233], v[36:39]
	v_mfma_f32_16x16x32_bf16 v[36:39], v[160:163], v[234:237], v[36:39]
	v_mfma_f32_16x16x32_bf16 v[32:35], v[164:167], v[230:233], v[32:35]
	v_mfma_f32_16x16x32_bf16 v[32:35], v[168:171], v[234:237], v[32:35]
	v_mfma_f32_16x16x32_bf16 v[24:27], v[184:187], v[230:233], v[24:27]
	v_mfma_f32_16x16x32_bf16 v[24:27], v[188:191], v[234:237], v[24:27]
	v_mfma_f32_16x16x32_bf16 v[28:31], v[172:175], v[230:233], v[28:31]
	v_mfma_f32_16x16x32_bf16 v[28:31], v[176:179], v[234:237], v[28:31]
	v_mfma_f32_16x16x32_bf16 v[12:15], v[172:175], v[238:241], v[12:15]
	v_mfma_f32_16x16x32_bf16 v[12:15], v[176:179], v[242:245], v[12:15]
	v_mfma_f32_16x16x32_bf16 v[8:11], v[184:187], v[238:241], v[8:11]
	v_mfma_f32_16x16x32_bf16 v[8:11], v[188:191], v[242:245], v[8:11]
	v_mfma_f32_16x16x32_bf16 v[16:19], v[164:167], v[238:241], v[16:19]
	v_mfma_f32_16x16x32_bf16 v[16:19], v[168:171], v[242:245], v[16:19]
	v_mfma_f32_16x16x32_bf16 v[20:23], v[156:159], v[238:241], v[20:23]
	v_mfma_f32_16x16x32_bf16 v[20:23], v[160:163], v[242:245], v[20:23]
	s_setprio 0
	s_barrier
	ds_read_b128 v[156:159], v152
	ds_read_b128 v[160:163], v152 offset:1024
	ds_read_b128 v[164:167], v152 offset:2048
	ds_read_b128 v[168:171], v152 offset:3072
	ds_read_b128 v[172:175], v153
	ds_read_b128 v[176:179], v153 offset:1024
	ds_read_b128 v[184:187], v153 offset:2048
	ds_read_b128 v[188:191], v153 offset:3072
	s_add_u32 s40, s40, s48
	s_addc_u32 s41, s41, s49
	s_mov_b32 m0, s53
	v_lshl_add_u64 v[246:247], s[40:41], 0, v[2:3]
	ds_read_b128 v[192:195], v149 offset:32768
	ds_read_b128 v[196:199], v149 offset:33792
	ds_read_b128 v[200:203], v149 offset:34816
	ds_read_b128 v[204:207], v149 offset:35840
	ds_read_b128 v[230:233], v149 offset:36864
	ds_read_b128 v[234:237], v149 offset:37888
	ds_read_b128 v[238:241], v149 offset:38912
	ds_read_b128 v[242:245], v149 offset:39936
	global_load_lds_dwordx4 v[246:247], off
	v_lshl_add_u64 v[246:247], s[40:41], 0, v[136:137]
	s_mov_b32 m0, s72
	s_nop 0
	global_load_lds_dwordx4 v[246:247], off
	s_waitcnt vmcnt(8)
	s_waitcnt lgkmcnt(0)
	s_barrier
	s_setprio 1
	s_waitcnt lgkmcnt(0)
	v_mfma_f32_16x16x32_bf16 v[132:135], v[156:159], v[192:195], v[132:135]
	v_mfma_f32_16x16x32_bf16 v[132:135], v[160:163], v[196:199], v[132:135]
	v_mfma_f32_16x16x32_bf16 v[128:131], v[164:167], v[192:195], v[128:131]
	v_mfma_f32_16x16x32_bf16 v[128:131], v[168:171], v[196:199], v[128:131]
	v_mfma_f32_16x16x32_bf16 v[120:123], v[184:187], v[192:195], v[120:123]
	v_mfma_f32_16x16x32_bf16 v[120:123], v[188:191], v[196:199], v[120:123]
	v_mfma_f32_16x16x32_bf16 v[124:127], v[172:175], v[192:195], v[124:127]
	v_mfma_f32_16x16x32_bf16 v[124:127], v[176:179], v[196:199], v[124:127]
	v_mfma_f32_16x16x32_bf16 v[108:111], v[172:175], v[200:203], v[108:111]
	v_mfma_f32_16x16x32_bf16 v[108:111], v[176:179], v[204:207], v[108:111]
	v_mfma_f32_16x16x32_bf16 v[104:107], v[184:187], v[200:203], v[104:107]
	v_mfma_f32_16x16x32_bf16 v[104:107], v[188:191], v[204:207], v[104:107]
	v_mfma_f32_16x16x32_bf16 v[112:115], v[164:167], v[200:203], v[112:115]
	v_mfma_f32_16x16x32_bf16 v[112:115], v[168:171], v[204:207], v[112:115]
	v_mfma_f32_16x16x32_bf16 v[116:119], v[156:159], v[200:203], v[116:119]
	v_mfma_f32_16x16x32_bf16 v[116:119], v[160:163], v[204:207], v[116:119]
	s_setprio 0
	s_setprio 1
	v_mfma_f32_16x16x32_bf16 v[100:103], v[156:159], v[230:233], v[100:103]
	v_mfma_f32_16x16x32_bf16 v[100:103], v[160:163], v[234:237], v[100:103]
	v_mfma_f32_16x16x32_bf16 v[96:99], v[164:167], v[230:233], v[96:99]
	v_mfma_f32_16x16x32_bf16 v[96:99], v[168:171], v[234:237], v[96:99]
	v_mfma_f32_16x16x32_bf16 v[88:91], v[184:187], v[230:233], v[88:91]
	v_mfma_f32_16x16x32_bf16 v[88:91], v[188:191], v[234:237], v[88:91]
	v_mfma_f32_16x16x32_bf16 v[92:95], v[172:175], v[230:233], v[92:95]
	v_mfma_f32_16x16x32_bf16 v[92:95], v[176:179], v[234:237], v[92:95]
	v_mfma_f32_16x16x32_bf16 v[76:79], v[172:175], v[238:241], v[76:79]
	v_mfma_f32_16x16x32_bf16 v[76:79], v[176:179], v[242:245], v[76:79]
	v_mfma_f32_16x16x32_bf16 v[72:75], v[184:187], v[238:241], v[72:75]
	v_mfma_f32_16x16x32_bf16 v[72:75], v[188:191], v[242:245], v[72:75]
	v_mfma_f32_16x16x32_bf16 v[80:83], v[164:167], v[238:241], v[80:83]
	v_mfma_f32_16x16x32_bf16 v[80:83], v[168:171], v[242:245], v[80:83]
	v_mfma_f32_16x16x32_bf16 v[84:87], v[156:159], v[238:241], v[84:87]
	v_mfma_f32_16x16x32_bf16 v[84:87], v[160:163], v[242:245], v[84:87]
	s_setprio 0
	s_barrier
; #define PG8_STAGE(bufoff, gbase, voff) do { _Pragma("unroll") for (int _i = 0; _i < 2; ++_i) \
;         __builtin_amdgcn_global_load_lds((const unsigned*)((const char*)(gbase) + (voff)[_i]), (PG8_LAS unsigned*)(lds + (bufoff) + ldsw + _i * 8192), 16, 0, 0); } while (0)
; #define PG8_LDA(dst, b, h) do { _Pragma("unroll") for (int m = 0; m < 4; ++m) _Pragma("unroll") for (int k = 0; k < 2; ++k) dst[m][k] = *(const PG8_LAS bf16x8*)(lds + PG8_SA(b, h) + aoff + m * 2048 + k * 1024); } while (0)
; #define PG8_WAIT_V(n) asm volatile("s_waitcnt vmcnt(" #n ")" ::: "memory")
; #define PG8_BAR __builtin_amdgcn_s_barrier()
; template <class Epi, class Sched, bool ALIGN_EPI = false, bool SP2 = false>
; __device__ __forceinline__ void gemm_phase(PG8_LAS unsigned char* lds, const Gemm g, const Sched& S, const Epi& E) {
;     ...
;         for (int t = 0; t < nt; t += 2) {
;             if constexpr (Epi::KHOOK) { if ((t & 7) == 0 && t != 0) E.khook(acc, t >> 3, wr, fr, lds); }
;             const bool last = (t == nt - 2);
;             const char* a1 = cA + (size_t)(t + 1) * kstep;
;             const char* a2 = last ? nA : cA + (size_t)(t + 2) * kstep; const char* b2 = last ? nB : cB + (size_t)(t + 2) * kstep;
;             const char* a3 = a2 + kstep; const char* b3 = b2 + kstep;
;             if (last && has_next) S.a_ready(nxt);
;             if constexpr (SP2) {
;             PG8_LDB(B0, 0, 0); PG8_LDB(B1, 0, 1); PG8_SCHED; PG8_LDA(At, 0, 0); PG8_STAGE(PG8_SA(1, 1), a1 + hstep, voffA);
;             PG8_WAIT_V(8); PG8_WAIT_L(0); PG8_BAR; PG8_MMA(0, 0, At, B0); PG8_MMA(0, 1, At, B1); PG8_BAR; PG8_SCHED;
;             PG8_LDA(At, 0, 1); PG8_STAGE(PG8_SB(0, 0), b2, voffB); PG8_STAGE(PG8_SB(0, 1), b2 + hstep, voffB); PG8_STAGE(PG8_SA(0, 0), a2, voffA);
;             PG8_WAIT_V(8); PG8_WAIT_L(0); PG8_BAR; PG8_MMA(1, 0, At, B0); PG8_MMA(1, 1, At, B1); PG8_BAR; PG8_SCHED;
;             PG8_LDB(B0, 1, 0); PG8_LDB(B1, 1, 1); PG8_SCHED; PG8_LDA(At, 1, 0); PG8_STAGE(PG8_SA(0, 1), a2 + hstep, voffA);
;             PG8_WAIT_V(8); PG8_WAIT_L(0); PG8_BAR; PG8_MMA(0, 0, At, B0); PG8_MMA(0, 1, At, B1); PG8_BAR; PG8_SCHED;
;             PG8_LDA(At, 1, 1); PG8_STAGE(PG8_SB(1, 0), b3, voffB); PG8_STAGE(PG8_SB(1, 1), b3 + hstep, voffB); PG8_STAGE(PG8_SA(1, 0), a3, voffA);
;             PG8_WAIT_V(8); PG8_WAIT_L(0); PG8_BAR; PG8_MMA(1, 0, At, B0); PG8_MMA(1, 1, At, B1); PG8_BAR; PG8_SCHED;
	s_mov_b32 m0, s85
	v_lshl_add_u64 v[180:181], v[180:181], 0, s[24:25]
	ds_read_b128 v[192:195], v149 offset:49152
	ds_read_b128 v[196:199], v149 offset:50176
	ds_read_b128 v[200:203], v149 offset:51200
	ds_read_b128 v[204:207], v149 offset:52224
	ds_read_b128 v[230:233], v149 offset:53248
	ds_read_b128 v[234:237], v149 offset:54272
	ds_read_b128 v[238:241], v149 offset:55296
	ds_read_b128 v[242:245], v149 offset:56320
	global_load_lds_dwordx4 v[180:181], off
	v_lshl_add_u64 v[180:181], v[208:209], 0, s[24:25]
	s_mov_b32 m0, s86
	s_nop 0
	global_load_lds_dwordx4 v[180:181], off
	v_lshl_add_u64 v[180:181], v[216:217], 0, s[24:25]
	s_mov_b32 m0, s87
	s_nop 0
	global_load_lds_dwordx4 v[180:181], off
	v_lshl_add_u64 v[180:181], v[224:225], 0, s[24:25]
	s_mov_b32 m0, s88
	s_nop 0
	global_load_lds_dwordx4 v[180:181], off
	v_lshl_add_u64 v[180:181], v[226:227], 0, s[24:25]
	s_mov_b32 m0, s75
	s_nop 0
	global_load_lds_dwordx4 v[180:181], off
	v_lshl_add_u64 v[180:181], v[228:229], 0, s[24:25]
	s_mov_b32 m0, s76
	s_nop 0
	global_load_lds_dwordx4 v[180:181], off
	s_waitcnt vmcnt(8)
	s_waitcnt lgkmcnt(0)
	s_barrier
	s_setprio 1
	s_waitcnt lgkmcnt(0)
	v_mfma_f32_16x16x32_bf16 v[68:71], v[156:159], v[192:195], v[68:71]
	v_mfma_f32_16x16x32_bf16 v[68:71], v[160:163], v[196:199], v[68:71]
	v_mfma_f32_16x16x32_bf16 v[64:67], v[164:167], v[192:195], v[64:67]
	v_mfma_f32_16x16x32_bf16 v[64:67], v[168:171], v[196:199], v[64:67]
	v_mfma_f32_16x16x32_bf16 v[56:59], v[184:187], v[192:195], v[56:59]
	v_mfma_f32_16x16x32_bf16 v[56:59], v[188:191], v[196:199], v[56:59]
	v_mfma_f32_16x16x32_bf16 v[60:63], v[172:175], v[192:195], v[60:63]
	v_mfma_f32_16x16x32_bf16 v[60:63], v[176:179], v[196:199], v[60:63]
	v_mfma_f32_16x16x32_bf16 v[44:47], v[172:175], v[200:203], v[44:47]
	v_mfma_f32_16x16x32_bf16 v[44:47], v[176:179], v[204:207], v[44:47]
	v_mfma_f32_16x16x32_bf16 v[40:43], v[184:187], v[200:203], v[40:43]
	v_mfma_f32_16x16x32_bf16 v[40:43], v[188:191], v[204:207], v[40:43]
	v_mfma_f32_16x16x32_bf16 v[48:51], v[164:167], v[200:203], v[48:51]
	v_mfma_f32_16x16x32_bf16 v[48:51], v[168:171], v[204:207], v[48:51]
	v_mfma_f32_16x16x32_bf16 v[52:55], v[156:159], v[200:203], v[52:55]
	v_mfma_f32_16x16x32_bf16 v[52:55], v[160:163], v[204:207], v[52:55]
	s_setprio 0
	s_setprio 1
	v_mfma_f32_16x16x32_bf16 v[36:39], v[156:159], v[230:233], v[36:39]
	v_mfma_f32_16x16x32_bf16 v[36:39], v[160:163], v[234:237], v[36:39]
	v_mfma_f32_16x16x32_bf16 v[32:35], v[164:167], v[230:233], v[32:35]
	v_mfma_f32_16x16x32_bf16 v[32:35], v[168:171], v[234:237], v[32:35]
	v_mfma_f32_16x16x32_bf16 v[24:27], v[184:187], v[230:233], v[24:27]
	v_mfma_f32_16x16x32_bf16 v[24:27], v[188:191], v[234:237], v[24:27]
	v_mfma_f32_16x16x32_bf16 v[28:31], v[172:175], v[230:233], v[28:31]
	v_mfma_f32_16x16x32_bf16 v[28:31], v[176:179], v[234:237], v[28:31]
	v_mfma_f32_16x16x32_bf16 v[12:15], v[172:175], v[238:241], v[12:15]
	v_mfma_f32_16x16x32_bf16 v[12:15], v[176:179], v[242:245], v[12:15]
	v_mfma_f32_16x16x32_bf16 v[8:11], v[184:187], v[238:241], v[8:11]
	v_mfma_f32_16x16x32_bf16 v[8:11], v[188:191], v[242:245], v[8:11]
	v_mfma_f32_16x16x32_bf16 v[16:19], v[164:167], v[238:241], v[16:19]
	v_mfma_f32_16x16x32_bf16 v[16:19], v[168:171], v[242:245], v[16:19]
	v_mfma_f32_16x16x32_bf16 v[20:23], v[156:159], v[238:241], v[20:23]
	v_mfma_f32_16x16x32_bf16 v[20:23], v[160:163], v[242:245], v[20:23]
	s_setprio 0
	s_barrier
	s_add_i32 s40, s93, 2
	s_add_u32 s22, s22, 0x100
	s_addc_u32 s23, s23, 0
	s_add_u32 s89, s89, 0x100
	s_addc_u32 s92, s92, 0
	s_cmp_ge_u32 s93, s9
	v_add_u32_e32 v154, 0x100, v154
	s_cbranch_scc0 .LBB0_248

; #define PG8_STAGE(bufoff, gbase, voff) do { _Pragma("unroll") for (int _i = 0; _i < 2; ++_i) \
;         __builtin_amdgcn_global_load_lds((const unsigned*)((const char*)(gbase) + (voff)[_i]), (PG8_LAS unsigned*)(lds + (bufoff) + ldsw + _i * 8192), 16, 0, 0); } while (0)
; #define PG8_LDA(dst, b, h) do { _Pragma("unroll") for (int m = 0; m < 4; ++m) _Pragma("unroll") for (int k = 0; k < 2; ++k) dst[m][k] = *(const PG8_LAS bf16x8*)(lds + PG8_SA(b, h) + aoff + m * 2048 + k * 1024); } while (0)
; #define PG8_WAIT_V(n) asm volatile("s_waitcnt vmcnt(" #n ")" ::: "memory")
; #define PG8_BAR __builtin_amdgcn_s_barrier()
; template <class Epi, class Sched, bool ALIGN_EPI = false, bool SP2 = false>
; __device__ __forceinline__ void gemm_phase(PG8_LAS unsigned char* lds, const Gemm g, const Sched& S, const Epi& E) {
;     ...
;         for (int t = 0; t < nt; t += 2) {
;             if constexpr (Epi::KHOOK) { if ((t & 7) == 0 && t != 0) E.khook(acc, t >> 3, wr, fr, lds); }
;             const bool last = (t == nt - 2);
;             const char* a1 = cA + (size_t)(t + 1) * kstep;
;             const char* a2 = last ? nA : cA + (size_t)(t + 2) * kstep; const char* b2 = last ? nB : cB + (size_t)(t + 2) * kstep;
;             const char* a3 = a2 + kstep; const char* b3 = b2 + kstep;
;             if (last && has_next) S.a_ready(nxt);
;             if constexpr (SP2) {
;             PG8_LDB(B0, 0, 0); PG8_LDB(B1, 0, 1); PG8_SCHED; PG8_LDA(At, 0, 0); PG8_STAGE(PG8_SA(1, 1), a1 + hstep, voffA);
;             PG8_WAIT_V(8); PG8_WAIT_L(0); PG8_BAR; PG8_MMA(0, 0, At, B0); PG8_MMA(0, 1, At, B1); PG8_BAR; PG8_SCHED;
;             PG8_LDA(At, 0, 1); PG8_STAGE(PG8_SB(0, 0), b2, voffB); PG8_STAGE(PG8_SB(0, 1), b2 + hstep, voffB); PG8_STAGE(PG8_SA(0, 0), a2, voffA);
;             PG8_WAIT_V(8); PG8_WAIT_L(0); PG8_BAR; PG8_MMA(1, 0, At, B0); PG8_MMA(1, 1, At, B1); PG8_BAR; PG8_SCHED;
;             PG8_LDB(B0, 1, 0); PG8_LDB(B1, 1, 1); PG8_SCHED; PG8_LDA(At, 1, 0); PG8_STAGE(PG8_SA(0, 1), a2 + hstep, voffA);
;             PG8_WAIT_V(8); PG8_WAIT_L(0); PG8_BAR; PG8_MMA(0, 0, At, B0); PG8_MMA(0, 1, At, B1); PG8_BAR; PG8_SCHED;
;             PG8_LDA(At, 1, 1); PG8_STAGE(PG8_SB(1, 0), b3, voffB); PG8_STAGE(PG8_SB(1, 1), b3 + hstep, voffB); PG8_STAGE(PG8_SA(1, 0), a3, voffA);
;             PG8_WAIT_V(8); PG8_WAIT_L(0); PG8_BAR; PG8_MMA(1, 0, At, B0); PG8_MMA(1, 1, At, B1); PG8_BAR; PG8_SCHED;
.LBB0_294:
	s_add_i32 s81, s40, 2
	s_add_u32 s82, s38, 0x80
	s_addc_u32 s41, s39, 0
	s_cmp_eq_u32 s33, s40
	s_cselect_b32 s41, s7, s41
	s_cselect_b32 s40, s6, s82
	v_add_u32_e32 v0, s19, v151
	s_cselect_b32 s83, s23, s80
	s_cselect_b32 s82, s22, s79
	s_add_i32 s84, 0, 0x14000
	ds_read_b128 v[154:157], v0
	ds_read_b128 v[158:161], v0 offset:1024
	ds_read_b128 v[162:165], v0 offset:2048
	ds_read_b128 v[166:169], v0 offset:3072
	v_add_u32_e32 v0, s84, v151
	ds_read_b128 v[170:173], v0
	ds_read_b128 v[174:177], v0 offset:1024
	ds_read_b128 v[178:181], v0 offset:2048
	ds_read_b128 v[184:187], v0 offset:3072
	v_lshl_add_u64 v[2:3], s[38:39], 0, v[144:145]
	s_add_i32 m0, s46, 0xc000
	ds_read_b128 v[188:191], v152
	ds_read_b128 v[192:195], v152 offset:1024
	ds_read_b128 v[196:199], v152 offset:2048
	ds_read_b128 v[200:203], v152 offset:3072
	ds_read_b128 v[204:207], v152 offset:4096
	ds_read_b128 v[230:233], v152 offset:5120
	ds_read_b128 v[234:237], v152 offset:6144
	ds_read_b128 v[238:241], v152 offset:7168
	global_load_lds_dwordx4 v[2:3], off
	v_lshl_add_u64 v[2:3], s[38:39], 0, v[146:147]
	s_add_i32 m0, s46, 0xe000
	s_nop 0
	global_load_lds_dwordx4 v[2:3], off
	s_waitcnt vmcnt(8)
	s_waitcnt lgkmcnt(0)
	s_barrier
	s_setprio 1
	s_waitcnt lgkmcnt(0)
	v_mfma_f32_16x16x32_bf16 v[8:11], v[154:157], v[188:191], v[8:11]
	v_mfma_f32_16x16x32_bf16 v[8:11], v[158:161], v[192:195], v[8:11]
	v_mfma_f32_16x16x32_bf16 v[12:15], v[162:165], v[188:191], v[12:15]
	v_mfma_f32_16x16x32_bf16 v[12:15], v[166:169], v[192:195], v[12:15]
	v_mfma_f32_16x16x32_bf16 v[28:31], v[178:181], v[188:191], v[28:31]
	v_mfma_f32_16x16x32_bf16 v[28:31], v[184:187], v[192:195], v[28:31]
	v_mfma_f32_16x16x32_bf16 v[24:27], v[170:173], v[188:191], v[24:27]
	v_mfma_f32_16x16x32_bf16 v[24:27], v[174:177], v[192:195], v[24:27]
	v_mfma_f32_16x16x32_bf16 v[72:75], v[170:173], v[196:199], v[72:75]
	v_mfma_f32_16x16x32_bf16 v[72:75], v[174:177], v[200:203], v[72:75]
	v_mfma_f32_16x16x32_bf16 v[76:79], v[178:181], v[196:199], v[76:79]
	v_mfma_f32_16x16x32_bf16 v[76:79], v[184:187], v[200:203], v[76:79]
	v_mfma_f32_16x16x32_bf16 v[52:55], v[162:165], v[196:199], v[52:55]
	v_mfma_f32_16x16x32_bf16 v[52:55], v[166:169], v[200:203], v[52:55]
	v_mfma_f32_16x16x32_bf16 v[48:51], v[154:157], v[196:199], v[48:51]
	v_mfma_f32_16x16x32_bf16 v[48:51], v[158:161], v[200:203], v[48:51]
	s_setprio 0
	s_setprio 1
	v_mfma_f32_16x16x32_bf16 v[96:99], v[154:157], v[204:207], v[96:99]
	v_mfma_f32_16x16x32_bf16 v[96:99], v[158:161], v[230:233], v[96:99]
	v_mfma_f32_16x16x32_bf16 v[100:103], v[162:165], v[204:207], v[100:103]
	v_mfma_f32_16x16x32_bf16 v[100:103], v[166:169], v[230:233], v[100:103]
	v_mfma_f32_16x16x32_bf16 v[116:119], v[178:181], v[204:207], v[116:119]
	v_mfma_f32_16x16x32_bf16 v[116:119], v[184:187], v[230:233], v[116:119]
	v_mfma_f32_16x16x32_bf16 v[112:115], v[170:173], v[204:207], v[112:115]
	v_mfma_f32_16x16x32_bf16 v[112:115], v[174:177], v[230:233], v[112:115]
	v_mfma_f32_16x16x32_bf16 v[128:131], v[170:173], v[234:237], v[128:131]
	v_mfma_f32_16x16x32_bf16 v[128:131], v[174:177], v[238:241], v[128:131]
	v_mfma_f32_16x16x32_bf16 v[132:135], v[178:181], v[234:237], v[132:135]
	v_mfma_f32_16x16x32_bf16 v[132:135], v[184:187], v[238:241], v[132:135]
	v_mfma_f32_16x16x32_bf16 v[124:127], v[162:165], v[234:237], v[124:127]
	v_mfma_f32_16x16x32_bf16 v[124:127], v[166:169], v[238:241], v[124:127]
	v_mfma_f32_16x16x32_bf16 v[120:123], v[154:157], v[234:237], v[120:123]
	v_mfma_f32_16x16x32_bf16 v[120:123], v[158:161], v[238:241], v[120:123]
	s_setprio 0
	s_barrier
	s_add_i32 s85, s19, s37
	v_lshl_add_u64 v[2:3], s[82:83], 0, v[140:141]
	s_mov_b32 m0, s85
	ds_read_b128 v[188:191], v152 offset:16384
	ds_read_b128 v[192:195], v152 offset:17408
	ds_read_b128 v[196:199], v152 offset:18432
	ds_read_b128 v[200:203], v152 offset:19456
	ds_read_b128 v[204:207], v152 offset:20480
	ds_read_b128 v[230:233], v152 offset:21504
	ds_read_b128 v[234:237], v152 offset:22528
	ds_read_b128 v[238:241], v152 offset:23552
	global_load_lds_dwordx4 v[2:3], off
	s_add_i32 m0, s85, 0x2000
	v_lshl_add_u64 v[208:209], s[82:83], 0, v[136:137]
	s_add_u32 s82, s82, s48
	s_addc_u32 s83, s83, s49
	s_add_i32 s84, s84, s37
	global_load_lds_dwordx4 v[208:209], off
	v_lshl_add_u64 v[216:217], s[82:83], 0, v[140:141]
	s_mov_b32 m0, s84
	v_lshl_add_u64 v[224:225], s[82:83], 0, v[136:137]
	global_load_lds_dwordx4 v[216:217], off
	s_add_i32 m0, s84, 0x2000
	v_lshl_add_u64 v[226:227], s[40:41], 0, v[142:143]
	global_load_lds_dwordx4 v[224:225], off
	s_mov_b32 m0, s46
	v_lshl_add_u64 v[228:229], s[40:41], 0, v[138:139]
	global_load_lds_dwordx4 v[226:227], off
	s_mov_b32 m0, s47
	s_nop 0
	global_load_lds_dwordx4 v[228:229], off
	s_waitcnt vmcnt(8)
	s_waitcnt lgkmcnt(0)
	s_barrier
; #define PG8_STAGE(bufoff, gbase, voff) do { _Pragma("unroll") for (int _i = 0; _i < 2; ++_i) \
;         __builtin_amdgcn_global_load_lds((const unsigned*)((const char*)(gbase) + (voff)[_i]), (PG8_LAS unsigned*)(lds + (bufoff) + ldsw + _i * 8192), 16, 0, 0); } while (0)
; #define PG8_LDA(dst, b, h) do { _Pragma("unroll") for (int m = 0; m < 4; ++m) _Pragma("unroll") for (int k = 0; k < 2; ++k) dst[m][k] = *(const PG8_LAS bf16x8*)(lds + PG8_SA(b, h) + aoff + m * 2048 + k * 1024); } while (0)
; #define PG8_LDB(dst, b, h) do { _Pragma("unroll") for (int n = 0; n < 2; ++n) _Pragma("unroll") for (int k = 0; k < 2; ++k) dst[n][k] = *(const PG8_LAS bf16x8*)(lds + PG8_SB(b, h) + boff + n * 2048 + k * 1024); } while (0)
; #define PG8_MMA(ai, bj, At, Bt) do { __builtin_amdgcn_s_setprio(1); _Pragma("unroll") for (int m = 0; m < 4; ++m) _Pragma("unroll") for (int n = 0; n < 2; ++n) _Pragma("unroll") for (int k = 0; k < 2; ++k) \
;         acc[ai][bj][m][n] = __builtin_amdgcn_mfma_f32_16x16x32_bf16(Bt[n][k], At[m][k], acc[ai][bj][m][n], 0, 0, 0); __builtin_amdgcn_s_setprio(0); } while (0)
; #define PG8_BAR __builtin_amdgcn_s_barrier()
; template <class Epi, class Sched, bool ALIGN_EPI = false, bool SP2 = false>
; __device__ __forceinline__ void gemm_phase(PG8_LAS unsigned char* lds, const Gemm g, const Sched& S, const Epi& E) {
;     ...
;             if constexpr (SP2) {
;             PG8_LDB(B0, 0, 0); PG8_LDB(B1, 0, 1); PG8_SCHED; PG8_LDA(At, 0, 0); PG8_STAGE(PG8_SA(1, 1), a1 + hstep, voffA);
;             PG8_WAIT_V(8); PG8_WAIT_L(0); PG8_BAR; PG8_MMA(0, 0, At, B0); PG8_MMA(0, 1, At, B1); PG8_BAR; PG8_SCHED;
;             PG8_LDA(At, 0, 1); PG8_STAGE(PG8_SB(0, 0), b2, voffB); PG8_STAGE(PG8_SB(0, 1), b2 + hstep, voffB); PG8_STAGE(PG8_SA(0, 0), a2, voffA);
;             PG8_WAIT_V(8); PG8_WAIT_L(0); PG8_BAR; PG8_MMA(1, 0, At, B0); PG8_MMA(1, 1, At, B1); PG8_BAR; PG8_SCHED;
;             PG8_LDB(B0, 1, 0); PG8_LDB(B1, 1, 1); PG8_SCHED; PG8_LDA(At, 1, 0); PG8_STAGE(PG8_SA(0, 1), a2 + hstep, voffA);
;             PG8_WAIT_V(8); PG8_WAIT_L(0); PG8_BAR; PG8_MMA(0, 0, At, B0); PG8_MMA(0, 1, At, B1); PG8_BAR; PG8_SCHED;
;             PG8_LDA(At, 1, 1); PG8_STAGE(PG8_SB(1, 0), b3, voffB); PG8_STAGE(PG8_SB(1, 1), b3 + hstep, voffB); PG8_STAGE(PG8_SA(1, 0), a3, voffA);
;             PG8_WAIT_V(8); PG8_WAIT_L(0); PG8_BAR; PG8_MMA(1, 0, At, B0); PG8_MMA(1, 1, At, B1); PG8_BAR; PG8_SCHED;
	s_setprio 1
	s_waitcnt lgkmcnt(0)
	v_mfma_f32_16x16x32_bf16 v[16:19], v[154:157], v[188:191], v[16:19]
	v_mfma_f32_16x16x32_bf16 v[16:19], v[158:161], v[192:195], v[16:19]
	v_mfma_f32_16x16x32_bf16 v[20:23], v[162:165], v[188:191], v[20:23]
	v_mfma_f32_16x16x32_bf16 v[20:23], v[166:169], v[192:195], v[20:23]
	v_mfma_f32_16x16x32_bf16 v[44:47], v[178:181], v[188:191], v[44:47]
	v_mfma_f32_16x16x32_bf16 v[44:47], v[184:187], v[192:195], v[44:47]
	v_mfma_f32_16x16x32_bf16 v[40:43], v[170:173], v[188:191], v[40:43]
	v_mfma_f32_16x16x32_bf16 v[40:43], v[174:177], v[192:195], v[40:43]
	v_mfma_f32_16x16x32_bf16 v[88:91], v[170:173], v[196:199], v[88:91]
	v_mfma_f32_16x16x32_bf16 v[88:91], v[174:177], v[200:203], v[88:91]
	v_mfma_f32_16x16x32_bf16 v[92:95], v[178:181], v[196:199], v[92:95]
	v_mfma_f32_16x16x32_bf16 v[92:95], v[184:187], v[200:203], v[92:95]
	v_mfma_f32_16x16x32_bf16 v[60:63], v[162:165], v[196:199], v[60:63]
	v_mfma_f32_16x16x32_bf16 v[60:63], v[166:169], v[200:203], v[60:63]
	v_mfma_f32_16x16x32_bf16 v[56:59], v[154:157], v[196:199], v[56:59]
	v_mfma_f32_16x16x32_bf16 v[56:59], v[158:161], v[200:203], v[56:59]
	s_setprio 0
	s_setprio 1
	v_mfma_f32_16x16x32_bf16 v[104:107], v[154:157], v[204:207], v[104:107]
	v_mfma_f32_16x16x32_bf16 v[104:107], v[158:161], v[230:233], v[104:107]
	v_mfma_f32_16x16x32_bf16 v[108:111], v[162:165], v[204:207], v[108:111]
	v_mfma_f32_16x16x32_bf16 v[108:111], v[166:169], v[230:233], v[108:111]
	v_mfma_f32_16x16x32_bf16 v[80:83], v[178:181], v[204:207], v[80:83]
	v_mfma_f32_16x16x32_bf16 v[80:83], v[184:187], v[230:233], v[80:83]
	v_mfma_f32_16x16x32_bf16 v[84:87], v[170:173], v[204:207], v[84:87]
	v_mfma_f32_16x16x32_bf16 v[84:87], v[174:177], v[230:233], v[84:87]
	v_mfma_f32_16x16x32_bf16 v[36:39], v[170:173], v[234:237], v[36:39]
	v_mfma_f32_16x16x32_bf16 v[36:39], v[174:177], v[238:241], v[36:39]
	v_mfma_f32_16x16x32_bf16 v[32:35], v[178:181], v[234:237], v[32:35]
	v_mfma_f32_16x16x32_bf16 v[32:35], v[184:187], v[238:241], v[32:35]
	v_mfma_f32_16x16x32_bf16 v[64:67], v[162:165], v[234:237], v[64:67]
	v_mfma_f32_16x16x32_bf16 v[64:67], v[166:169], v[238:241], v[64:67]
	v_mfma_f32_16x16x32_bf16 v[68:71], v[154:157], v[234:237], v[68:71]
	v_mfma_f32_16x16x32_bf16 v[68:71], v[158:161], v[238:241], v[68:71]
	s_setprio 0
	s_barrier
	v_add_u32_e32 v0, s91, v151
	s_add_i32 s82, 0, 0x1c000
	ds_read_b128 v[154:157], v0
	ds_read_b128 v[158:161], v0 offset:1024
	ds_read_b128 v[162:165], v0 offset:2048
	ds_read_b128 v[166:169], v0 offset:3072
	v_add_u32_e32 v0, s82, v151
	ds_read_b128 v[170:173], v0
	ds_read_b128 v[174:177], v0 offset:1024
	ds_read_b128 v[178:181], v0 offset:2048
	ds_read_b128 v[184:187], v0 offset:3072
	s_add_u32 s40, s40, s48
	s_addc_u32 s41, s41, s49
	s_mov_b32 m0, s52
	v_lshl_add_u64 v[242:243], s[40:41], 0, v[142:143]
	ds_read_b128 v[188:191], v152 offset:32768
	ds_read_b128 v[192:195], v152 offset:33792
	ds_read_b128 v[196:199], v152 offset:34816
	ds_read_b128 v[200:203], v152 offset:35840
	ds_read_b128 v[204:207], v152 offset:36864
	ds_read_b128 v[230:233], v152 offset:37888
	ds_read_b128 v[234:237], v152 offset:38912
	ds_read_b128 v[238:241], v152 offset:39936
	global_load_lds_dwordx4 v[242:243], off
	v_lshl_add_u64 v[242:243], s[40:41], 0, v[138:139]
	s_mov_b32 m0, s53
	s_nop 0
	global_load_lds_dwordx4 v[242:243], off
	s_waitcnt vmcnt(8)
	s_waitcnt lgkmcnt(0)
	s_barrier
	s_setprio 1
	s_waitcnt lgkmcnt(0)
	v_mfma_f32_16x16x32_bf16 v[8:11], v[154:157], v[188:191], v[8:11]
	v_mfma_f32_16x16x32_bf16 v[8:11], v[158:161], v[192:195], v[8:11]
	v_mfma_f32_16x16x32_bf16 v[12:15], v[162:165], v[188:191], v[12:15]
	v_mfma_f32_16x16x32_bf16 v[12:15], v[166:169], v[192:195], v[12:15]
	v_mfma_f32_16x16x32_bf16 v[28:31], v[178:181], v[188:191], v[28:31]
	v_mfma_f32_16x16x32_bf16 v[28:31], v[184:187], v[192:195], v[28:31]
	v_mfma_f32_16x16x32_bf16 v[24:27], v[170:173], v[188:191], v[24:27]
	v_mfma_f32_16x16x32_bf16 v[24:27], v[174:177], v[192:195], v[24:27]
	v_mfma_f32_16x16x32_bf16 v[72:75], v[170:173], v[196:199], v[72:75]
	v_mfma_f32_16x16x32_bf16 v[72:75], v[174:177], v[200:203], v[72:75]
	v_mfma_f32_16x16x32_bf16 v[76:79], v[178:181], v[196:199], v[76:79]
	v_mfma_f32_16x16x32_bf16 v[76:79], v[184:187], v[200:203], v[76:79]
	v_mfma_f32_16x16x32_bf16 v[52:55], v[162:165], v[196:199], v[52:55]
	v_mfma_f32_16x16x32_bf16 v[52:55], v[166:169], v[200:203], v[52:55]
	v_mfma_f32_16x16x32_bf16 v[48:51], v[154:157], v[196:199], v[48:51]
	v_mfma_f32_16x16x32_bf16 v[48:51], v[158:161], v[200:203], v[48:51]
	s_setprio 0
	s_setprio 1
	v_mfma_f32_16x16x32_bf16 v[96:99], v[154:157], v[204:207], v[96:99]
	v_mfma_f32_16x16x32_bf16 v[96:99], v[158:161], v[230:233], v[96:99]
	v_mfma_f32_16x16x32_bf16 v[100:103], v[162:165], v[204:207], v[100:103]
	v_mfma_f32_16x16x32_bf16 v[100:103], v[166:169], v[230:233], v[100:103]
	v_mfma_f32_16x16x32_bf16 v[116:119], v[178:181], v[204:207], v[116:119]
	v_mfma_f32_16x16x32_bf16 v[116:119], v[184:187], v[230:233], v[116:119]
	v_mfma_f32_16x16x32_bf16 v[112:115], v[170:173], v[204:207], v[112:115]
	v_mfma_f32_16x16x32_bf16 v[112:115], v[174:177], v[230:233], v[112:115]
	v_mfma_f32_16x16x32_bf16 v[128:131], v[170:173], v[234:237], v[128:131]
	v_mfma_f32_16x16x32_bf16 v[128:131], v[174:177], v[238:241], v[128:131]
	v_mfma_f32_16x16x32_bf16 v[132:135], v[178:181], v[234:237], v[132:135]
	v_mfma_f32_16x16x32_bf16 v[132:135], v[184:187], v[238:241], v[132:135]
	v_mfma_f32_16x16x32_bf16 v[124:127], v[162:165], v[234:237], v[124:127]
	v_mfma_f32_16x16x32_bf16 v[124:127], v[166:169], v[238:241], v[124:127]
	v_mfma_f32_16x16x32_bf16 v[120:123], v[154:157], v[234:237], v[120:123]
	v_mfma_f32_16x16x32_bf16 v[120:123], v[158:161], v[238:241], v[120:123]
	s_setprio 0
	s_barrier
; #define PG8_STAGE(bufoff, gbase, voff) do { _Pragma("unroll") for (int _i = 0; _i < 2; ++_i) \
;         __builtin_amdgcn_global_load_lds((const unsigned*)((const char*)(gbase) + (voff)[_i]), (PG8_LAS unsigned*)(lds + (bufoff) + ldsw + _i * 8192), 16, 0, 0); } while (0)
; #define PG8_LDA(dst, b, h) do { _Pragma("unroll") for (int m = 0; m < 4; ++m) _Pragma("unroll") for (int k = 0; k < 2; ++k) dst[m][k] = *(const PG8_LAS bf16x8*)(lds + PG8_SA(b, h) + aoff + m * 2048 + k * 1024); } while (0)
; #define PG8_MMA(ai, bj, At, Bt) do { __builtin_amdgcn_s_setprio(1); _Pragma("unroll") for (int m = 0; m < 4; ++m) _Pragma("unroll") for (int n = 0; n < 2; ++n) _Pragma("unroll") for (int k = 0; k < 2; ++k) \
;         acc[ai][bj][m][n] = __builtin_amdgcn_mfma_f32_16x16x32_bf16(Bt[n][k], At[m][k], acc[ai][bj][m][n], 0, 0, 0); __builtin_amdgcn_s_setprio(0); } while (0)
; #define PG8_WAIT_V(n) asm volatile("s_waitcnt vmcnt(" #n ")" ::: "memory")
; #define PG8_WAIT_L(n) asm volatile("s_waitcnt lgkmcnt(" #n ")" ::: "memory")
; #define PG8_BAR __builtin_amdgcn_s_barrier()
; #define PG8_SCHED __builtin_amdgcn_sched_barrier(0)
; template <class Epi, class Sched, bool ALIGN_EPI = false, bool SP2 = false>
; __device__ __forceinline__ void gemm_phase(PG8_LAS unsigned char* lds, const Gemm g, const Sched& S, const Epi& E) {
;     ...
;             PG8_LDA(At, 1, 1); PG8_STAGE(PG8_SB(1, 0), b3, voffB); PG8_STAGE(PG8_SB(1, 1), b3 + hstep, voffB); PG8_STAGE(PG8_SA(1, 0), a3, voffA);
;             PG8_WAIT_V(8); PG8_WAIT_L(0); PG8_BAR; PG8_MMA(1, 0, At, B0); PG8_MMA(1, 1, At, B1); PG8_BAR; PG8_SCHED;
	s_add_i32 s40, s91, s37
	v_lshl_add_u64 v[2:3], v[2:3], 0, s[24:25]
	s_mov_b32 m0, s40
	ds_read_b128 v[188:191], v152 offset:49152
	ds_read_b128 v[192:195], v152 offset:50176
	ds_read_b128 v[196:199], v152 offset:51200
	ds_read_b128 v[200:203], v152 offset:52224
	ds_read_b128 v[204:207], v152 offset:53248
	ds_read_b128 v[230:233], v152 offset:54272
	ds_read_b128 v[234:237], v152 offset:55296
	ds_read_b128 v[238:241], v152 offset:56320
	global_load_lds_dwordx4 v[2:3], off
	v_lshl_add_u64 v[2:3], v[208:209], 0, s[24:25]
	s_add_i32 m0, s40, 0x2000
	s_add_i32 s40, s82, s37
	global_load_lds_dwordx4 v[2:3], off
	v_lshl_add_u64 v[2:3], v[216:217], 0, s[24:25]
	s_mov_b32 m0, s40
	s_nop 0
	global_load_lds_dwordx4 v[2:3], off
	v_lshl_add_u64 v[2:3], v[224:225], 0, s[24:25]
	s_add_i32 m0, s40, 0x2000
	s_nop 0
	global_load_lds_dwordx4 v[2:3], off
	v_lshl_add_u64 v[2:3], v[226:227], 0, s[24:25]
	s_mov_b32 m0, s73
	s_nop 0
	global_load_lds_dwordx4 v[2:3], off
	v_lshl_add_u64 v[2:3], v[228:229], 0, s[24:25]
	s_mov_b32 m0, s74
	s_nop 0
	global_load_lds_dwordx4 v[2:3], off
	s_waitcnt vmcnt(8)
	s_waitcnt lgkmcnt(0)
	s_barrier
	s_setprio 1
	s_waitcnt lgkmcnt(0)
	v_mfma_f32_16x16x32_bf16 v[16:19], v[154:157], v[188:191], v[16:19]
	v_mfma_f32_16x16x32_bf16 v[16:19], v[158:161], v[192:195], v[16:19]
	v_mfma_f32_16x16x32_bf16 v[20:23], v[162:165], v[188:191], v[20:23]
	v_mfma_f32_16x16x32_bf16 v[20:23], v[166:169], v[192:195], v[20:23]
	v_mfma_f32_16x16x32_bf16 v[44:47], v[178:181], v[188:191], v[44:47]
	v_mfma_f32_16x16x32_bf16 v[44:47], v[184:187], v[192:195], v[44:47]
	v_mfma_f32_16x16x32_bf16 v[40:43], v[170:173], v[188:191], v[40:43]
	v_mfma_f32_16x16x32_bf16 v[40:43], v[174:177], v[192:195], v[40:43]
	v_mfma_f32_16x16x32_bf16 v[88:91], v[170:173], v[196:199], v[88:91]
	v_mfma_f32_16x16x32_bf16 v[88:91], v[174:177], v[200:203], v[88:91]
	v_mfma_f32_16x16x32_bf16 v[92:95], v[178:181], v[196:199], v[92:95]
	v_mfma_f32_16x16x32_bf16 v[92:95], v[184:187], v[200:203], v[92:95]
	v_mfma_f32_16x16x32_bf16 v[60:63], v[162:165], v[196:199], v[60:63]
	v_mfma_f32_16x16x32_bf16 v[60:63], v[166:169], v[200:203], v[60:63]
	v_mfma_f32_16x16x32_bf16 v[56:59], v[154:157], v[196:199], v[56:59]
	v_mfma_f32_16x16x32_bf16 v[56:59], v[158:161], v[200:203], v[56:59]
	s_setprio 0
	s_setprio 1
	v_mfma_f32_16x16x32_bf16 v[104:107], v[154:157], v[204:207], v[104:107]
	v_mfma_f32_16x16x32_bf16 v[104:107], v[158:161], v[230:233], v[104:107]
	v_mfma_f32_16x16x32_bf16 v[108:111], v[162:165], v[204:207], v[108:111]
	v_mfma_f32_16x16x32_bf16 v[108:111], v[166:169], v[230:233], v[108:111]
	v_mfma_f32_16x16x32_bf16 v[80:83], v[178:181], v[204:207], v[80:83]
	v_mfma_f32_16x16x32_bf16 v[80:83], v[184:187], v[230:233], v[80:83]
	v_mfma_f32_16x16x32_bf16 v[84:87], v[170:173], v[204:207], v[84:87]
	v_mfma_f32_16x16x32_bf16 v[84:87], v[174:177], v[230:233], v[84:87]
	v_mfma_f32_16x16x32_bf16 v[36:39], v[170:173], v[234:237], v[36:39]
	v_mfma_f32_16x16x32_bf16 v[36:39], v[174:177], v[238:241], v[36:39]
	v_mfma_f32_16x16x32_bf16 v[32:35], v[178:181], v[234:237], v[32:35]
	v_mfma_f32_16x16x32_bf16 v[32:35], v[184:187], v[238:241], v[32:35]
	v_mfma_f32_16x16x32_bf16 v[64:67], v[162:165], v[234:237], v[64:67]
	v_mfma_f32_16x16x32_bf16 v[64:67], v[166:169], v[238:241], v[64:67]
	v_mfma_f32_16x16x32_bf16 v[68:71], v[154:157], v[234:237], v[68:71]
	v_mfma_f32_16x16x32_bf16 v[68:71], v[158:161], v[238:241], v[68:71]
	s_setprio 0
	s_barrier
	s_add_u32 s38, s38, 0x100
	s_addc_u32 s39, s39, 0
	s_add_u32 s79, s79, 0x100
	s_addc_u32 s80, s80, 0
	s_cmp_ge_u32 s81, s9
	s_mov_b32 s40, s81
	s_cbranch_scc0 .LBB0_294

; #define PG8_STAGE(bufoff, gbase, voff) do { _Pragma("unroll") for (int _i = 0; _i < 2; ++_i) \
;         __builtin_amdgcn_global_load_lds((const unsigned*)((const char*)(gbase) + (voff)[_i]), (PG8_LAS unsigned*)(lds + (bufoff) + ldsw + _i * 8192), 16, 0, 0); } while (0)
; #define PG8_LDA(dst, b, h) do { _Pragma("unroll") for (int m = 0; m < 4; ++m) _Pragma("unroll") for (int k = 0; k < 2; ++k) dst[m][k] = *(const PG8_LAS bf16x8*)(lds + PG8_SA(b, h) + aoff + m * 2048 + k * 1024); } while (0)
; #define PG8_LDB(dst, b, h) do { _Pragma("unroll") for (int n = 0; n < 2; ++n) _Pragma("unroll") for (int k = 0; k < 2; ++k) dst[n][k] = *(const PG8_LAS bf16x8*)(lds + PG8_SB(b, h) + boff + n * 2048 + k * 1024); } while (0)
; #define PG8_MMA(ai, bj, At, Bt) do { __builtin_amdgcn_s_setprio(1); _Pragma("unroll") for (int m = 0; m < 4; ++m) _Pragma("unroll") for (int n = 0; n < 2; ++n) _Pragma("unroll") for (int k = 0; k < 2; ++k) \
;         acc[ai][bj][m][n] = __builtin_amdgcn_mfma_f32_16x16x32_bf16(Bt[n][k], At[m][k], acc[ai][bj][m][n], 0, 0, 0); __builtin_amdgcn_s_setprio(0); } while (0)
; #define PG8_WAIT_V(n) asm volatile("s_waitcnt vmcnt(" #n ")" ::: "memory")
; #define PG8_WAIT_L(n) asm volatile("s_waitcnt lgkmcnt(" #n ")" ::: "memory")
; template <class Epi, class Sched, bool ALIGN_EPI = false, bool SP2 = false>
; __device__ __forceinline__ void gemm_phase(PG8_LAS unsigned char* lds, const Gemm g, const Sched& S, const Epi& E) {
;     ...
;             const bool last = (t == nt - 2);
;             const char* a1 = cA + (size_t)(t + 1) * kstep;
;             const char* a2 = last ? nA : cA + (size_t)(t + 2) * kstep; const char* b2 = last ? nB : cB + (size_t)(t + 2) * kstep;
;             const char* a3 = a2 + kstep; const char* b3 = b2 + kstep;
;             if (last && has_next) S.a_ready(nxt);
;             if constexpr (SP2) {
;             PG8_LDB(B0, 0, 0); PG8_LDB(B1, 0, 1); PG8_SCHED; PG8_LDA(At, 0, 0); PG8_STAGE(PG8_SA(1, 1), a1 + hstep, voffA);
;             PG8_WAIT_V(8); PG8_WAIT_L(0); PG8_BAR; PG8_MMA(0, 0, At, B0); PG8_MMA(0, 1, At, B1); PG8_BAR; PG8_SCHED;
;             PG8_LDA(At, 0, 1); PG8_STAGE(PG8_SB(0, 0), b2, voffB); PG8_STAGE(PG8_SB(0, 1), b2 + hstep, voffB); PG8_STAGE(PG8_SA(0, 0), a2, voffA);
;             PG8_WAIT_V(8); PG8_WAIT_L(0); PG8_BAR; PG8_MMA(1, 0, At, B0); PG8_MMA(1, 1, At, B1); PG8_BAR; PG8_SCHED;
.LBB0_365:
	s_add_i32 s88, s86, 2
	s_add_u32 s89, s0, 0x80
	s_addc_u32 s87, s1, 0
	s_cmp_eq_u32 s33, s86
	s_cselect_b32 s87, s3, s87
	s_cselect_b32 s86, s2, s89
	v_add_u32_e32 v0, s19, v230
	s_cselect_b32 vcc_hi, s85, s73
	s_cselect_b32 vcc_lo, s84, s72
	s_add_i32 s89, 0, 0x14000
	ds_read_b128 v[120:123], v0
	ds_read_b128 v[124:127], v0 offset:1024
	ds_read_b128 v[128:131], v0 offset:2048
	ds_read_b128 v[132:135], v0 offset:3072
	v_add_u32_e32 v0, s89, v230
	ds_read_b128 v[136:139], v0
	ds_read_b128 v[140:143], v0 offset:1024
	ds_read_b128 v[162:165], v0 offset:2048
	ds_read_b128 v[166:169], v0 offset:3072
	v_lshl_add_u64 v[144:145], s[0:1], 0, v[184:185]
	s_add_i32 m0, s93, 0xc000
	ds_read_b128 v[170:173], v238
	ds_read_b128 v[188:191], v238 offset:1024
	ds_read_b128 v[192:195], v238 offset:2048
	ds_read_b128 v[196:199], v238 offset:3072
	ds_read_b128 v[200:203], v238 offset:4096
	ds_read_b128 v[204:207], v238 offset:5120
	ds_read_b128 v[242:245], v238 offset:6144
	ds_read_b128 v[246:249], v238 offset:7168
	global_load_lds_dwordx4 v[144:145], off
	v_lshl_add_u64 v[144:145], s[0:1], 0, v[186:187]
	s_add_i32 m0, s93, 0xe000
	s_nop 0
	global_load_lds_dwordx4 v[144:145], off
	s_waitcnt vmcnt(8)
	s_waitcnt lgkmcnt(0)
	s_barrier
	s_setprio 1
	s_waitcnt lgkmcnt(0)
	v_mfma_f32_16x16x32_bf16 v[158:161], v[120:123], v[170:173], v[158:161]
	v_mfma_f32_16x16x32_bf16 v[158:161], v[124:127], v[188:191], v[158:161]
	v_mfma_f32_16x16x32_bf16 v[150:153], v[120:123], v[192:195], v[150:153]
	v_mfma_f32_16x16x32_bf16 v[150:153], v[124:127], v[196:199], v[150:153]
	v_mfma_f32_16x16x32_bf16 v[100:103], v[120:123], v[200:203], v[100:103]
	v_mfma_f32_16x16x32_bf16 v[100:103], v[124:127], v[204:207], v[100:103]
	v_mfma_f32_16x16x32_bf16 v[116:119], v[120:123], v[242:245], v[116:119]
	v_mfma_f32_16x16x32_bf16 v[116:119], v[124:127], v[246:249], v[116:119]
	v_mfma_f32_16x16x32_bf16 v[68:71], v[128:131], v[242:245], v[68:71]
	v_mfma_f32_16x16x32_bf16 v[68:71], v[132:135], v[246:249], v[68:71]
	v_mfma_f32_16x16x32_bf16 v[36:39], v[128:131], v[200:203], v[36:39]
	v_mfma_f32_16x16x32_bf16 v[36:39], v[132:135], v[204:207], v[36:39]
	v_mfma_f32_16x16x32_bf16 v[52:55], v[128:131], v[192:195], v[52:55]
	v_mfma_f32_16x16x32_bf16 v[52:55], v[132:135], v[196:199], v[52:55]
	v_mfma_f32_16x16x32_bf16 v[60:63], v[128:131], v[170:173], v[60:63]
	v_mfma_f32_16x16x32_bf16 v[60:63], v[132:135], v[188:191], v[60:63]
	s_setprio 0
	s_setprio 1
	v_mfma_f32_16x16x32_bf16 v[154:157], v[136:139], v[170:173], v[154:157]
	v_mfma_f32_16x16x32_bf16 v[154:157], v[140:143], v[188:191], v[154:157]
	v_mfma_f32_16x16x32_bf16 v[144:147], v[136:139], v[192:195], v[146:149]
	v_mfma_f32_16x16x32_bf16 v[144:147], v[140:143], v[196:199], v[144:147]
	v_mfma_f32_16x16x32_bf16 v[96:99], v[136:139], v[200:203], v[96:99]
	v_mfma_f32_16x16x32_bf16 v[96:99], v[140:143], v[204:207], v[96:99]
	v_mfma_f32_16x16x32_bf16 v[112:115], v[136:139], v[242:245], v[112:115]
	v_mfma_f32_16x16x32_bf16 v[112:115], v[140:143], v[246:249], v[112:115]
	v_mfma_f32_16x16x32_bf16 v[64:67], v[162:165], v[242:245], v[64:67]
	v_mfma_f32_16x16x32_bf16 v[64:67], v[166:169], v[246:249], v[64:67]
	v_mfma_f32_16x16x32_bf16 v[32:35], v[162:165], v[200:203], v[32:35]
	v_mfma_f32_16x16x32_bf16 v[32:35], v[166:169], v[204:207], v[32:35]
	v_mfma_f32_16x16x32_bf16 v[48:51], v[162:165], v[192:195], v[48:51]
	v_mfma_f32_16x16x32_bf16 v[48:51], v[166:169], v[196:199], v[48:51]
	v_mfma_f32_16x16x32_bf16 v[56:59], v[162:165], v[170:173], v[56:59]
	v_mfma_f32_16x16x32_bf16 v[56:59], v[166:169], v[188:191], v[56:59]
	s_setprio 0
	s_barrier
	s_add_i32 s38, s19, s92
	v_lshl_add_u64 v[174:175], vcc, 0, v[176:177]
	s_mov_b32 m0, s38
	ds_read_b128 v[170:173], v238 offset:16384
	ds_read_b128 v[188:191], v238 offset:17408
	ds_read_b128 v[192:195], v238 offset:18432
	ds_read_b128 v[196:199], v238 offset:19456
	ds_read_b128 v[200:203], v238 offset:20480
	ds_read_b128 v[204:207], v238 offset:21504
	ds_read_b128 v[242:245], v238 offset:22528
	ds_read_b128 v[246:249], v238 offset:23552
	global_load_lds_dwordx4 v[174:175], off
	s_add_i32 m0, s38, 0x2000
	v_lshl_add_u64 v[208:209], vcc, 0, v[180:181]
	s_add_u32 vcc_lo, vcc_lo, s48
	s_addc_u32 vcc_hi, vcc_hi, s49
	s_add_i32 s38, s89, s92
	global_load_lds_dwordx4 v[208:209], off
	v_lshl_add_u64 v[216:217], vcc, 0, v[176:177]
	s_mov_b32 m0, s38
	v_lshl_add_u64 v[224:225], vcc, 0, v[180:181]
	global_load_lds_dwordx4 v[216:217], off
	s_add_i32 m0, s38, 0x2000
	v_lshl_add_u64 v[226:227], s[86:87], 0, v[2:3]
	global_load_lds_dwordx4 v[224:225], off
	s_mov_b32 m0, s93
	v_lshl_add_u64 v[228:229], s[86:87], 0, v[178:179]
	global_load_lds_dwordx4 v[226:227], off
	s_mov_b32 m0, s94
	s_nop 0
	global_load_lds_dwordx4 v[228:229], off
	s_waitcnt vmcnt(8)
	s_waitcnt lgkmcnt(0)
	s_barrier
; #define PG8_STAGE(bufoff, gbase, voff) do { _Pragma("unroll") for (int _i = 0; _i < 2; ++_i) \
;         __builtin_amdgcn_global_load_lds((const unsigned*)((const char*)(gbase) + (voff)[_i]), (PG8_LAS unsigned*)(lds + (bufoff) + ldsw + _i * 8192), 16, 0, 0); } while (0)
; #define PG8_LDA(dst, b, h) do { _Pragma("unroll") for (int m = 0; m < 4; ++m) _Pragma("unroll") for (int k = 0; k < 2; ++k) dst[m][k] = *(const PG8_LAS bf16x8*)(lds + PG8_SA(b, h) + aoff + m * 2048 + k * 1024); } while (0)
; #define PG8_LDB(dst, b, h) do { _Pragma("unroll") for (int n = 0; n < 2; ++n) _Pragma("unroll") for (int k = 0; k < 2; ++k) dst[n][k] = *(const PG8_LAS bf16x8*)(lds + PG8_SB(b, h) + boff + n * 2048 + k * 1024); } while (0)
; #define PG8_MMA(ai, bj, At, Bt) do { __builtin_amdgcn_s_setprio(1); _Pragma("unroll") for (int m = 0; m < 4; ++m) _Pragma("unroll") for (int n = 0; n < 2; ++n) _Pragma("unroll") for (int k = 0; k < 2; ++k) \
;         acc[ai][bj][m][n] = __builtin_amdgcn_mfma_f32_16x16x32_bf16(Bt[n][k], At[m][k], acc[ai][bj][m][n], 0, 0, 0); __builtin_amdgcn_s_setprio(0); } while (0)
; #define PG8_WAIT_V(n) asm volatile("s_waitcnt vmcnt(" #n ")" ::: "memory")
; #define PG8_WAIT_L(n) asm volatile("s_waitcnt lgkmcnt(" #n ")" ::: "memory")
; #define PG8_BAR __builtin_amdgcn_s_barrier()
; #define PG8_SCHED __builtin_amdgcn_sched_barrier(0)
; template <class Epi, class Sched, bool ALIGN_EPI = false, bool SP2 = false>
; __device__ __forceinline__ void gemm_phase(PG8_LAS unsigned char* lds, const Gemm g, const Sched& S, const Epi& E) {
;     ...
;             PG8_WAIT_V(8); PG8_WAIT_L(0); PG8_BAR; PG8_MMA(1, 0, At, B0); PG8_MMA(1, 1, At, B1); PG8_BAR; PG8_SCHED;
;             PG8_LDB(B0, 1, 0); PG8_LDB(B1, 1, 1); PG8_SCHED; PG8_LDA(At, 1, 0); PG8_STAGE(PG8_SA(0, 1), a2 + hstep, voffA);
;             PG8_WAIT_V(8); PG8_WAIT_L(0); PG8_BAR; PG8_MMA(0, 0, At, B0); PG8_MMA(0, 1, At, B1); PG8_BAR; PG8_SCHED;
	s_setprio 1
	s_waitcnt lgkmcnt(0)
	v_mfma_f32_16x16x32_bf16 v[92:95], v[120:123], v[170:173], v[92:95]
	v_mfma_f32_16x16x32_bf16 v[92:95], v[124:127], v[188:191], v[92:95]
	v_mfma_f32_16x16x32_bf16 v[28:31], v[128:131], v[170:173], v[28:31]
	v_mfma_f32_16x16x32_bf16 v[28:31], v[132:135], v[188:191], v[28:31]
	v_mfma_f32_16x16x32_bf16 v[24:27], v[162:165], v[170:173], v[24:27]
	v_mfma_f32_16x16x32_bf16 v[24:27], v[166:169], v[188:191], v[24:27]
	v_mfma_f32_16x16x32_bf16 v[88:91], v[136:139], v[170:173], v[88:91]
	v_mfma_f32_16x16x32_bf16 v[88:91], v[140:143], v[188:191], v[88:91]
	v_mfma_f32_16x16x32_bf16 v[80:83], v[136:139], v[192:195], v[80:83]
	v_mfma_f32_16x16x32_bf16 v[80:83], v[140:143], v[196:199], v[80:83]
	v_mfma_f32_16x16x32_bf16 v[16:19], v[162:165], v[192:195], v[16:19]
	v_mfma_f32_16x16x32_bf16 v[16:19], v[166:169], v[196:199], v[16:19]
	v_mfma_f32_16x16x32_bf16 v[20:23], v[128:131], v[192:195], v[20:23]
	v_mfma_f32_16x16x32_bf16 v[20:23], v[132:135], v[196:199], v[20:23]
	v_mfma_f32_16x16x32_bf16 v[84:87], v[120:123], v[192:195], v[84:87]
	v_mfma_f32_16x16x32_bf16 v[84:87], v[124:127], v[196:199], v[84:87]
	s_setprio 0
	s_setprio 1
	v_mfma_f32_16x16x32_bf16 v[76:79], v[120:123], v[200:203], v[76:79]
	v_mfma_f32_16x16x32_bf16 v[76:79], v[124:127], v[204:207], v[76:79]
	v_mfma_f32_16x16x32_bf16 v[12:15], v[128:131], v[200:203], v[12:15]
	v_mfma_f32_16x16x32_bf16 v[12:15], v[132:135], v[204:207], v[12:15]
	v_mfma_f32_16x16x32_bf16 v[8:11], v[162:165], v[200:203], v[8:11]
	v_mfma_f32_16x16x32_bf16 v[8:11], v[166:169], v[204:207], v[8:11]
	v_mfma_f32_16x16x32_bf16 v[72:75], v[136:139], v[200:203], v[72:75]
	v_mfma_f32_16x16x32_bf16 v[72:75], v[140:143], v[204:207], v[72:75]
	v_mfma_f32_16x16x32_bf16 v[104:107], v[136:139], v[242:245], v[104:107]
	v_mfma_f32_16x16x32_bf16 v[104:107], v[140:143], v[246:249], v[104:107]
	v_mfma_f32_16x16x32_bf16 v[40:43], v[162:165], v[242:245], v[40:43]
	v_mfma_f32_16x16x32_bf16 v[40:43], v[166:169], v[246:249], v[40:43]
	v_mfma_f32_16x16x32_bf16 v[44:47], v[128:131], v[242:245], v[44:47]
	v_mfma_f32_16x16x32_bf16 v[44:47], v[132:135], v[246:249], v[44:47]
	v_mfma_f32_16x16x32_bf16 v[108:111], v[120:123], v[242:245], v[108:111]
	v_mfma_f32_16x16x32_bf16 v[108:111], v[124:127], v[246:249], v[108:111]
	s_setprio 0
	s_barrier
	v_add_u32_e32 v0, s91, v230
	s_add_i32 s38, 0, 0x1c000
	ds_read_b128 v[120:123], v0
	ds_read_b128 v[124:127], v0 offset:1024
	ds_read_b128 v[128:131], v0 offset:2048
	ds_read_b128 v[132:135], v0 offset:3072
	v_add_u32_e32 v0, s38, v230
	ds_read_b128 v[136:139], v0
	ds_read_b128 v[140:143], v0 offset:1024
	ds_read_b128 v[162:165], v0 offset:2048
	ds_read_b128 v[166:169], v0 offset:3072
	s_add_u32 s86, s86, s48
	s_addc_u32 s87, s87, s49
	s_mov_b32 m0, s95
	v_lshl_add_u64 v[148:149], s[86:87], 0, v[2:3]
	ds_read_b128 v[170:173], v238 offset:32768
	ds_read_b128 v[188:191], v238 offset:33792
	ds_read_b128 v[192:195], v238 offset:34816
	ds_read_b128 v[196:199], v238 offset:35840
	ds_read_b128 v[200:203], v238 offset:36864
	ds_read_b128 v[204:207], v238 offset:37888
	ds_read_b128 v[242:245], v238 offset:38912
	ds_read_b128 v[246:249], v238 offset:39936
	global_load_lds_dwordx4 v[148:149], off
	v_lshl_add_u64 v[148:149], s[86:87], 0, v[178:179]
	s_mov_b32 m0, s96
	s_nop 0
	global_load_lds_dwordx4 v[148:149], off
	s_waitcnt vmcnt(8)
	s_waitcnt lgkmcnt(0)
	s_barrier
	s_setprio 1
	s_waitcnt lgkmcnt(0)
	v_mfma_f32_16x16x32_bf16 v[158:161], v[120:123], v[170:173], v[158:161]
	v_mfma_f32_16x16x32_bf16 v[158:161], v[124:127], v[188:191], v[158:161]
	v_mfma_f32_16x16x32_bf16 v[148:151], v[120:123], v[192:195], v[150:153]
	v_mfma_f32_16x16x32_bf16 v[150:153], v[124:127], v[196:199], v[148:151]
	v_mfma_f32_16x16x32_bf16 v[100:103], v[120:123], v[200:203], v[100:103]
	v_mfma_f32_16x16x32_bf16 v[100:103], v[124:127], v[204:207], v[100:103]
	v_mfma_f32_16x16x32_bf16 v[116:119], v[120:123], v[242:245], v[116:119]
	v_mfma_f32_16x16x32_bf16 v[116:119], v[124:127], v[246:249], v[116:119]
	v_mfma_f32_16x16x32_bf16 v[68:71], v[128:131], v[242:245], v[68:71]
	v_mfma_f32_16x16x32_bf16 v[68:71], v[132:135], v[246:249], v[68:71]
	v_mfma_f32_16x16x32_bf16 v[36:39], v[128:131], v[200:203], v[36:39]
	v_mfma_f32_16x16x32_bf16 v[36:39], v[132:135], v[204:207], v[36:39]
	v_mfma_f32_16x16x32_bf16 v[52:55], v[128:131], v[192:195], v[52:55]
	v_mfma_f32_16x16x32_bf16 v[52:55], v[132:135], v[196:199], v[52:55]
	v_mfma_f32_16x16x32_bf16 v[60:63], v[128:131], v[170:173], v[60:63]
	v_mfma_f32_16x16x32_bf16 v[60:63], v[132:135], v[188:191], v[60:63]
	s_setprio 0
	s_setprio 1
	v_mfma_f32_16x16x32_bf16 v[154:157], v[136:139], v[170:173], v[154:157]
	v_mfma_f32_16x16x32_bf16 v[154:157], v[140:143], v[188:191], v[154:157]
	v_mfma_f32_16x16x32_bf16 v[144:147], v[136:139], v[192:195], v[144:147]
	v_mfma_f32_16x16x32_bf16 v[146:149], v[140:143], v[196:199], v[144:147]
	v_mfma_f32_16x16x32_bf16 v[96:99], v[136:139], v[200:203], v[96:99]
	v_mfma_f32_16x16x32_bf16 v[96:99], v[140:143], v[204:207], v[96:99]
	v_mfma_f32_16x16x32_bf16 v[112:115], v[136:139], v[242:245], v[112:115]
	v_mfma_f32_16x16x32_bf16 v[112:115], v[140:143], v[246:249], v[112:115]
	v_mfma_f32_16x16x32_bf16 v[64:67], v[162:165], v[242:245], v[64:67]
	v_mfma_f32_16x16x32_bf16 v[64:67], v[166:169], v[246:249], v[64:67]
	v_mfma_f32_16x16x32_bf16 v[32:35], v[162:165], v[200:203], v[32:35]
	v_mfma_f32_16x16x32_bf16 v[32:35], v[166:169], v[204:207], v[32:35]
	v_mfma_f32_16x16x32_bf16 v[48:51], v[162:165], v[192:195], v[48:51]
	v_mfma_f32_16x16x32_bf16 v[48:51], v[166:169], v[196:199], v[48:51]
	v_mfma_f32_16x16x32_bf16 v[56:59], v[162:165], v[170:173], v[56:59]
	v_mfma_f32_16x16x32_bf16 v[56:59], v[166:169], v[188:191], v[56:59]
	s_setprio 0
	s_barrier
; #define PG8_STAGE(bufoff, gbase, voff) do { _Pragma("unroll") for (int _i = 0; _i < 2; ++_i) \
;         __builtin_amdgcn_global_load_lds((const unsigned*)((const char*)(gbase) + (voff)[_i]), (PG8_LAS unsigned*)(lds + (bufoff) + ldsw + _i * 8192), 16, 0, 0); } while (0)
; #define PG8_LDA(dst, b, h) do { _Pragma("unroll") for (int m = 0; m < 4; ++m) _Pragma("unroll") for (int k = 0; k < 2; ++k) dst[m][k] = *(const PG8_LAS bf16x8*)(lds + PG8_SA(b, h) + aoff + m * 2048 + k * 1024); } while (0)
; #define PG8_MMA(ai, bj, At, Bt) do { __builtin_amdgcn_s_setprio(1); _Pragma("unroll") for (int m = 0; m < 4; ++m) _Pragma("unroll") for (int n = 0; n < 2; ++n) _Pragma("unroll") for (int k = 0; k < 2; ++k) \
;         acc[ai][bj][m][n] = __builtin_amdgcn_mfma_f32_16x16x32_bf16(Bt[n][k], At[m][k], acc[ai][bj][m][n], 0, 0, 0); __builtin_amdgcn_s_setprio(0); } while (0)
; #define PG8_WAIT_V(n) asm volatile("s_waitcnt vmcnt(" #n ")" ::: "memory")
; #define PG8_WAIT_L(n) asm volatile("s_waitcnt lgkmcnt(" #n ")" ::: "memory")
; #define PG8_BAR __builtin_amdgcn_s_barrier()
; #define PG8_SCHED __builtin_amdgcn_sched_barrier(0)
; template <class Epi, class Sched, bool ALIGN_EPI = false, bool SP2 = false>
; __device__ __forceinline__ void gemm_phase(PG8_LAS unsigned char* lds, const Gemm g, const Sched& S, const Epi& E) {
;     ...
;             PG8_LDA(At, 1, 1); PG8_STAGE(PG8_SB(1, 0), b3, voffB); PG8_STAGE(PG8_SB(1, 1), b3 + hstep, voffB); PG8_STAGE(PG8_SA(1, 0), a3, voffA);
;             PG8_WAIT_V(8); PG8_WAIT_L(0); PG8_BAR; PG8_MMA(1, 0, At, B0); PG8_MMA(1, 1, At, B1); PG8_BAR; PG8_SCHED;
	s_add_i32 s39, s91, s92
	v_lshl_add_u64 v[144:145], v[174:175], 0, s[24:25]
	s_mov_b32 m0, s39
	ds_read_b128 v[170:173], v238 offset:49152
	ds_read_b128 v[188:191], v238 offset:50176
	ds_read_b128 v[192:195], v238 offset:51200
	ds_read_b128 v[196:199], v238 offset:52224
	ds_read_b128 v[200:203], v238 offset:53248
	ds_read_b128 v[204:207], v238 offset:54272
	ds_read_b128 v[242:245], v238 offset:55296
	ds_read_b128 v[246:249], v238 offset:56320
	global_load_lds_dwordx4 v[144:145], off
	v_lshl_add_u64 v[144:145], v[208:209], 0, s[24:25]
	s_add_i32 m0, s39, 0x2000
	s_add_i32 s38, s38, s92
	global_load_lds_dwordx4 v[144:145], off
	v_lshl_add_u64 v[144:145], v[216:217], 0, s[24:25]
	s_mov_b32 m0, s38
	s_nop 0
	global_load_lds_dwordx4 v[144:145], off
	v_lshl_add_u64 v[144:145], v[224:225], 0, s[24:25]
	s_add_i32 m0, s38, 0x2000
	s_nop 0
	global_load_lds_dwordx4 v[144:145], off
	v_lshl_add_u64 v[144:145], v[226:227], 0, s[24:25]
	s_mov_b32 m0, s10
	s_nop 0
	global_load_lds_dwordx4 v[144:145], off
	v_lshl_add_u64 v[144:145], v[228:229], 0, s[24:25]
	s_mov_b32 m0, s11
	s_nop 0
	global_load_lds_dwordx4 v[144:145], off
	s_waitcnt vmcnt(8)
	s_waitcnt lgkmcnt(0)
	s_barrier
	s_setprio 1
	s_waitcnt lgkmcnt(0)
	v_mfma_f32_16x16x32_bf16 v[92:95], v[120:123], v[170:173], v[92:95]
	v_mfma_f32_16x16x32_bf16 v[92:95], v[124:127], v[188:191], v[92:95]
	v_mfma_f32_16x16x32_bf16 v[28:31], v[128:131], v[170:173], v[28:31]
	v_mfma_f32_16x16x32_bf16 v[28:31], v[132:135], v[188:191], v[28:31]
	v_mfma_f32_16x16x32_bf16 v[24:27], v[162:165], v[170:173], v[24:27]
	v_mfma_f32_16x16x32_bf16 v[24:27], v[166:169], v[188:191], v[24:27]
	v_mfma_f32_16x16x32_bf16 v[88:91], v[136:139], v[170:173], v[88:91]
	v_mfma_f32_16x16x32_bf16 v[88:91], v[140:143], v[188:191], v[88:91]
	v_mfma_f32_16x16x32_bf16 v[80:83], v[136:139], v[192:195], v[80:83]
	v_mfma_f32_16x16x32_bf16 v[80:83], v[140:143], v[196:199], v[80:83]
	v_mfma_f32_16x16x32_bf16 v[16:19], v[162:165], v[192:195], v[16:19]
	v_mfma_f32_16x16x32_bf16 v[16:19], v[166:169], v[196:199], v[16:19]
	v_mfma_f32_16x16x32_bf16 v[20:23], v[128:131], v[192:195], v[20:23]
	v_mfma_f32_16x16x32_bf16 v[20:23], v[132:135], v[196:199], v[20:23]
	v_mfma_f32_16x16x32_bf16 v[84:87], v[120:123], v[192:195], v[84:87]
	v_mfma_f32_16x16x32_bf16 v[84:87], v[124:127], v[196:199], v[84:87]
	s_setprio 0
	s_setprio 1
	v_mfma_f32_16x16x32_bf16 v[76:79], v[120:123], v[200:203], v[76:79]
	v_mfma_f32_16x16x32_bf16 v[76:79], v[124:127], v[204:207], v[76:79]
	v_mfma_f32_16x16x32_bf16 v[12:15], v[128:131], v[200:203], v[12:15]
	v_mfma_f32_16x16x32_bf16 v[12:15], v[132:135], v[204:207], v[12:15]
	v_mfma_f32_16x16x32_bf16 v[8:11], v[162:165], v[200:203], v[8:11]
	v_mfma_f32_16x16x32_bf16 v[8:11], v[166:169], v[204:207], v[8:11]
	v_mfma_f32_16x16x32_bf16 v[72:75], v[136:139], v[200:203], v[72:75]
	v_mfma_f32_16x16x32_bf16 v[72:75], v[140:143], v[204:207], v[72:75]
	v_mfma_f32_16x16x32_bf16 v[104:107], v[136:139], v[242:245], v[104:107]
	v_mfma_f32_16x16x32_bf16 v[104:107], v[140:143], v[246:249], v[104:107]
	v_mfma_f32_16x16x32_bf16 v[40:43], v[162:165], v[242:245], v[40:43]
	v_mfma_f32_16x16x32_bf16 v[40:43], v[166:169], v[246:249], v[40:43]
	v_mfma_f32_16x16x32_bf16 v[44:47], v[128:131], v[242:245], v[44:47]
	v_mfma_f32_16x16x32_bf16 v[44:47], v[132:135], v[246:249], v[44:47]
	v_mfma_f32_16x16x32_bf16 v[108:111], v[120:123], v[242:245], v[108:111]
	v_mfma_f32_16x16x32_bf16 v[108:111], v[124:127], v[246:249], v[108:111]
	s_setprio 0
	s_barrier
	s_add_u32 s0, s0, 0x100
	s_addc_u32 s1, s1, 0
	s_add_u32 s72, s72, 0x100
	s_addc_u32 s73, s73, 0
	s_cmp_ge_u32 s88, s9
	s_mov_b32 s86, s88
	s_cbranch_scc0 .LBB0_365

; #define PG8_STAGE(bufoff, gbase, voff) do { _Pragma("unroll") for (int _i = 0; _i < 2; ++_i) \
;         __builtin_amdgcn_global_load_lds((const unsigned*)((const char*)(gbase) + (voff)[_i]), (PG8_LAS unsigned*)(lds + (bufoff) + ldsw + _i * 8192), 16, 0, 0); } while (0)
; #define PG8_LDA(dst, b, h) do { _Pragma("unroll") for (int m = 0; m < 4; ++m) _Pragma("unroll") for (int k = 0; k < 2; ++k) dst[m][k] = *(const PG8_LAS bf16x8*)(lds + PG8_SA(b, h) + aoff + m * 2048 + k * 1024); } while (0)
; #define PG8_LDB(dst, b, h) do { _Pragma("unroll") for (int n = 0; n < 2; ++n) _Pragma("unroll") for (int k = 0; k < 2; ++k) dst[n][k] = *(const PG8_LAS bf16x8*)(lds + PG8_SB(b, h) + boff + n * 2048 + k * 1024); } while (0)
; #define PG8_MMA(ai, bj, At, Bt) do { __builtin_amdgcn_s_setprio(1); _Pragma("unroll") for (int m = 0; m < 4; ++m) _Pragma("unroll") for (int n = 0; n < 2; ++n) _Pragma("unroll") for (int k = 0; k < 2; ++k) \
;         acc[ai][bj][m][n] = __builtin_amdgcn_mfma_f32_16x16x32_bf16(Bt[n][k], At[m][k], acc[ai][bj][m][n], 0, 0, 0); __builtin_amdgcn_s_setprio(0); } while (0)
; #define PG8_WAIT_V(n) asm volatile("s_waitcnt vmcnt(" #n ")" ::: "memory")
; #define PG8_WAIT_L(n) asm volatile("s_waitcnt lgkmcnt(" #n ")" ::: "memory")
; template <class Epi, class Sched, bool ALIGN_EPI = false, bool SP2 = false>
; __device__ __forceinline__ void gemm_phase(PG8_LAS unsigned char* lds, const Gemm g, const Sched& S, const Epi& E) {
;     ...
;             const bool last = (t == nt - 2);
;             const char* a1 = cA + (size_t)(t + 1) * kstep;
;             const char* a2 = last ? nA : cA + (size_t)(t + 2) * kstep; const char* b2 = last ? nB : cB + (size_t)(t + 2) * kstep;
;             const char* a3 = a2 + kstep; const char* b3 = b2 + kstep;
;             if (last && has_next) S.a_ready(nxt);
;             if constexpr (SP2) {
;             PG8_LDB(B0, 0, 0); PG8_LDB(B1, 0, 1); PG8_SCHED; PG8_LDA(At, 0, 0); PG8_STAGE(PG8_SA(1, 1), a1 + hstep, voffA);
;             PG8_WAIT_V(8); PG8_WAIT_L(0); PG8_BAR; PG8_MMA(0, 0, At, B0); PG8_MMA(0, 1, At, B1); PG8_BAR; PG8_SCHED;
;             PG8_LDA(At, 0, 1); PG8_STAGE(PG8_SB(0, 0), b2, voffB); PG8_STAGE(PG8_SB(0, 1), b2 + hstep, voffB); PG8_STAGE(PG8_SA(0, 0), a2, voffA);
;             PG8_WAIT_V(8); PG8_WAIT_L(0); PG8_BAR; PG8_MMA(1, 0, At, B0); PG8_MMA(1, 1, At, B1); PG8_BAR; PG8_SCHED;
.LBB0_468:
	s_add_i32 s78, s38, 2
	s_add_u32 s79, s0, 0x80
	s_addc_u32 s39, s1, 0
	s_cmp_eq_u32 s33, s38
	s_cselect_b32 s39, s7, s39
	s_cselect_b32 s38, s6, s79
	s_cselect_b32 s81, s23, s41
	s_cselect_b32 s80, s22, s40
	s_add_i32 s79, 0, 0x14000
	v_add_u32_e32 v148, s19, v162
	v_add_u32_e32 v171, s79, v162
	ds_read_b128 v[136:139], v148
	ds_read_b128 v[140:143], v148 offset:1024
	ds_read_b128 v[144:147], v148 offset:2048
	ds_read_b128 v[148:151], v148 offset:3072
	ds_read_b128 v[172:175], v171
	ds_read_b128 v[176:179], v171 offset:1024
	ds_read_b128 v[184:187], v171 offset:2048
	ds_read_b128 v[188:191], v171 offset:3072
	v_lshl_add_u64 v[180:181], s[0:1], 0, v[158:159]
	s_add_i32 m0, s46, 0xc000
	ds_read_b128 v[192:195], v167
	ds_read_b128 v[196:199], v167 offset:1024
	ds_read_b128 v[200:203], v167 offset:2048
	ds_read_b128 v[204:207], v167 offset:3072
	ds_read_b128 v[230:233], v167 offset:4096
	ds_read_b128 v[234:237], v167 offset:5120
	ds_read_b128 v[238:241], v167 offset:6144
	ds_read_b128 v[242:245], v167 offset:7168
	global_load_lds_dwordx4 v[180:181], off
	v_lshl_add_u64 v[180:181], s[0:1], 0, v[160:161]
	s_add_i32 m0, s46, 0xe000
	s_nop 0
	global_load_lds_dwordx4 v[180:181], off
	s_waitcnt vmcnt(8)
	s_waitcnt lgkmcnt(0)
	s_barrier
	s_setprio 1
	s_waitcnt lgkmcnt(0)
	v_mfma_f32_16x16x32_bf16 v[132:135], v[136:139], v[192:195], v[132:135]
	v_mfma_f32_16x16x32_bf16 v[132:135], v[140:143], v[196:199], v[132:135]
	v_mfma_f32_16x16x32_bf16 v[128:131], v[144:147], v[192:195], v[128:131]
	v_mfma_f32_16x16x32_bf16 v[128:131], v[148:151], v[196:199], v[128:131]
	v_mfma_f32_16x16x32_bf16 v[120:123], v[184:187], v[192:195], v[120:123]
	v_mfma_f32_16x16x32_bf16 v[120:123], v[188:191], v[196:199], v[120:123]
	v_mfma_f32_16x16x32_bf16 v[124:127], v[172:175], v[192:195], v[124:127]
	v_mfma_f32_16x16x32_bf16 v[124:127], v[176:179], v[196:199], v[124:127]
	v_mfma_f32_16x16x32_bf16 v[108:111], v[172:175], v[200:203], v[108:111]
	v_mfma_f32_16x16x32_bf16 v[108:111], v[176:179], v[204:207], v[108:111]
	v_mfma_f32_16x16x32_bf16 v[104:107], v[184:187], v[200:203], v[104:107]
	v_mfma_f32_16x16x32_bf16 v[104:107], v[188:191], v[204:207], v[104:107]
	v_mfma_f32_16x16x32_bf16 v[112:115], v[144:147], v[200:203], v[112:115]
	v_mfma_f32_16x16x32_bf16 v[112:115], v[148:151], v[204:207], v[112:115]
	v_mfma_f32_16x16x32_bf16 v[116:119], v[136:139], v[200:203], v[116:119]
	v_mfma_f32_16x16x32_bf16 v[116:119], v[140:143], v[204:207], v[116:119]
	s_setprio 0
	s_setprio 1
	v_mfma_f32_16x16x32_bf16 v[100:103], v[136:139], v[230:233], v[100:103]
	v_mfma_f32_16x16x32_bf16 v[100:103], v[140:143], v[234:237], v[100:103]
	v_mfma_f32_16x16x32_bf16 v[96:99], v[144:147], v[230:233], v[96:99]
	v_mfma_f32_16x16x32_bf16 v[96:99], v[148:151], v[234:237], v[96:99]
	v_mfma_f32_16x16x32_bf16 v[88:91], v[184:187], v[230:233], v[88:91]
	v_mfma_f32_16x16x32_bf16 v[88:91], v[188:191], v[234:237], v[88:91]
	v_mfma_f32_16x16x32_bf16 v[92:95], v[172:175], v[230:233], v[92:95]
	v_mfma_f32_16x16x32_bf16 v[92:95], v[176:179], v[234:237], v[92:95]
	v_mfma_f32_16x16x32_bf16 v[76:79], v[172:175], v[238:241], v[76:79]
	v_mfma_f32_16x16x32_bf16 v[76:79], v[176:179], v[242:245], v[76:79]
	v_mfma_f32_16x16x32_bf16 v[72:75], v[184:187], v[238:241], v[72:75]
	v_mfma_f32_16x16x32_bf16 v[72:75], v[188:191], v[242:245], v[72:75]
	v_mfma_f32_16x16x32_bf16 v[80:83], v[144:147], v[238:241], v[80:83]
	v_mfma_f32_16x16x32_bf16 v[80:83], v[148:151], v[242:245], v[80:83]
	v_mfma_f32_16x16x32_bf16 v[84:87], v[136:139], v[238:241], v[84:87]
	v_mfma_f32_16x16x32_bf16 v[84:87], v[140:143], v[242:245], v[84:87]
	s_setprio 0
	s_barrier
	s_add_i32 s82, s19, s42
	v_lshl_add_u64 v[180:181], s[80:81], 0, v[154:155]
	s_mov_b32 m0, s82
	ds_read_b128 v[192:195], v167 offset:16384
	ds_read_b128 v[196:199], v167 offset:17408
	ds_read_b128 v[200:203], v167 offset:18432
	ds_read_b128 v[204:207], v167 offset:19456
	ds_read_b128 v[230:233], v167 offset:20480
	ds_read_b128 v[234:237], v167 offset:21504
	ds_read_b128 v[238:241], v167 offset:22528
	ds_read_b128 v[242:245], v167 offset:23552
	global_load_lds_dwordx4 v[180:181], off
	s_add_i32 m0, s82, 0x2000
	v_lshl_add_u64 v[208:209], s[80:81], 0, v[2:3]
	s_add_u32 s80, s80, s48
	s_addc_u32 s81, s81, s49
	s_add_i32 s79, s79, s42
	global_load_lds_dwordx4 v[208:209], off
	v_lshl_add_u64 v[216:217], s[80:81], 0, v[154:155]
	s_mov_b32 m0, s79
	v_lshl_add_u64 v[224:225], s[80:81], 0, v[2:3]
	global_load_lds_dwordx4 v[216:217], off
	s_add_i32 m0, s79, 0x2000
	v_lshl_add_u64 v[226:227], s[38:39], 0, v[156:157]
	global_load_lds_dwordx4 v[224:225], off
	s_mov_b32 m0, s46
	v_lshl_add_u64 v[246:247], s[38:39], 0, v[152:153]
	global_load_lds_dwordx4 v[226:227], off
	s_mov_b32 m0, s47
	s_nop 0
	global_load_lds_dwordx4 v[246:247], off
	s_waitcnt vmcnt(8)
	s_waitcnt lgkmcnt(0)
	s_barrier
; #define PG8_STAGE(bufoff, gbase, voff) do { _Pragma("unroll") for (int _i = 0; _i < 2; ++_i) \
;         __builtin_amdgcn_global_load_lds((const unsigned*)((const char*)(gbase) + (voff)[_i]), (PG8_LAS unsigned*)(lds + (bufoff) + ldsw + _i * 8192), 16, 0, 0); } while (0)
; #define PG8_LDA(dst, b, h) do { _Pragma("unroll") for (int m = 0; m < 4; ++m) _Pragma("unroll") for (int k = 0; k < 2; ++k) dst[m][k] = *(const PG8_LAS bf16x8*)(lds + PG8_SA(b, h) + aoff + m * 2048 + k * 1024); } while (0)
; #define PG8_LDB(dst, b, h) do { _Pragma("unroll") for (int n = 0; n < 2; ++n) _Pragma("unroll") for (int k = 0; k < 2; ++k) dst[n][k] = *(const PG8_LAS bf16x8*)(lds + PG8_SB(b, h) + boff + n * 2048 + k * 1024); } while (0)
; #define PG8_MMA(ai, bj, At, Bt) do { __builtin_amdgcn_s_setprio(1); _Pragma("unroll") for (int m = 0; m < 4; ++m) _Pragma("unroll") for (int n = 0; n < 2; ++n) _Pragma("unroll") for (int k = 0; k < 2; ++k) \
;         acc[ai][bj][m][n] = __builtin_amdgcn_mfma_f32_16x16x32_bf16(Bt[n][k], At[m][k], acc[ai][bj][m][n], 0, 0, 0); __builtin_amdgcn_s_setprio(0); } while (0)
; #define PG8_WAIT_V(n) asm volatile("s_waitcnt vmcnt(" #n ")" ::: "memory")
; #define PG8_WAIT_L(n) asm volatile("s_waitcnt lgkmcnt(" #n ")" ::: "memory")
; #define PG8_BAR __builtin_amdgcn_s_barrier()
; #define PG8_SCHED __builtin_amdgcn_sched_barrier(0)
; template <class Epi, class Sched, bool ALIGN_EPI = false, bool SP2 = false>
; __device__ __forceinline__ void gemm_phase(PG8_LAS unsigned char* lds, const Gemm g, const Sched& S, const Epi& E) {
;     ...
;             PG8_WAIT_V(8); PG8_WAIT_L(0); PG8_BAR; PG8_MMA(1, 0, At, B0); PG8_MMA(1, 1, At, B1); PG8_BAR; PG8_SCHED;
;             PG8_LDB(B0, 1, 0); PG8_LDB(B1, 1, 1); PG8_SCHED; PG8_LDA(At, 1, 0); PG8_STAGE(PG8_SA(0, 1), a2 + hstep, voffA);
;             PG8_WAIT_V(8); PG8_WAIT_L(0); PG8_BAR; PG8_MMA(0, 0, At, B0); PG8_MMA(0, 1, At, B1); PG8_BAR; PG8_SCHED;
	s_setprio 1
	s_waitcnt lgkmcnt(0)
	v_mfma_f32_16x16x32_bf16 v[68:71], v[136:139], v[192:195], v[68:71]
	v_mfma_f32_16x16x32_bf16 v[68:71], v[140:143], v[196:199], v[68:71]
	v_mfma_f32_16x16x32_bf16 v[64:67], v[144:147], v[192:195], v[64:67]
	v_mfma_f32_16x16x32_bf16 v[64:67], v[148:151], v[196:199], v[64:67]
	v_mfma_f32_16x16x32_bf16 v[56:59], v[184:187], v[192:195], v[56:59]
	v_mfma_f32_16x16x32_bf16 v[56:59], v[188:191], v[196:199], v[56:59]
	v_mfma_f32_16x16x32_bf16 v[60:63], v[172:175], v[192:195], v[60:63]
	v_mfma_f32_16x16x32_bf16 v[60:63], v[176:179], v[196:199], v[60:63]
	v_mfma_f32_16x16x32_bf16 v[44:47], v[172:175], v[200:203], v[44:47]
	v_mfma_f32_16x16x32_bf16 v[44:47], v[176:179], v[204:207], v[44:47]
	v_mfma_f32_16x16x32_bf16 v[40:43], v[184:187], v[200:203], v[40:43]
	v_mfma_f32_16x16x32_bf16 v[40:43], v[188:191], v[204:207], v[40:43]
	v_mfma_f32_16x16x32_bf16 v[48:51], v[144:147], v[200:203], v[48:51]
	v_mfma_f32_16x16x32_bf16 v[48:51], v[148:151], v[204:207], v[48:51]
	v_mfma_f32_16x16x32_bf16 v[52:55], v[136:139], v[200:203], v[52:55]
	v_mfma_f32_16x16x32_bf16 v[52:55], v[140:143], v[204:207], v[52:55]
	s_setprio 0
	s_setprio 1
	v_mfma_f32_16x16x32_bf16 v[36:39], v[136:139], v[230:233], v[36:39]
	v_mfma_f32_16x16x32_bf16 v[36:39], v[140:143], v[234:237], v[36:39]
	v_mfma_f32_16x16x32_bf16 v[32:35], v[144:147], v[230:233], v[32:35]
	v_mfma_f32_16x16x32_bf16 v[32:35], v[148:151], v[234:237], v[32:35]
	v_mfma_f32_16x16x32_bf16 v[24:27], v[184:187], v[230:233], v[24:27]
	v_mfma_f32_16x16x32_bf16 v[24:27], v[188:191], v[234:237], v[24:27]
	v_mfma_f32_16x16x32_bf16 v[28:31], v[172:175], v[230:233], v[28:31]
	v_mfma_f32_16x16x32_bf16 v[28:31], v[176:179], v[234:237], v[28:31]
	v_mfma_f32_16x16x32_bf16 v[12:15], v[172:175], v[238:241], v[12:15]
	v_mfma_f32_16x16x32_bf16 v[12:15], v[176:179], v[242:245], v[12:15]
	v_mfma_f32_16x16x32_bf16 v[8:11], v[184:187], v[238:241], v[8:11]
	v_mfma_f32_16x16x32_bf16 v[8:11], v[188:191], v[242:245], v[8:11]
	v_mfma_f32_16x16x32_bf16 v[16:19], v[144:147], v[238:241], v[16:19]
	v_mfma_f32_16x16x32_bf16 v[16:19], v[148:151], v[242:245], v[16:19]
	v_mfma_f32_16x16x32_bf16 v[20:23], v[136:139], v[238:241], v[20:23]
	v_mfma_f32_16x16x32_bf16 v[20:23], v[140:143], v[242:245], v[20:23]
	s_setprio 0
	s_barrier
	s_add_i32 s79, 0, 0x1c000
	v_add_u32_e32 v148, s91, v162
	v_add_u32_e32 v171, s79, v162
	ds_read_b128 v[136:139], v148
	ds_read_b128 v[140:143], v148 offset:1024
	ds_read_b128 v[144:147], v148 offset:2048
	ds_read_b128 v[148:151], v148 offset:3072
	ds_read_b128 v[172:175], v171
	ds_read_b128 v[176:179], v171 offset:1024
	ds_read_b128 v[184:187], v171 offset:2048
	ds_read_b128 v[188:191], v171 offset:3072
	s_add_u32 s38, s38, s48
	s_addc_u32 s39, s39, s49
	s_mov_b32 m0, s52
	v_lshl_add_u64 v[248:249], s[38:39], 0, v[156:157]
	ds_read_b128 v[192:195], v167 offset:32768
	ds_read_b128 v[196:199], v167 offset:33792
	ds_read_b128 v[200:203], v167 offset:34816
	ds_read_b128 v[204:207], v167 offset:35840
	ds_read_b128 v[230:233], v167 offset:36864
	ds_read_b128 v[234:237], v167 offset:37888
	ds_read_b128 v[238:241], v167 offset:38912
	ds_read_b128 v[242:245], v167 offset:39936
	global_load_lds_dwordx4 v[248:249], off
	v_lshl_add_u64 v[248:249], s[38:39], 0, v[152:153]
	s_mov_b32 m0, s53
	s_nop 0
	global_load_lds_dwordx4 v[248:249], off
	s_waitcnt vmcnt(8)
	s_waitcnt lgkmcnt(0)
	s_barrier
	s_setprio 1
	s_waitcnt lgkmcnt(0)
	v_mfma_f32_16x16x32_bf16 v[132:135], v[136:139], v[192:195], v[132:135]
	v_mfma_f32_16x16x32_bf16 v[132:135], v[140:143], v[196:199], v[132:135]
	v_mfma_f32_16x16x32_bf16 v[128:131], v[144:147], v[192:195], v[128:131]
	v_mfma_f32_16x16x32_bf16 v[128:131], v[148:151], v[196:199], v[128:131]
	v_mfma_f32_16x16x32_bf16 v[120:123], v[184:187], v[192:195], v[120:123]
	v_mfma_f32_16x16x32_bf16 v[120:123], v[188:191], v[196:199], v[120:123]
	v_mfma_f32_16x16x32_bf16 v[124:127], v[172:175], v[192:195], v[124:127]
	v_mfma_f32_16x16x32_bf16 v[124:127], v[176:179], v[196:199], v[124:127]
	v_mfma_f32_16x16x32_bf16 v[108:111], v[172:175], v[200:203], v[108:111]
	v_mfma_f32_16x16x32_bf16 v[108:111], v[176:179], v[204:207], v[108:111]
	v_mfma_f32_16x16x32_bf16 v[104:107], v[184:187], v[200:203], v[104:107]
	v_mfma_f32_16x16x32_bf16 v[104:107], v[188:191], v[204:207], v[104:107]
	v_mfma_f32_16x16x32_bf16 v[112:115], v[144:147], v[200:203], v[112:115]
	v_mfma_f32_16x16x32_bf16 v[112:115], v[148:151], v[204:207], v[112:115]
	v_mfma_f32_16x16x32_bf16 v[116:119], v[136:139], v[200:203], v[116:119]
	v_mfma_f32_16x16x32_bf16 v[116:119], v[140:143], v[204:207], v[116:119]
	s_setprio 0
	s_setprio 1
	v_mfma_f32_16x16x32_bf16 v[100:103], v[136:139], v[230:233], v[100:103]
	v_mfma_f32_16x16x32_bf16 v[100:103], v[140:143], v[234:237], v[100:103]
	v_mfma_f32_16x16x32_bf16 v[96:99], v[144:147], v[230:233], v[96:99]
	v_mfma_f32_16x16x32_bf16 v[96:99], v[148:151], v[234:237], v[96:99]
	v_mfma_f32_16x16x32_bf16 v[88:91], v[184:187], v[230:233], v[88:91]
	v_mfma_f32_16x16x32_bf16 v[88:91], v[188:191], v[234:237], v[88:91]
	v_mfma_f32_16x16x32_bf16 v[92:95], v[172:175], v[230:233], v[92:95]
	v_mfma_f32_16x16x32_bf16 v[92:95], v[176:179], v[234:237], v[92:95]
	v_mfma_f32_16x16x32_bf16 v[76:79], v[172:175], v[238:241], v[76:79]
	v_mfma_f32_16x16x32_bf16 v[76:79], v[176:179], v[242:245], v[76:79]
	v_mfma_f32_16x16x32_bf16 v[72:75], v[184:187], v[238:241], v[72:75]
	v_mfma_f32_16x16x32_bf16 v[72:75], v[188:191], v[242:245], v[72:75]
	v_mfma_f32_16x16x32_bf16 v[80:83], v[144:147], v[238:241], v[80:83]
	v_mfma_f32_16x16x32_bf16 v[80:83], v[148:151], v[242:245], v[80:83]
	v_mfma_f32_16x16x32_bf16 v[84:87], v[136:139], v[238:241], v[84:87]
	v_mfma_f32_16x16x32_bf16 v[84:87], v[140:143], v[242:245], v[84:87]
	s_setprio 0
	s_barrier
; #define PG8_STAGE(bufoff, gbase, voff) do { _Pragma("unroll") for (int _i = 0; _i < 2; ++_i) \
;         __builtin_amdgcn_global_load_lds((const unsigned*)((const char*)(gbase) + (voff)[_i]), (PG8_LAS unsigned*)(lds + (bufoff) + ldsw + _i * 8192), 16, 0, 0); } while (0)
; #define PG8_LDA(dst, b, h) do { _Pragma("unroll") for (int m = 0; m < 4; ++m) _Pragma("unroll") for (int k = 0; k < 2; ++k) dst[m][k] = *(const PG8_LAS bf16x8*)(lds + PG8_SA(b, h) + aoff + m * 2048 + k * 1024); } while (0)
; #define PG8_MMA(ai, bj, At, Bt) do { __builtin_amdgcn_s_setprio(1); _Pragma("unroll") for (int m = 0; m < 4; ++m) _Pragma("unroll") for (int n = 0; n < 2; ++n) _Pragma("unroll") for (int k = 0; k < 2; ++k) \
;         acc[ai][bj][m][n] = __builtin_amdgcn_mfma_f32_16x16x32_bf16(Bt[n][k], At[m][k], acc[ai][bj][m][n], 0, 0, 0); __builtin_amdgcn_s_setprio(0); } while (0)
; #define PG8_WAIT_V(n) asm volatile("s_waitcnt vmcnt(" #n ")" ::: "memory")
; #define PG8_WAIT_L(n) asm volatile("s_waitcnt lgkmcnt(" #n ")" ::: "memory")
; #define PG8_BAR __builtin_amdgcn_s_barrier()
; #define PG8_SCHED __builtin_amdgcn_sched_barrier(0)
; template <class Epi, class Sched, bool ALIGN_EPI = false, bool SP2 = false>
; __device__ __forceinline__ void gemm_phase(PG8_LAS unsigned char* lds, const Gemm g, const Sched& S, const Epi& E) {
;     ...
;             PG8_LDA(At, 1, 1); PG8_STAGE(PG8_SB(1, 0), b3, voffB); PG8_STAGE(PG8_SB(1, 1), b3 + hstep, voffB); PG8_STAGE(PG8_SA(1, 0), a3, voffA);
;             PG8_WAIT_V(8); PG8_WAIT_L(0); PG8_BAR; PG8_MMA(1, 0, At, B0); PG8_MMA(1, 1, At, B1); PG8_BAR; PG8_SCHED;
	s_add_i32 s38, s91, s42
	v_lshl_add_u64 v[180:181], v[180:181], 0, s[24:25]
	s_mov_b32 m0, s38
	ds_read_b128 v[192:195], v167 offset:49152
	ds_read_b128 v[196:199], v167 offset:50176
	ds_read_b128 v[200:203], v167 offset:51200
	ds_read_b128 v[204:207], v167 offset:52224
	ds_read_b128 v[230:233], v167 offset:53248
	ds_read_b128 v[234:237], v167 offset:54272
	ds_read_b128 v[238:241], v167 offset:55296
	ds_read_b128 v[242:245], v167 offset:56320
	global_load_lds_dwordx4 v[180:181], off
	v_lshl_add_u64 v[180:181], v[208:209], 0, s[24:25]
	s_add_i32 m0, s38, 0x2000
	s_add_i32 s38, s79, s42
	global_load_lds_dwordx4 v[180:181], off
	v_lshl_add_u64 v[180:181], v[216:217], 0, s[24:25]
	s_mov_b32 m0, s38
	s_nop 0
	global_load_lds_dwordx4 v[180:181], off
	v_lshl_add_u64 v[180:181], v[224:225], 0, s[24:25]
	s_add_i32 m0, s38, 0x2000
	s_nop 0
	global_load_lds_dwordx4 v[180:181], off
	v_lshl_add_u64 v[180:181], v[226:227], 0, s[24:25]
	s_mov_b32 m0, s72
	s_nop 0
	global_load_lds_dwordx4 v[180:181], off
	v_lshl_add_u64 v[180:181], v[246:247], 0, s[24:25]
	s_mov_b32 m0, s73
	s_nop 0
	global_load_lds_dwordx4 v[180:181], off
	s_waitcnt vmcnt(8)
	s_waitcnt lgkmcnt(0)
	s_barrier
	s_setprio 1
	s_waitcnt lgkmcnt(0)
	v_mfma_f32_16x16x32_bf16 v[68:71], v[136:139], v[192:195], v[68:71]
	v_mfma_f32_16x16x32_bf16 v[68:71], v[140:143], v[196:199], v[68:71]
	v_mfma_f32_16x16x32_bf16 v[64:67], v[144:147], v[192:195], v[64:67]
	v_mfma_f32_16x16x32_bf16 v[64:67], v[148:151], v[196:199], v[64:67]
	v_mfma_f32_16x16x32_bf16 v[56:59], v[184:187], v[192:195], v[56:59]
	v_mfma_f32_16x16x32_bf16 v[56:59], v[188:191], v[196:199], v[56:59]
	v_mfma_f32_16x16x32_bf16 v[60:63], v[172:175], v[192:195], v[60:63]
	v_mfma_f32_16x16x32_bf16 v[60:63], v[176:179], v[196:199], v[60:63]
	v_mfma_f32_16x16x32_bf16 v[44:47], v[172:175], v[200:203], v[44:47]
	v_mfma_f32_16x16x32_bf16 v[44:47], v[176:179], v[204:207], v[44:47]
	v_mfma_f32_16x16x32_bf16 v[40:43], v[184:187], v[200:203], v[40:43]
	v_mfma_f32_16x16x32_bf16 v[40:43], v[188:191], v[204:207], v[40:43]
	v_mfma_f32_16x16x32_bf16 v[48:51], v[144:147], v[200:203], v[48:51]
	v_mfma_f32_16x16x32_bf16 v[48:51], v[148:151], v[204:207], v[48:51]
	v_mfma_f32_16x16x32_bf16 v[52:55], v[136:139], v[200:203], v[52:55]
	v_mfma_f32_16x16x32_bf16 v[52:55], v[140:143], v[204:207], v[52:55]
	s_setprio 0
	s_setprio 1
	v_mfma_f32_16x16x32_bf16 v[36:39], v[136:139], v[230:233], v[36:39]
	v_mfma_f32_16x16x32_bf16 v[36:39], v[140:143], v[234:237], v[36:39]
	v_mfma_f32_16x16x32_bf16 v[32:35], v[144:147], v[230:233], v[32:35]
	v_mfma_f32_16x16x32_bf16 v[32:35], v[148:151], v[234:237], v[32:35]
	v_mfma_f32_16x16x32_bf16 v[24:27], v[184:187], v[230:233], v[24:27]
	v_mfma_f32_16x16x32_bf16 v[24:27], v[188:191], v[234:237], v[24:27]
	v_mfma_f32_16x16x32_bf16 v[28:31], v[172:175], v[230:233], v[28:31]
	v_mfma_f32_16x16x32_bf16 v[28:31], v[176:179], v[234:237], v[28:31]
	v_mfma_f32_16x16x32_bf16 v[12:15], v[172:175], v[238:241], v[12:15]
	v_mfma_f32_16x16x32_bf16 v[12:15], v[176:179], v[242:245], v[12:15]
	v_mfma_f32_16x16x32_bf16 v[8:11], v[184:187], v[238:241], v[8:11]
	v_mfma_f32_16x16x32_bf16 v[8:11], v[188:191], v[242:245], v[8:11]
	v_mfma_f32_16x16x32_bf16 v[16:19], v[144:147], v[238:241], v[16:19]
	v_mfma_f32_16x16x32_bf16 v[16:19], v[148:151], v[242:245], v[16:19]
	v_mfma_f32_16x16x32_bf16 v[20:23], v[136:139], v[238:241], v[20:23]
	v_mfma_f32_16x16x32_bf16 v[20:23], v[140:143], v[242:245], v[20:23]
	s_setprio 0
	s_barrier
	s_add_u32 s0, s0, 0x100
	s_addc_u32 s1, s1, 0
	s_add_u32 s40, s40, 0x100
	s_addc_u32 s41, s41, 0
	s_cmp_ge_u32 s78, s9
	s_mov_b32 s38, s78
	s_cbranch_scc0 .LBB0_468

; #define PG8_STAGE(bufoff, gbase, voff) do { _Pragma("unroll") for (int _i = 0; _i < 2; ++_i) \
;         __builtin_amdgcn_global_load_lds((const unsigned*)((const char*)(gbase) + (voff)[_i]), (PG8_LAS unsigned*)(lds + (bufoff) + ldsw + _i * 8192), 16, 0, 0); } while (0)
; #define PG8_LDA(dst, b, h) do { _Pragma("unroll") for (int m = 0; m < 4; ++m) _Pragma("unroll") for (int k = 0; k < 2; ++k) dst[m][k] = *(const PG8_LAS bf16x8*)(lds + PG8_SA(b, h) + aoff + m * 2048 + k * 1024); } while (0)
; #define PG8_LDB(dst, b, h) do { _Pragma("unroll") for (int n = 0; n < 2; ++n) _Pragma("unroll") for (int k = 0; k < 2; ++k) dst[n][k] = *(const PG8_LAS bf16x8*)(lds + PG8_SB(b, h) + boff + n * 2048 + k * 1024); } while (0)
; #define PG8_MMA(ai, bj, At, Bt) do { __builtin_amdgcn_s_setprio(1); _Pragma("unroll") for (int m = 0; m < 4; ++m) _Pragma("unroll") for (int n = 0; n < 2; ++n) _Pragma("unroll") for (int k = 0; k < 2; ++k) \
;         acc[ai][bj][m][n] = __builtin_amdgcn_mfma_f32_16x16x32_bf16(Bt[n][k], At[m][k], acc[ai][bj][m][n], 0, 0, 0); __builtin_amdgcn_s_setprio(0); } while (0)
; #define PG8_WAIT_V(n) asm volatile("s_waitcnt vmcnt(" #n ")" ::: "memory")
; #define PG8_WAIT_L(n) asm volatile("s_waitcnt lgkmcnt(" #n ")" ::: "memory")
; template <class Epi, class Sched, bool ALIGN_EPI = false, bool SP2 = false>
; __device__ __forceinline__ void gemm_phase(PG8_LAS unsigned char* lds, const Gemm g, const Sched& S, const Epi& E) {
;     ...
;             const bool last = (t == nt - 2);
;             const char* a1 = cA + (size_t)(t + 1) * kstep;
;             const char* a2 = last ? nA : cA + (size_t)(t + 2) * kstep; const char* b2 = last ? nB : cB + (size_t)(t + 2) * kstep;
;             const char* a3 = a2 + kstep; const char* b3 = b2 + kstep;
;             if (last && has_next) S.a_ready(nxt);
;             if constexpr (SP2) {
;             PG8_LDB(B0, 0, 0); PG8_LDB(B1, 0, 1); PG8_SCHED; PG8_LDA(At, 0, 0); PG8_STAGE(PG8_SA(1, 1), a1 + hstep, voffA);
;             PG8_WAIT_V(8); PG8_WAIT_L(0); PG8_BAR; PG8_MMA(0, 0, At, B0); PG8_MMA(0, 1, At, B1); PG8_BAR; PG8_SCHED;
;             PG8_LDA(At, 0, 1); PG8_STAGE(PG8_SB(0, 0), b2, voffB); PG8_STAGE(PG8_SB(0, 1), b2 + hstep, voffB); PG8_STAGE(PG8_SA(0, 0), a2, voffA);
;             PG8_WAIT_V(8); PG8_WAIT_L(0); PG8_BAR; PG8_MMA(1, 0, At, B0); PG8_MMA(1, 1, At, B1); PG8_BAR; PG8_SCHED;
.LBB0_501:
	s_add_i32 s80, s4, 2
	s_add_u32 s81, s0, 0x80
	s_addc_u32 s5, s1, 0
	s_cmp_eq_u32 s33, s4
	s_cselect_b32 s5, s23, s5
	s_cselect_b32 s4, s22, s81
	s_cselect_b32 s83, s41, s43
	s_cselect_b32 s82, s40, s42
	s_add_i32 s81, 0, 0x14000
	v_add_u32_e32 v148, s19, v164
	v_add_u32_e32 v162, s81, v164
	ds_read_b128 v[136:139], v148
	ds_read_b128 v[140:143], v148 offset:1024
	ds_read_b128 v[144:147], v148 offset:2048
	ds_read_b128 v[148:151], v148 offset:3072
	ds_read_b128 v[174:177], v162
	ds_read_b128 v[178:181], v162 offset:1024
	ds_read_b128 v[184:187], v162 offset:2048
	ds_read_b128 v[188:191], v162 offset:3072
	v_lshl_add_u64 v[162:163], s[0:1], 0, v[158:159]
	s_add_i32 m0, s45, 0xc000
	ds_read_b128 v[192:195], v170
	ds_read_b128 v[196:199], v170 offset:1024
	ds_read_b128 v[200:203], v170 offset:2048
	ds_read_b128 v[204:207], v170 offset:3072
	ds_read_b128 v[230:233], v170 offset:4096
	ds_read_b128 v[234:237], v170 offset:5120
	ds_read_b128 v[238:241], v170 offset:6144
	ds_read_b128 v[242:245], v170 offset:7168
	global_load_lds_dwordx4 v[162:163], off
	v_lshl_add_u64 v[162:163], s[0:1], 0, v[160:161]
	s_add_i32 m0, s45, 0xe000
	s_nop 0
	global_load_lds_dwordx4 v[162:163], off
	s_waitcnt vmcnt(8)
	s_waitcnt lgkmcnt(0)
	s_barrier
	s_setprio 1
	s_waitcnt lgkmcnt(0)
	v_mfma_f32_16x16x32_bf16 v[132:135], v[136:139], v[192:195], v[132:135]
	v_mfma_f32_16x16x32_bf16 v[132:135], v[140:143], v[196:199], v[132:135]
	v_mfma_f32_16x16x32_bf16 v[128:131], v[144:147], v[192:195], v[128:131]
	v_mfma_f32_16x16x32_bf16 v[128:131], v[148:151], v[196:199], v[128:131]
	v_mfma_f32_16x16x32_bf16 v[120:123], v[184:187], v[192:195], v[120:123]
	v_mfma_f32_16x16x32_bf16 v[120:123], v[188:191], v[196:199], v[120:123]
	v_mfma_f32_16x16x32_bf16 v[124:127], v[174:177], v[192:195], v[124:127]
	v_mfma_f32_16x16x32_bf16 v[124:127], v[178:181], v[196:199], v[124:127]
	v_mfma_f32_16x16x32_bf16 v[108:111], v[174:177], v[200:203], v[108:111]
	v_mfma_f32_16x16x32_bf16 v[108:111], v[178:181], v[204:207], v[108:111]
	v_mfma_f32_16x16x32_bf16 v[104:107], v[184:187], v[200:203], v[104:107]
	v_mfma_f32_16x16x32_bf16 v[104:107], v[188:191], v[204:207], v[104:107]
	v_mfma_f32_16x16x32_bf16 v[112:115], v[144:147], v[200:203], v[112:115]
	v_mfma_f32_16x16x32_bf16 v[112:115], v[148:151], v[204:207], v[112:115]
	v_mfma_f32_16x16x32_bf16 v[116:119], v[136:139], v[200:203], v[116:119]
	v_mfma_f32_16x16x32_bf16 v[116:119], v[140:143], v[204:207], v[116:119]
	s_setprio 0
	s_setprio 1
	v_mfma_f32_16x16x32_bf16 v[100:103], v[136:139], v[230:233], v[100:103]
	v_mfma_f32_16x16x32_bf16 v[100:103], v[140:143], v[234:237], v[100:103]
	v_mfma_f32_16x16x32_bf16 v[96:99], v[144:147], v[230:233], v[96:99]
	v_mfma_f32_16x16x32_bf16 v[96:99], v[148:151], v[234:237], v[96:99]
	v_mfma_f32_16x16x32_bf16 v[88:91], v[184:187], v[230:233], v[88:91]
	v_mfma_f32_16x16x32_bf16 v[88:91], v[188:191], v[234:237], v[88:91]
	v_mfma_f32_16x16x32_bf16 v[92:95], v[174:177], v[230:233], v[92:95]
	v_mfma_f32_16x16x32_bf16 v[92:95], v[178:181], v[234:237], v[92:95]
	v_mfma_f32_16x16x32_bf16 v[76:79], v[174:177], v[238:241], v[76:79]
	v_mfma_f32_16x16x32_bf16 v[76:79], v[178:181], v[242:245], v[76:79]
	v_mfma_f32_16x16x32_bf16 v[72:75], v[184:187], v[238:241], v[72:75]
	v_mfma_f32_16x16x32_bf16 v[72:75], v[188:191], v[242:245], v[72:75]
	v_mfma_f32_16x16x32_bf16 v[80:83], v[144:147], v[238:241], v[80:83]
	v_mfma_f32_16x16x32_bf16 v[80:83], v[148:151], v[242:245], v[80:83]
	v_mfma_f32_16x16x32_bf16 v[84:87], v[136:139], v[238:241], v[84:87]
	v_mfma_f32_16x16x32_bf16 v[84:87], v[140:143], v[242:245], v[84:87]
	s_setprio 0
	s_barrier
	s_add_i32 s84, s19, s44
	v_lshl_add_u64 v[162:163], s[82:83], 0, v[152:153]
	s_mov_b32 m0, s84
	ds_read_b128 v[192:195], v170 offset:16384
	ds_read_b128 v[196:199], v170 offset:17408
	ds_read_b128 v[200:203], v170 offset:18432
	ds_read_b128 v[204:207], v170 offset:19456
	ds_read_b128 v[230:233], v170 offset:20480
	ds_read_b128 v[234:237], v170 offset:21504
	ds_read_b128 v[238:241], v170 offset:22528
	ds_read_b128 v[242:245], v170 offset:23552
	global_load_lds_dwordx4 v[162:163], off
	s_add_i32 m0, s84, 0x2000
	v_lshl_add_u64 v[208:209], s[82:83], 0, v[156:157]
	s_add_u32 s82, s82, s48
	s_addc_u32 s83, s83, s49
	s_add_i32 s81, s81, s44
	global_load_lds_dwordx4 v[208:209], off
	v_lshl_add_u64 v[246:247], s[82:83], 0, v[152:153]
	s_mov_b32 m0, s81
	v_lshl_add_u64 v[248:249], s[82:83], 0, v[156:157]
	global_load_lds_dwordx4 v[246:247], off
	s_add_i32 m0, s81, 0x2000
	v_lshl_add_u64 v[216:217], s[4:5], 0, v[2:3]
	global_load_lds_dwordx4 v[248:249], off
	s_mov_b32 m0, s45
	v_lshl_add_u64 v[224:225], s[4:5], 0, v[154:155]
	global_load_lds_dwordx4 v[216:217], off
	s_mov_b32 m0, s46
	s_nop 0
	global_load_lds_dwordx4 v[224:225], off
	s_waitcnt vmcnt(8)
	s_waitcnt lgkmcnt(0)
	s_barrier
; #define PG8_STAGE(bufoff, gbase, voff) do { _Pragma("unroll") for (int _i = 0; _i < 2; ++_i) \
;         __builtin_amdgcn_global_load_lds((const unsigned*)((const char*)(gbase) + (voff)[_i]), (PG8_LAS unsigned*)(lds + (bufoff) + ldsw + _i * 8192), 16, 0, 0); } while (0)
; #define PG8_LDA(dst, b, h) do { _Pragma("unroll") for (int m = 0; m < 4; ++m) _Pragma("unroll") for (int k = 0; k < 2; ++k) dst[m][k] = *(const PG8_LAS bf16x8*)(lds + PG8_SA(b, h) + aoff + m * 2048 + k * 1024); } while (0)
; #define PG8_LDB(dst, b, h) do { _Pragma("unroll") for (int n = 0; n < 2; ++n) _Pragma("unroll") for (int k = 0; k < 2; ++k) dst[n][k] = *(const PG8_LAS bf16x8*)(lds + PG8_SB(b, h) + boff + n * 2048 + k * 1024); } while (0)
; #define PG8_MMA(ai, bj, At, Bt) do { __builtin_amdgcn_s_setprio(1); _Pragma("unroll") for (int m = 0; m < 4; ++m) _Pragma("unroll") for (int n = 0; n < 2; ++n) _Pragma("unroll") for (int k = 0; k < 2; ++k) \
;         acc[ai][bj][m][n] = __builtin_amdgcn_mfma_f32_16x16x32_bf16(Bt[n][k], At[m][k], acc[ai][bj][m][n], 0, 0, 0); __builtin_amdgcn_s_setprio(0); } while (0)
; #define PG8_WAIT_V(n) asm volatile("s_waitcnt vmcnt(" #n ")" ::: "memory")
; #define PG8_WAIT_L(n) asm volatile("s_waitcnt lgkmcnt(" #n ")" ::: "memory")
; #define PG8_BAR __builtin_amdgcn_s_barrier()
; #define PG8_SCHED __builtin_amdgcn_sched_barrier(0)
; template <class Epi, class Sched, bool ALIGN_EPI = false, bool SP2 = false>
; __device__ __forceinline__ void gemm_phase(PG8_LAS unsigned char* lds, const Gemm g, const Sched& S, const Epi& E) {
;     ...
;             PG8_WAIT_V(8); PG8_WAIT_L(0); PG8_BAR; PG8_MMA(1, 0, At, B0); PG8_MMA(1, 1, At, B1); PG8_BAR; PG8_SCHED;
;             PG8_LDB(B0, 1, 0); PG8_LDB(B1, 1, 1); PG8_SCHED; PG8_LDA(At, 1, 0); PG8_STAGE(PG8_SA(0, 1), a2 + hstep, voffA);
;             PG8_WAIT_V(8); PG8_WAIT_L(0); PG8_BAR; PG8_MMA(0, 0, At, B0); PG8_MMA(0, 1, At, B1); PG8_BAR; PG8_SCHED;
	s_setprio 1
	s_waitcnt lgkmcnt(0)
	v_mfma_f32_16x16x32_bf16 v[68:71], v[136:139], v[192:195], v[68:71]
	v_mfma_f32_16x16x32_bf16 v[68:71], v[140:143], v[196:199], v[68:71]
	v_mfma_f32_16x16x32_bf16 v[64:67], v[144:147], v[192:195], v[64:67]
	v_mfma_f32_16x16x32_bf16 v[64:67], v[148:151], v[196:199], v[64:67]
	v_mfma_f32_16x16x32_bf16 v[56:59], v[184:187], v[192:195], v[56:59]
	v_mfma_f32_16x16x32_bf16 v[56:59], v[188:191], v[196:199], v[56:59]
	v_mfma_f32_16x16x32_bf16 v[60:63], v[174:177], v[192:195], v[60:63]
	v_mfma_f32_16x16x32_bf16 v[60:63], v[178:181], v[196:199], v[60:63]
	v_mfma_f32_16x16x32_bf16 v[44:47], v[174:177], v[200:203], v[44:47]
	v_mfma_f32_16x16x32_bf16 v[44:47], v[178:181], v[204:207], v[44:47]
	v_mfma_f32_16x16x32_bf16 v[40:43], v[184:187], v[200:203], v[40:43]
	v_mfma_f32_16x16x32_bf16 v[40:43], v[188:191], v[204:207], v[40:43]
	v_mfma_f32_16x16x32_bf16 v[48:51], v[144:147], v[200:203], v[48:51]
	v_mfma_f32_16x16x32_bf16 v[48:51], v[148:151], v[204:207], v[48:51]
	v_mfma_f32_16x16x32_bf16 v[52:55], v[136:139], v[200:203], v[52:55]
	v_mfma_f32_16x16x32_bf16 v[52:55], v[140:143], v[204:207], v[52:55]
	s_setprio 0
	s_setprio 1
	v_mfma_f32_16x16x32_bf16 v[36:39], v[136:139], v[230:233], v[36:39]
	v_mfma_f32_16x16x32_bf16 v[36:39], v[140:143], v[234:237], v[36:39]
	v_mfma_f32_16x16x32_bf16 v[32:35], v[144:147], v[230:233], v[32:35]
	v_mfma_f32_16x16x32_bf16 v[32:35], v[148:151], v[234:237], v[32:35]
	v_mfma_f32_16x16x32_bf16 v[24:27], v[184:187], v[230:233], v[24:27]
	v_mfma_f32_16x16x32_bf16 v[24:27], v[188:191], v[234:237], v[24:27]
	v_mfma_f32_16x16x32_bf16 v[28:31], v[174:177], v[230:233], v[28:31]
	v_mfma_f32_16x16x32_bf16 v[28:31], v[178:181], v[234:237], v[28:31]
	v_mfma_f32_16x16x32_bf16 v[12:15], v[174:177], v[238:241], v[12:15]
	v_mfma_f32_16x16x32_bf16 v[12:15], v[178:181], v[242:245], v[12:15]
	v_mfma_f32_16x16x32_bf16 v[8:11], v[184:187], v[238:241], v[8:11]
	v_mfma_f32_16x16x32_bf16 v[8:11], v[188:191], v[242:245], v[8:11]
	v_mfma_f32_16x16x32_bf16 v[16:19], v[144:147], v[238:241], v[16:19]
	v_mfma_f32_16x16x32_bf16 v[16:19], v[148:151], v[242:245], v[16:19]
	v_mfma_f32_16x16x32_bf16 v[20:23], v[136:139], v[238:241], v[20:23]
	v_mfma_f32_16x16x32_bf16 v[20:23], v[140:143], v[242:245], v[20:23]
	s_setprio 0
	s_barrier
	s_add_i32 s81, 0, 0x1c000
	v_add_u32_e32 v148, s91, v164
	v_add_u32_e32 v173, s81, v164
	ds_read_b128 v[136:139], v148
	ds_read_b128 v[140:143], v148 offset:1024
	ds_read_b128 v[144:147], v148 offset:2048
	ds_read_b128 v[148:151], v148 offset:3072
	ds_read_b128 v[174:177], v173
	ds_read_b128 v[178:181], v173 offset:1024
	ds_read_b128 v[184:187], v173 offset:2048
	ds_read_b128 v[188:191], v173 offset:3072
	s_add_u32 s4, s4, s48
	s_addc_u32 s5, s5, s49
	s_mov_b32 m0, s47
	v_lshl_add_u64 v[226:227], s[4:5], 0, v[2:3]
	ds_read_b128 v[192:195], v170 offset:32768
	ds_read_b128 v[196:199], v170 offset:33792
	ds_read_b128 v[200:203], v170 offset:34816
	ds_read_b128 v[204:207], v170 offset:35840
	ds_read_b128 v[230:233], v170 offset:36864
	ds_read_b128 v[234:237], v170 offset:37888
	ds_read_b128 v[238:241], v170 offset:38912
	ds_read_b128 v[242:245], v170 offset:39936
	global_load_lds_dwordx4 v[226:227], off
	v_lshl_add_u64 v[226:227], s[4:5], 0, v[154:155]
	s_mov_b32 m0, s52
	s_nop 0
	global_load_lds_dwordx4 v[226:227], off
	s_waitcnt vmcnt(8)
	s_waitcnt lgkmcnt(0)
	s_barrier
	s_setprio 1
	s_waitcnt lgkmcnt(0)
	v_mfma_f32_16x16x32_bf16 v[132:135], v[136:139], v[192:195], v[132:135]
	v_mfma_f32_16x16x32_bf16 v[132:135], v[140:143], v[196:199], v[132:135]
	v_mfma_f32_16x16x32_bf16 v[128:131], v[144:147], v[192:195], v[128:131]
	v_mfma_f32_16x16x32_bf16 v[128:131], v[148:151], v[196:199], v[128:131]
	v_mfma_f32_16x16x32_bf16 v[120:123], v[184:187], v[192:195], v[120:123]
	v_mfma_f32_16x16x32_bf16 v[120:123], v[188:191], v[196:199], v[120:123]
	v_mfma_f32_16x16x32_bf16 v[124:127], v[174:177], v[192:195], v[124:127]
	v_mfma_f32_16x16x32_bf16 v[124:127], v[178:181], v[196:199], v[124:127]
	v_mfma_f32_16x16x32_bf16 v[108:111], v[174:177], v[200:203], v[108:111]
	v_mfma_f32_16x16x32_bf16 v[108:111], v[178:181], v[204:207], v[108:111]
	v_mfma_f32_16x16x32_bf16 v[104:107], v[184:187], v[200:203], v[104:107]
	v_mfma_f32_16x16x32_bf16 v[104:107], v[188:191], v[204:207], v[104:107]
	v_mfma_f32_16x16x32_bf16 v[112:115], v[144:147], v[200:203], v[112:115]
	v_mfma_f32_16x16x32_bf16 v[112:115], v[148:151], v[204:207], v[112:115]
	v_mfma_f32_16x16x32_bf16 v[116:119], v[136:139], v[200:203], v[116:119]
	v_mfma_f32_16x16x32_bf16 v[116:119], v[140:143], v[204:207], v[116:119]
	s_setprio 0
	s_setprio 1
	v_mfma_f32_16x16x32_bf16 v[100:103], v[136:139], v[230:233], v[100:103]
	v_mfma_f32_16x16x32_bf16 v[100:103], v[140:143], v[234:237], v[100:103]
	v_mfma_f32_16x16x32_bf16 v[96:99], v[144:147], v[230:233], v[96:99]
	v_mfma_f32_16x16x32_bf16 v[96:99], v[148:151], v[234:237], v[96:99]
	v_mfma_f32_16x16x32_bf16 v[88:91], v[184:187], v[230:233], v[88:91]
	v_mfma_f32_16x16x32_bf16 v[88:91], v[188:191], v[234:237], v[88:91]
	v_mfma_f32_16x16x32_bf16 v[92:95], v[174:177], v[230:233], v[92:95]
	v_mfma_f32_16x16x32_bf16 v[92:95], v[178:181], v[234:237], v[92:95]
	v_mfma_f32_16x16x32_bf16 v[76:79], v[174:177], v[238:241], v[76:79]
	v_mfma_f32_16x16x32_bf16 v[76:79], v[178:181], v[242:245], v[76:79]
	v_mfma_f32_16x16x32_bf16 v[72:75], v[184:187], v[238:241], v[72:75]
	v_mfma_f32_16x16x32_bf16 v[72:75], v[188:191], v[242:245], v[72:75]
	v_mfma_f32_16x16x32_bf16 v[80:83], v[144:147], v[238:241], v[80:83]
	v_mfma_f32_16x16x32_bf16 v[80:83], v[148:151], v[242:245], v[80:83]
	v_mfma_f32_16x16x32_bf16 v[84:87], v[136:139], v[238:241], v[84:87]
	v_mfma_f32_16x16x32_bf16 v[84:87], v[140:143], v[242:245], v[84:87]
	s_setprio 0
	s_barrier
; #define PG8_STAGE(bufoff, gbase, voff) do { _Pragma("unroll") for (int _i = 0; _i < 2; ++_i) \
;         __builtin_amdgcn_global_load_lds((const unsigned*)((const char*)(gbase) + (voff)[_i]), (PG8_LAS unsigned*)(lds + (bufoff) + ldsw + _i * 8192), 16, 0, 0); } while (0)
; #define PG8_LDA(dst, b, h) do { _Pragma("unroll") for (int m = 0; m < 4; ++m) _Pragma("unroll") for (int k = 0; k < 2; ++k) dst[m][k] = *(const PG8_LAS bf16x8*)(lds + PG8_SA(b, h) + aoff + m * 2048 + k * 1024); } while (0)
; #define PG8_MMA(ai, bj, At, Bt) do { __builtin_amdgcn_s_setprio(1); _Pragma("unroll") for (int m = 0; m < 4; ++m) _Pragma("unroll") for (int n = 0; n < 2; ++n) _Pragma("unroll") for (int k = 0; k < 2; ++k) \
;         acc[ai][bj][m][n] = __builtin_amdgcn_mfma_f32_16x16x32_bf16(Bt[n][k], At[m][k], acc[ai][bj][m][n], 0, 0, 0); __builtin_amdgcn_s_setprio(0); } while (0)
; #define PG8_WAIT_V(n) asm volatile("s_waitcnt vmcnt(" #n ")" ::: "memory")
; #define PG8_WAIT_L(n) asm volatile("s_waitcnt lgkmcnt(" #n ")" ::: "memory")
; #define PG8_BAR __builtin_amdgcn_s_barrier()
; #define PG8_SCHED __builtin_amdgcn_sched_barrier(0)
; template <class Epi, class Sched, bool ALIGN_EPI = false, bool SP2 = false>
; __device__ __forceinline__ void gemm_phase(PG8_LAS unsigned char* lds, const Gemm g, const Sched& S, const Epi& E) {
;     ...
;             PG8_LDA(At, 1, 1); PG8_STAGE(PG8_SB(1, 0), b3, voffB); PG8_STAGE(PG8_SB(1, 1), b3 + hstep, voffB); PG8_STAGE(PG8_SA(1, 0), a3, voffA);
;             PG8_WAIT_V(8); PG8_WAIT_L(0); PG8_BAR; PG8_MMA(1, 0, At, B0); PG8_MMA(1, 1, At, B1); PG8_BAR; PG8_SCHED;
	s_add_i32 s4, s91, s44
	v_lshl_add_u64 v[162:163], v[162:163], 0, s[24:25]
	s_mov_b32 m0, s4
	ds_read_b128 v[192:195], v170 offset:49152
	ds_read_b128 v[196:199], v170 offset:50176
	ds_read_b128 v[200:203], v170 offset:51200
	ds_read_b128 v[204:207], v170 offset:52224
	ds_read_b128 v[230:233], v170 offset:53248
	ds_read_b128 v[234:237], v170 offset:54272
	ds_read_b128 v[238:241], v170 offset:55296
	ds_read_b128 v[242:245], v170 offset:56320
	global_load_lds_dwordx4 v[162:163], off
	v_lshl_add_u64 v[162:163], v[208:209], 0, s[24:25]
	s_add_i32 m0, s4, 0x2000
	s_add_i32 s4, s81, s44
	global_load_lds_dwordx4 v[162:163], off
	v_lshl_add_u64 v[162:163], v[246:247], 0, s[24:25]
	s_mov_b32 m0, s4
	s_nop 0
	global_load_lds_dwordx4 v[162:163], off
	v_lshl_add_u64 v[162:163], v[248:249], 0, s[24:25]
	s_add_i32 m0, s4, 0x2000
	s_nop 0
	global_load_lds_dwordx4 v[162:163], off
	v_lshl_add_u64 v[162:163], v[216:217], 0, s[24:25]
	s_mov_b32 m0, s53
	s_nop 0
	global_load_lds_dwordx4 v[162:163], off
	v_lshl_add_u64 v[162:163], v[224:225], 0, s[24:25]
	s_mov_b32 m0, s72
	s_nop 0
	global_load_lds_dwordx4 v[162:163], off
	s_waitcnt vmcnt(8)
	s_waitcnt lgkmcnt(0)
	s_barrier
	s_setprio 1
	s_waitcnt lgkmcnt(0)
	v_mfma_f32_16x16x32_bf16 v[68:71], v[136:139], v[192:195], v[68:71]
	v_mfma_f32_16x16x32_bf16 v[68:71], v[140:143], v[196:199], v[68:71]
	v_mfma_f32_16x16x32_bf16 v[64:67], v[144:147], v[192:195], v[64:67]
	v_mfma_f32_16x16x32_bf16 v[64:67], v[148:151], v[196:199], v[64:67]
	v_mfma_f32_16x16x32_bf16 v[56:59], v[184:187], v[192:195], v[56:59]
	v_mfma_f32_16x16x32_bf16 v[56:59], v[188:191], v[196:199], v[56:59]
	v_mfma_f32_16x16x32_bf16 v[60:63], v[174:177], v[192:195], v[60:63]
	v_mfma_f32_16x16x32_bf16 v[60:63], v[178:181], v[196:199], v[60:63]
	v_mfma_f32_16x16x32_bf16 v[44:47], v[174:177], v[200:203], v[44:47]
	v_mfma_f32_16x16x32_bf16 v[44:47], v[178:181], v[204:207], v[44:47]
	v_mfma_f32_16x16x32_bf16 v[40:43], v[184:187], v[200:203], v[40:43]
	v_mfma_f32_16x16x32_bf16 v[40:43], v[188:191], v[204:207], v[40:43]
	v_mfma_f32_16x16x32_bf16 v[48:51], v[144:147], v[200:203], v[48:51]
	v_mfma_f32_16x16x32_bf16 v[48:51], v[148:151], v[204:207], v[48:51]
	v_mfma_f32_16x16x32_bf16 v[52:55], v[136:139], v[200:203], v[52:55]
	v_mfma_f32_16x16x32_bf16 v[52:55], v[140:143], v[204:207], v[52:55]
	s_setprio 0
	s_setprio 1
	v_mfma_f32_16x16x32_bf16 v[36:39], v[136:139], v[230:233], v[36:39]
	v_mfma_f32_16x16x32_bf16 v[36:39], v[140:143], v[234:237], v[36:39]
	v_mfma_f32_16x16x32_bf16 v[32:35], v[144:147], v[230:233], v[32:35]
	v_mfma_f32_16x16x32_bf16 v[32:35], v[148:151], v[234:237], v[32:35]
	v_mfma_f32_16x16x32_bf16 v[24:27], v[184:187], v[230:233], v[24:27]
	v_mfma_f32_16x16x32_bf16 v[24:27], v[188:191], v[234:237], v[24:27]
	v_mfma_f32_16x16x32_bf16 v[28:31], v[174:177], v[230:233], v[28:31]
	v_mfma_f32_16x16x32_bf16 v[28:31], v[178:181], v[234:237], v[28:31]
	v_mfma_f32_16x16x32_bf16 v[12:15], v[174:177], v[238:241], v[12:15]
	v_mfma_f32_16x16x32_bf16 v[12:15], v[178:181], v[242:245], v[12:15]
	v_mfma_f32_16x16x32_bf16 v[8:11], v[184:187], v[238:241], v[8:11]
	v_mfma_f32_16x16x32_bf16 v[8:11], v[188:191], v[242:245], v[8:11]
	v_mfma_f32_16x16x32_bf16 v[16:19], v[144:147], v[238:241], v[16:19]
	v_mfma_f32_16x16x32_bf16 v[16:19], v[148:151], v[242:245], v[16:19]
	v_mfma_f32_16x16x32_bf16 v[20:23], v[136:139], v[238:241], v[20:23]
	v_mfma_f32_16x16x32_bf16 v[20:23], v[140:143], v[242:245], v[20:23]
	s_setprio 0
	s_barrier
	s_add_u32 s0, s0, 0x100
	s_addc_u32 s1, s1, 0
	s_add_u32 s42, s42, 0x100
	s_addc_u32 s43, s43, 0
	s_cmp_ge_u32 s80, s9
	s_mov_b32 s4, s80
	s_cbranch_scc0 .LBB0_501
